# same as previous plus P11 keeps the compiler's phase flag SGPRs s36:37 intact (cleanup, no timing intent)
# baseline (speedup 1.0000x reference)
; DI f2_t cvt8lo(unsigned w) { return __builtin_amdgcn_cvt_pk_f32_fp8(w, false); }
; DI f2_t cvt8hi(unsigned w) { return __builtin_amdgcn_cvt_pk_f32_fp8(w, true); }
; DI void wave_lds_sync() { asm volatile("s_waitcnt lgkmcnt(0)" ::: "memory"); __builtin_amdgcn_wave_barrier(); }
; DI void phase11(const Params& p, char* smem, int rep) {
;     ...
;   xcd_queue((unsigned*)(p.ws + WS_BAR) + CTR_VQ + rep * 8, 512, smem, [&](int s, int c) __attribute__((always_inline)) {
; #pragma unroll 1
;     for (int t = 0; t < 4; ++t) {
;       const int tok = __builtin_amdgcn_readfirstlane(c * 16 + w * 4 + t);
;       const int i0 = IDS[(size_t)tok * 128 + lane], i1 = IDS[(size_t)tok * 128 + 64 + lane];
;       const float a0 = ACT[(size_t)tok * 128 + lane], a1 = ACT[(size_t)tok * 128 + 64 + lane];
;       wave_lds_sync();
;       lw[(lane & 3) * 32 + (lane >> 2)] = i0; lw[(lane & 3) * 32 + 16 + (lane >> 2)] = i1;
;       lf[(lane & 3) * 32 + (lane >> 2)] = a0; lf[(lane & 3) * 32 + 16 + (lane >> 2)] = a1;
;       wave_lds_sync();
;       f2_t o[8];
; #pragma unroll
;       for (int i = 0; i < 8; ++i) o[i] = f2_t{0.f, 0.f};
;       const unsigned char* vb = V8 + s * 256 + l15 * 16;
; #pragma unroll
;       for (int batch = 0; batch < 2; ++batch) {
;         int ida[16]; float aa[16];
; #pragma unroll
;         for (int q = 0; q < 4; ++q) {
;           const int4 v = *(const int4*)(lw + g * 32 + batch * 16 + q * 4); ida[q * 4] = v.x; ida[q * 4 + 1] = v.y; ida[q * 4 + 2] = v.z; ida[q * 4 + 3] = v.w;
;           const float4 f = *(const float4*)(lf + g * 32 + batch * 16 + q * 4); aa[q * 4] = f.x; aa[q * 4 + 1] = f.y; aa[q * 4 + 2] = f.z; aa[q * 4 + 3] = f.w;
;         }
;         u32x4 rows[16];
; #pragma unroll
;         for (int k = 0; k < 16; ++k) rows[k] = *(const u32x4*)(vb + (size_t)ida[k] * 2048);
; #pragma unroll
;         for (int k = 0; k < 16; ++k) {
;           const f2_t a2 = {aa[k], aa[k]};
; #pragma unroll
;           for (int d = 0; d < 4; ++d) { const unsigned ww = rows[k][d]; o[2 * d] += a2 * cvt8lo(ww); o[2 * d + 1] += a2 * cvt8hi(ww); }
;         }
.Lp11_body:
	s_add_i32 s54, s34, 0
	s_lshl_b32 s46, s54, 12
	s_add_i32 s46, s46, s24
	s_add_i32 s55, s34, 1
	s_lshl_b32 s47, s55, 9
	s_add_u32 s42, s6, s47
	s_addc_u32 s43, s7, 0
	s_add_u32 s44, s8, s47
	s_addc_u32 s45, s9, 0
	global_load_dword v10, v3, s[42:43]
	global_load_dword v11, v3, s[42:43] offset:256
	global_load_dword v12, v3, s[44:45]
	global_load_dword v13, v3, s[44:45] offset:256
	s_waitcnt lgkmcnt(0)
	v_lshl_add_u32 v20, v20, 11, v2
	v_lshl_add_u32 v21, v21, 11, v2
	v_lshl_add_u32 v22, v22, 11, v2
	v_lshl_add_u32 v23, v23, 11, v2
	v_lshl_add_u32 v24, v24, 11, v2
	v_lshl_add_u32 v25, v25, 11, v2
	v_lshl_add_u32 v26, v26, 11, v2
	v_lshl_add_u32 v27, v27, 11, v2
	v_lshl_add_u32 v28, v28, 11, v2
	v_lshl_add_u32 v29, v29, 11, v2
	v_lshl_add_u32 v30, v30, 11, v2
	v_lshl_add_u32 v31, v31, 11, v2
	v_lshl_add_u32 v32, v32, 11, v2
	v_lshl_add_u32 v33, v33, 11, v2
	v_lshl_add_u32 v34, v34, 11, v2
	v_lshl_add_u32 v35, v35, 11, v2
	v_lshl_add_u32 v36, v36, 11, v2
	v_lshl_add_u32 v37, v37, 11, v2
	v_lshl_add_u32 v38, v38, 11, v2
	v_lshl_add_u32 v39, v39, 11, v2
	v_lshl_add_u32 v40, v40, 11, v2
	v_lshl_add_u32 v41, v41, 11, v2
	v_lshl_add_u32 v42, v42, 11, v2
	v_lshl_add_u32 v43, v43, 11, v2
	v_lshl_add_u32 v44, v44, 11, v2
	v_lshl_add_u32 v45, v45, 11, v2
	v_lshl_add_u32 v46, v46, 11, v2
	v_lshl_add_u32 v47, v47, 11, v2
	v_lshl_add_u32 v48, v48, 11, v2
	v_lshl_add_u32 v49, v49, 11, v2
	v_lshl_add_u32 v50, v50, 11, v2
	v_lshl_add_u32 v51, v51, 11, v2
	global_load_dwordx4 v[84:87], v20, s[20:21]
	global_load_dwordx4 v[88:91], v21, s[20:21]
	global_load_dwordx4 v[92:95], v22, s[20:21]
	global_load_dwordx4 v[96:99], v23, s[20:21]
	global_load_dwordx4 v[100:103], v24, s[20:21]
	global_load_dwordx4 v[104:107], v25, s[20:21]
	global_load_dwordx4 v[108:111], v26, s[20:21]
	global_load_dwordx4 v[112:115], v27, s[20:21]
	global_load_dwordx4 v[116:119], v28, s[20:21]
	global_load_dwordx4 v[120:123], v29, s[20:21]
	global_load_dwordx4 v[124:127], v30, s[20:21]
	global_load_dwordx4 v[128:131], v31, s[20:21]
	global_load_dwordx4 v[132:135], v32, s[20:21]
	global_load_dwordx4 v[136:139], v33, s[20:21]
	global_load_dwordx4 v[140:143], v34, s[20:21]
	global_load_dwordx4 v[144:147], v35, s[20:21]
	global_load_dwordx4 v[148:151], v36, s[20:21]
	global_load_dwordx4 v[152:155], v37, s[20:21]
	global_load_dwordx4 v[156:159], v38, s[20:21]
	global_load_dwordx4 v[160:163], v39, s[20:21]
	global_load_dwordx4 v[164:167], v40, s[20:21]
	global_load_dwordx4 v[168:171], v41, s[20:21]
	global_load_dwordx4 v[172:175], v42, s[20:21]
	global_load_dwordx4 v[176:179], v43, s[20:21]
	global_load_dwordx4 v[180:183], v44, s[20:21]
	global_load_dwordx4 v[184:187], v45, s[20:21]
	global_load_dwordx4 v[190:193], v46, s[20:21]
	global_load_dwordx4 v[194:197], v47, s[20:21]
	global_load_dwordx4 v[198:201], v48, s[20:21]
	global_load_dwordx4 v[202:205], v49, s[20:21]
	global_load_dwordx4 v[206:209], v50, s[20:21]
	global_load_dwordx4 v[210:213], v51, s[20:21]
	s_waitcnt vmcnt(31)
	v_cvt_pk_f32_fp8_e32 v[232:233], v84
	v_cvt_pk_f32_fp8_sdwa v[234:235], v84 src0_sel:WORD_1
	v_pk_fma_f32 v[216:217], v[52:53], v[232:233], 0 op_sel_hi:[0,1,0]
	v_pk_fma_f32 v[218:219], v[52:53], v[234:235], 0 op_sel_hi:[0,1,0]
	v_cvt_pk_f32_fp8_e32 v[236:237], v85
	v_cvt_pk_f32_fp8_sdwa v[238:239], v85 src0_sel:WORD_1
	v_pk_fma_f32 v[220:221], v[52:53], v[236:237], 0 op_sel_hi:[0,1,0]
	v_pk_fma_f32 v[222:223], v[52:53], v[238:239], 0 op_sel_hi:[0,1,0]
	v_cvt_pk_f32_fp8_e32 v[232:233], v86
	v_cvt_pk_f32_fp8_sdwa v[234:235], v86 src0_sel:WORD_1
	v_pk_fma_f32 v[224:225], v[52:53], v[232:233], 0 op_sel_hi:[0,1,0]
	v_pk_fma_f32 v[226:227], v[52:53], v[234:235], 0 op_sel_hi:[0,1,0]
	v_cvt_pk_f32_fp8_e32 v[236:237], v87
	v_cvt_pk_f32_fp8_sdwa v[238:239], v87 src0_sel:WORD_1
	v_pk_fma_f32 v[228:229], v[52:53], v[236:237], 0 op_sel_hi:[0,1,0]
	v_pk_fma_f32 v[230:231], v[52:53], v[238:239], 0 op_sel_hi:[0,1,0]
	s_waitcnt vmcnt(30)
	v_cvt_pk_f32_fp8_e32 v[232:233], v88
	v_cvt_pk_f32_fp8_sdwa v[234:235], v88 src0_sel:WORD_1
	v_pk_fma_f32 v[216:217], v[52:53], v[232:233], v[216:217] op_sel:[1,0,0]
	v_pk_fma_f32 v[218:219], v[52:53], v[234:235], v[218:219] op_sel:[1,0,0]
	v_cvt_pk_f32_fp8_e32 v[236:237], v89
	v_cvt_pk_f32_fp8_sdwa v[238:239], v89 src0_sel:WORD_1
	v_pk_fma_f32 v[220:221], v[52:53], v[236:237], v[220:221] op_sel:[1,0,0]
	v_pk_fma_f32 v[222:223], v[52:53], v[238:239], v[222:223] op_sel:[1,0,0]
	v_cvt_pk_f32_fp8_e32 v[232:233], v90
	v_cvt_pk_f32_fp8_sdwa v[234:235], v90 src0_sel:WORD_1
	v_pk_fma_f32 v[224:225], v[52:53], v[232:233], v[224:225] op_sel:[1,0,0]
	v_pk_fma_f32 v[226:227], v[52:53], v[234:235], v[226:227] op_sel:[1,0,0]
	v_cvt_pk_f32_fp8_e32 v[236:237], v91
	v_cvt_pk_f32_fp8_sdwa v[238:239], v91 src0_sel:WORD_1
	v_pk_fma_f32 v[228:229], v[52:53], v[236:237], v[228:229] op_sel:[1,0,0]
	v_pk_fma_f32 v[230:231], v[52:53], v[238:239], v[230:231] op_sel:[1,0,0]
	s_waitcnt vmcnt(29)
	v_cvt_pk_f32_fp8_e32 v[232:233], v92
	v_cvt_pk_f32_fp8_sdwa v[234:235], v92 src0_sel:WORD_1
	v_pk_fma_f32 v[216:217], v[54:55], v[232:233], v[216:217] op_sel_hi:[0,1,1]
	v_pk_fma_f32 v[218:219], v[54:55], v[234:235], v[218:219] op_sel_hi:[0,1,1]
	v_cvt_pk_f32_fp8_e32 v[236:237], v93
	v_cvt_pk_f32_fp8_sdwa v[238:239], v93 src0_sel:WORD_1
	v_pk_fma_f32 v[220:221], v[54:55], v[236:237], v[220:221] op_sel_hi:[0,1,1]
	v_pk_fma_f32 v[222:223], v[54:55], v[238:239], v[222:223] op_sel_hi:[0,1,1]
	v_cvt_pk_f32_fp8_e32 v[232:233], v94
	v_cvt_pk_f32_fp8_sdwa v[234:235], v94 src0_sel:WORD_1
	v_pk_fma_f32 v[224:225], v[54:55], v[232:233], v[224:225] op_sel_hi:[0,1,1]
	v_pk_fma_f32 v[226:227], v[54:55], v[234:235], v[226:227] op_sel_hi:[0,1,1]
	v_cvt_pk_f32_fp8_e32 v[236:237], v95
	v_cvt_pk_f32_fp8_sdwa v[238:239], v95 src0_sel:WORD_1
	v_pk_fma_f32 v[228:229], v[54:55], v[236:237], v[228:229] op_sel_hi:[0,1,1]
	v_pk_fma_f32 v[230:231], v[54:55], v[238:239], v[230:231] op_sel_hi:[0,1,1]
	s_waitcnt vmcnt(28)
; DI f2_t cvt8lo(unsigned w) { return __builtin_amdgcn_cvt_pk_f32_fp8(w, false); }
; DI f2_t cvt8hi(unsigned w) { return __builtin_amdgcn_cvt_pk_f32_fp8(w, true); }
; DI void phase11(const Params& p, char* smem, int rep) {
;     ...
; #pragma unroll
;         for (int k = 0; k < 16; ++k) {
;           const f2_t a2 = {aa[k], aa[k]};
; #pragma unroll
;           for (int d = 0; d < 4; ++d) { const unsigned ww = rows[k][d]; o[2 * d] += a2 * cvt8lo(ww); o[2 * d + 1] += a2 * cvt8hi(ww); }
;         }
	v_cvt_pk_f32_fp8_e32 v[232:233], v96
	v_cvt_pk_f32_fp8_sdwa v[234:235], v96 src0_sel:WORD_1
	v_pk_fma_f32 v[216:217], v[54:55], v[232:233], v[216:217] op_sel:[1,0,0]
	v_pk_fma_f32 v[218:219], v[54:55], v[234:235], v[218:219] op_sel:[1,0,0]
	v_cvt_pk_f32_fp8_e32 v[236:237], v97
	v_cvt_pk_f32_fp8_sdwa v[238:239], v97 src0_sel:WORD_1
	v_pk_fma_f32 v[220:221], v[54:55], v[236:237], v[220:221] op_sel:[1,0,0]
	v_pk_fma_f32 v[222:223], v[54:55], v[238:239], v[222:223] op_sel:[1,0,0]
	v_cvt_pk_f32_fp8_e32 v[232:233], v98
	v_cvt_pk_f32_fp8_sdwa v[234:235], v98 src0_sel:WORD_1
	v_pk_fma_f32 v[224:225], v[54:55], v[232:233], v[224:225] op_sel:[1,0,0]
	v_pk_fma_f32 v[226:227], v[54:55], v[234:235], v[226:227] op_sel:[1,0,0]
	v_cvt_pk_f32_fp8_e32 v[236:237], v99
	v_cvt_pk_f32_fp8_sdwa v[238:239], v99 src0_sel:WORD_1
	v_pk_fma_f32 v[228:229], v[54:55], v[236:237], v[228:229] op_sel:[1,0,0]
	v_pk_fma_f32 v[230:231], v[54:55], v[238:239], v[230:231] op_sel:[1,0,0]
	s_waitcnt vmcnt(27)
	v_cvt_pk_f32_fp8_e32 v[232:233], v100
	v_cvt_pk_f32_fp8_sdwa v[234:235], v100 src0_sel:WORD_1
	v_pk_fma_f32 v[216:217], v[56:57], v[232:233], v[216:217] op_sel_hi:[0,1,1]
	v_pk_fma_f32 v[218:219], v[56:57], v[234:235], v[218:219] op_sel_hi:[0,1,1]
	v_cvt_pk_f32_fp8_e32 v[236:237], v101
	v_cvt_pk_f32_fp8_sdwa v[238:239], v101 src0_sel:WORD_1
	v_pk_fma_f32 v[220:221], v[56:57], v[236:237], v[220:221] op_sel_hi:[0,1,1]
	v_pk_fma_f32 v[222:223], v[56:57], v[238:239], v[222:223] op_sel_hi:[0,1,1]
	v_cvt_pk_f32_fp8_e32 v[232:233], v102
	v_cvt_pk_f32_fp8_sdwa v[234:235], v102 src0_sel:WORD_1
	v_pk_fma_f32 v[224:225], v[56:57], v[232:233], v[224:225] op_sel_hi:[0,1,1]
	v_pk_fma_f32 v[226:227], v[56:57], v[234:235], v[226:227] op_sel_hi:[0,1,1]
	v_cvt_pk_f32_fp8_e32 v[236:237], v103
	v_cvt_pk_f32_fp8_sdwa v[238:239], v103 src0_sel:WORD_1
	v_pk_fma_f32 v[228:229], v[56:57], v[236:237], v[228:229] op_sel_hi:[0,1,1]
	v_pk_fma_f32 v[230:231], v[56:57], v[238:239], v[230:231] op_sel_hi:[0,1,1]
	s_waitcnt vmcnt(26)
	v_cvt_pk_f32_fp8_e32 v[232:233], v104
	v_cvt_pk_f32_fp8_sdwa v[234:235], v104 src0_sel:WORD_1
	v_pk_fma_f32 v[216:217], v[56:57], v[232:233], v[216:217] op_sel:[1,0,0]
	v_pk_fma_f32 v[218:219], v[56:57], v[234:235], v[218:219] op_sel:[1,0,0]
	v_cvt_pk_f32_fp8_e32 v[236:237], v105
	v_cvt_pk_f32_fp8_sdwa v[238:239], v105 src0_sel:WORD_1
	v_pk_fma_f32 v[220:221], v[56:57], v[236:237], v[220:221] op_sel:[1,0,0]
	v_pk_fma_f32 v[222:223], v[56:57], v[238:239], v[222:223] op_sel:[1,0,0]
	v_cvt_pk_f32_fp8_e32 v[232:233], v106
	v_cvt_pk_f32_fp8_sdwa v[234:235], v106 src0_sel:WORD_1
	v_pk_fma_f32 v[224:225], v[56:57], v[232:233], v[224:225] op_sel:[1,0,0]
	v_pk_fma_f32 v[226:227], v[56:57], v[234:235], v[226:227] op_sel:[1,0,0]
	v_cvt_pk_f32_fp8_e32 v[236:237], v107
	v_cvt_pk_f32_fp8_sdwa v[238:239], v107 src0_sel:WORD_1
	v_pk_fma_f32 v[228:229], v[56:57], v[236:237], v[228:229] op_sel:[1,0,0]
	v_pk_fma_f32 v[230:231], v[56:57], v[238:239], v[230:231] op_sel:[1,0,0]
	s_waitcnt vmcnt(25)
	v_cvt_pk_f32_fp8_e32 v[232:233], v108
	v_cvt_pk_f32_fp8_sdwa v[234:235], v108 src0_sel:WORD_1
	v_pk_fma_f32 v[216:217], v[58:59], v[232:233], v[216:217] op_sel_hi:[0,1,1]
	v_pk_fma_f32 v[218:219], v[58:59], v[234:235], v[218:219] op_sel_hi:[0,1,1]
	v_cvt_pk_f32_fp8_e32 v[236:237], v109
	v_cvt_pk_f32_fp8_sdwa v[238:239], v109 src0_sel:WORD_1
	v_pk_fma_f32 v[220:221], v[58:59], v[236:237], v[220:221] op_sel_hi:[0,1,1]
	v_pk_fma_f32 v[222:223], v[58:59], v[238:239], v[222:223] op_sel_hi:[0,1,1]
	v_cvt_pk_f32_fp8_e32 v[232:233], v110
	v_cvt_pk_f32_fp8_sdwa v[234:235], v110 src0_sel:WORD_1
	v_pk_fma_f32 v[224:225], v[58:59], v[232:233], v[224:225] op_sel_hi:[0,1,1]
	v_pk_fma_f32 v[226:227], v[58:59], v[234:235], v[226:227] op_sel_hi:[0,1,1]
	v_cvt_pk_f32_fp8_e32 v[236:237], v111
	v_cvt_pk_f32_fp8_sdwa v[238:239], v111 src0_sel:WORD_1
	v_pk_fma_f32 v[228:229], v[58:59], v[236:237], v[228:229] op_sel_hi:[0,1,1]
	v_pk_fma_f32 v[230:231], v[58:59], v[238:239], v[230:231] op_sel_hi:[0,1,1]
	s_waitcnt vmcnt(24)
	v_cvt_pk_f32_fp8_e32 v[232:233], v112
	v_cvt_pk_f32_fp8_sdwa v[234:235], v112 src0_sel:WORD_1
	v_pk_fma_f32 v[216:217], v[58:59], v[232:233], v[216:217] op_sel:[1,0,0]
	v_pk_fma_f32 v[218:219], v[58:59], v[234:235], v[218:219] op_sel:[1,0,0]
	v_cvt_pk_f32_fp8_e32 v[236:237], v113
	v_cvt_pk_f32_fp8_sdwa v[238:239], v113 src0_sel:WORD_1
	v_pk_fma_f32 v[220:221], v[58:59], v[236:237], v[220:221] op_sel:[1,0,0]
	v_pk_fma_f32 v[222:223], v[58:59], v[238:239], v[222:223] op_sel:[1,0,0]
	v_cvt_pk_f32_fp8_e32 v[232:233], v114
	v_cvt_pk_f32_fp8_sdwa v[234:235], v114 src0_sel:WORD_1
	v_pk_fma_f32 v[224:225], v[58:59], v[232:233], v[224:225] op_sel:[1,0,0]
	v_pk_fma_f32 v[226:227], v[58:59], v[234:235], v[226:227] op_sel:[1,0,0]
	v_cvt_pk_f32_fp8_e32 v[236:237], v115
	v_cvt_pk_f32_fp8_sdwa v[238:239], v115 src0_sel:WORD_1
	v_pk_fma_f32 v[228:229], v[58:59], v[236:237], v[228:229] op_sel:[1,0,0]
	v_pk_fma_f32 v[230:231], v[58:59], v[238:239], v[230:231] op_sel:[1,0,0]
	s_waitcnt vmcnt(23)
	v_cvt_pk_f32_fp8_e32 v[232:233], v116
	v_cvt_pk_f32_fp8_sdwa v[234:235], v116 src0_sel:WORD_1
	v_pk_fma_f32 v[216:217], v[60:61], v[232:233], v[216:217] op_sel_hi:[0,1,1]
	v_pk_fma_f32 v[218:219], v[60:61], v[234:235], v[218:219] op_sel_hi:[0,1,1]
	v_cvt_pk_f32_fp8_e32 v[236:237], v117
	v_cvt_pk_f32_fp8_sdwa v[238:239], v117 src0_sel:WORD_1
	v_pk_fma_f32 v[220:221], v[60:61], v[236:237], v[220:221] op_sel_hi:[0,1,1]
	v_pk_fma_f32 v[222:223], v[60:61], v[238:239], v[222:223] op_sel_hi:[0,1,1]
	v_cvt_pk_f32_fp8_e32 v[232:233], v118
	v_cvt_pk_f32_fp8_sdwa v[234:235], v118 src0_sel:WORD_1
	v_pk_fma_f32 v[224:225], v[60:61], v[232:233], v[224:225] op_sel_hi:[0,1,1]
	v_pk_fma_f32 v[226:227], v[60:61], v[234:235], v[226:227] op_sel_hi:[0,1,1]
	v_cvt_pk_f32_fp8_e32 v[236:237], v119
	v_cvt_pk_f32_fp8_sdwa v[238:239], v119 src0_sel:WORD_1
	v_pk_fma_f32 v[228:229], v[60:61], v[236:237], v[228:229] op_sel_hi:[0,1,1]
	v_pk_fma_f32 v[230:231], v[60:61], v[238:239], v[230:231] op_sel_hi:[0,1,1]
	s_waitcnt vmcnt(22)
; DI f2_t cvt8lo(unsigned w) { return __builtin_amdgcn_cvt_pk_f32_fp8(w, false); }
; DI f2_t cvt8hi(unsigned w) { return __builtin_amdgcn_cvt_pk_f32_fp8(w, true); }
; DI void phase11(const Params& p, char* smem, int rep) {
;     ...
; #pragma unroll
;         for (int k = 0; k < 16; ++k) {
;           const f2_t a2 = {aa[k], aa[k]};
; #pragma unroll
;           for (int d = 0; d < 4; ++d) { const unsigned ww = rows[k][d]; o[2 * d] += a2 * cvt8lo(ww); o[2 * d + 1] += a2 * cvt8hi(ww); }
;         }
	v_cvt_pk_f32_fp8_e32 v[232:233], v120
	v_cvt_pk_f32_fp8_sdwa v[234:235], v120 src0_sel:WORD_1
	v_pk_fma_f32 v[216:217], v[60:61], v[232:233], v[216:217] op_sel:[1,0,0]
	v_pk_fma_f32 v[218:219], v[60:61], v[234:235], v[218:219] op_sel:[1,0,0]
	v_cvt_pk_f32_fp8_e32 v[236:237], v121
	v_cvt_pk_f32_fp8_sdwa v[238:239], v121 src0_sel:WORD_1
	v_pk_fma_f32 v[220:221], v[60:61], v[236:237], v[220:221] op_sel:[1,0,0]
	v_pk_fma_f32 v[222:223], v[60:61], v[238:239], v[222:223] op_sel:[1,0,0]
	v_cvt_pk_f32_fp8_e32 v[232:233], v122
	v_cvt_pk_f32_fp8_sdwa v[234:235], v122 src0_sel:WORD_1
	v_pk_fma_f32 v[224:225], v[60:61], v[232:233], v[224:225] op_sel:[1,0,0]
	v_pk_fma_f32 v[226:227], v[60:61], v[234:235], v[226:227] op_sel:[1,0,0]
	v_cvt_pk_f32_fp8_e32 v[236:237], v123
	v_cvt_pk_f32_fp8_sdwa v[238:239], v123 src0_sel:WORD_1
	v_pk_fma_f32 v[228:229], v[60:61], v[236:237], v[228:229] op_sel:[1,0,0]
	v_pk_fma_f32 v[230:231], v[60:61], v[238:239], v[230:231] op_sel:[1,0,0]
	s_waitcnt vmcnt(21)
	v_cvt_pk_f32_fp8_e32 v[232:233], v124
	v_cvt_pk_f32_fp8_sdwa v[234:235], v124 src0_sel:WORD_1
	v_pk_fma_f32 v[216:217], v[62:63], v[232:233], v[216:217] op_sel_hi:[0,1,1]
	v_pk_fma_f32 v[218:219], v[62:63], v[234:235], v[218:219] op_sel_hi:[0,1,1]
	v_cvt_pk_f32_fp8_e32 v[236:237], v125
	v_cvt_pk_f32_fp8_sdwa v[238:239], v125 src0_sel:WORD_1
	v_pk_fma_f32 v[220:221], v[62:63], v[236:237], v[220:221] op_sel_hi:[0,1,1]
	v_pk_fma_f32 v[222:223], v[62:63], v[238:239], v[222:223] op_sel_hi:[0,1,1]
	v_cvt_pk_f32_fp8_e32 v[232:233], v126
	v_cvt_pk_f32_fp8_sdwa v[234:235], v126 src0_sel:WORD_1
	v_pk_fma_f32 v[224:225], v[62:63], v[232:233], v[224:225] op_sel_hi:[0,1,1]
	v_pk_fma_f32 v[226:227], v[62:63], v[234:235], v[226:227] op_sel_hi:[0,1,1]
	v_cvt_pk_f32_fp8_e32 v[236:237], v127
	v_cvt_pk_f32_fp8_sdwa v[238:239], v127 src0_sel:WORD_1
	v_pk_fma_f32 v[228:229], v[62:63], v[236:237], v[228:229] op_sel_hi:[0,1,1]
	v_pk_fma_f32 v[230:231], v[62:63], v[238:239], v[230:231] op_sel_hi:[0,1,1]
	s_waitcnt vmcnt(20)
	v_cvt_pk_f32_fp8_e32 v[232:233], v128
	v_cvt_pk_f32_fp8_sdwa v[234:235], v128 src0_sel:WORD_1
	v_pk_fma_f32 v[216:217], v[62:63], v[232:233], v[216:217] op_sel:[1,0,0]
	v_pk_fma_f32 v[218:219], v[62:63], v[234:235], v[218:219] op_sel:[1,0,0]
	v_cvt_pk_f32_fp8_e32 v[236:237], v129
	v_cvt_pk_f32_fp8_sdwa v[238:239], v129 src0_sel:WORD_1
	v_pk_fma_f32 v[220:221], v[62:63], v[236:237], v[220:221] op_sel:[1,0,0]
	v_pk_fma_f32 v[222:223], v[62:63], v[238:239], v[222:223] op_sel:[1,0,0]
	v_cvt_pk_f32_fp8_e32 v[232:233], v130
	v_cvt_pk_f32_fp8_sdwa v[234:235], v130 src0_sel:WORD_1
	v_pk_fma_f32 v[224:225], v[62:63], v[232:233], v[224:225] op_sel:[1,0,0]
	v_pk_fma_f32 v[226:227], v[62:63], v[234:235], v[226:227] op_sel:[1,0,0]
	v_cvt_pk_f32_fp8_e32 v[236:237], v131
	v_cvt_pk_f32_fp8_sdwa v[238:239], v131 src0_sel:WORD_1
	v_pk_fma_f32 v[228:229], v[62:63], v[236:237], v[228:229] op_sel:[1,0,0]
	v_pk_fma_f32 v[230:231], v[62:63], v[238:239], v[230:231] op_sel:[1,0,0]
	s_waitcnt vmcnt(19)
	v_cvt_pk_f32_fp8_e32 v[232:233], v132
	v_cvt_pk_f32_fp8_sdwa v[234:235], v132 src0_sel:WORD_1
	v_pk_fma_f32 v[216:217], v[64:65], v[232:233], v[216:217] op_sel_hi:[0,1,1]
	v_pk_fma_f32 v[218:219], v[64:65], v[234:235], v[218:219] op_sel_hi:[0,1,1]
	v_cvt_pk_f32_fp8_e32 v[236:237], v133
	v_cvt_pk_f32_fp8_sdwa v[238:239], v133 src0_sel:WORD_1
	v_pk_fma_f32 v[220:221], v[64:65], v[236:237], v[220:221] op_sel_hi:[0,1,1]
	v_pk_fma_f32 v[222:223], v[64:65], v[238:239], v[222:223] op_sel_hi:[0,1,1]
	v_cvt_pk_f32_fp8_e32 v[232:233], v134
	v_cvt_pk_f32_fp8_sdwa v[234:235], v134 src0_sel:WORD_1
	v_pk_fma_f32 v[224:225], v[64:65], v[232:233], v[224:225] op_sel_hi:[0,1,1]
	v_pk_fma_f32 v[226:227], v[64:65], v[234:235], v[226:227] op_sel_hi:[0,1,1]
	v_cvt_pk_f32_fp8_e32 v[236:237], v135
	v_cvt_pk_f32_fp8_sdwa v[238:239], v135 src0_sel:WORD_1
	v_pk_fma_f32 v[228:229], v[64:65], v[236:237], v[228:229] op_sel_hi:[0,1,1]
	v_pk_fma_f32 v[230:231], v[64:65], v[238:239], v[230:231] op_sel_hi:[0,1,1]
	s_waitcnt vmcnt(18)
	v_cvt_pk_f32_fp8_e32 v[232:233], v136
	v_cvt_pk_f32_fp8_sdwa v[234:235], v136 src0_sel:WORD_1
	v_pk_fma_f32 v[216:217], v[64:65], v[232:233], v[216:217] op_sel:[1,0,0]
	v_pk_fma_f32 v[218:219], v[64:65], v[234:235], v[218:219] op_sel:[1,0,0]
	v_cvt_pk_f32_fp8_e32 v[236:237], v137
	v_cvt_pk_f32_fp8_sdwa v[238:239], v137 src0_sel:WORD_1
	v_pk_fma_f32 v[220:221], v[64:65], v[236:237], v[220:221] op_sel:[1,0,0]
	v_pk_fma_f32 v[222:223], v[64:65], v[238:239], v[222:223] op_sel:[1,0,0]
	v_cvt_pk_f32_fp8_e32 v[232:233], v138
	v_cvt_pk_f32_fp8_sdwa v[234:235], v138 src0_sel:WORD_1
	v_pk_fma_f32 v[224:225], v[64:65], v[232:233], v[224:225] op_sel:[1,0,0]
	v_pk_fma_f32 v[226:227], v[64:65], v[234:235], v[226:227] op_sel:[1,0,0]
	v_cvt_pk_f32_fp8_e32 v[236:237], v139
	v_cvt_pk_f32_fp8_sdwa v[238:239], v139 src0_sel:WORD_1
	v_pk_fma_f32 v[228:229], v[64:65], v[236:237], v[228:229] op_sel:[1,0,0]
	v_pk_fma_f32 v[230:231], v[64:65], v[238:239], v[230:231] op_sel:[1,0,0]
	s_waitcnt vmcnt(17)
	v_cvt_pk_f32_fp8_e32 v[232:233], v140
	v_cvt_pk_f32_fp8_sdwa v[234:235], v140 src0_sel:WORD_1
	v_pk_fma_f32 v[216:217], v[66:67], v[232:233], v[216:217] op_sel_hi:[0,1,1]
	v_pk_fma_f32 v[218:219], v[66:67], v[234:235], v[218:219] op_sel_hi:[0,1,1]
	v_cvt_pk_f32_fp8_e32 v[236:237], v141
	v_cvt_pk_f32_fp8_sdwa v[238:239], v141 src0_sel:WORD_1
	v_pk_fma_f32 v[220:221], v[66:67], v[236:237], v[220:221] op_sel_hi:[0,1,1]
	v_pk_fma_f32 v[222:223], v[66:67], v[238:239], v[222:223] op_sel_hi:[0,1,1]
	v_cvt_pk_f32_fp8_e32 v[232:233], v142
	v_cvt_pk_f32_fp8_sdwa v[234:235], v142 src0_sel:WORD_1
	v_pk_fma_f32 v[224:225], v[66:67], v[232:233], v[224:225] op_sel_hi:[0,1,1]
	v_pk_fma_f32 v[226:227], v[66:67], v[234:235], v[226:227] op_sel_hi:[0,1,1]
	v_cvt_pk_f32_fp8_e32 v[236:237], v143
	v_cvt_pk_f32_fp8_sdwa v[238:239], v143 src0_sel:WORD_1
	v_pk_fma_f32 v[228:229], v[66:67], v[236:237], v[228:229] op_sel_hi:[0,1,1]
	v_pk_fma_f32 v[230:231], v[66:67], v[238:239], v[230:231] op_sel_hi:[0,1,1]
	s_waitcnt vmcnt(16)
; DI f2_t cvt8lo(unsigned w) { return __builtin_amdgcn_cvt_pk_f32_fp8(w, false); }
; DI f2_t cvt8hi(unsigned w) { return __builtin_amdgcn_cvt_pk_f32_fp8(w, true); }
; DI void wave_lds_sync() { asm volatile("s_waitcnt lgkmcnt(0)" ::: "memory"); __builtin_amdgcn_wave_barrier(); }
; DI void phase11(const Params& p, char* smem, int rep) {
;     ...
;       wave_lds_sync();
;       lw[(lane & 3) * 32 + (lane >> 2)] = i0; lw[(lane & 3) * 32 + 16 + (lane >> 2)] = i1;
;       lf[(lane & 3) * 32 + (lane >> 2)] = a0; lf[(lane & 3) * 32 + 16 + (lane >> 2)] = a1;
;       wave_lds_sync();
;     ...
; #pragma unroll
;         for (int k = 0; k < 16; ++k) {
;           const f2_t a2 = {aa[k], aa[k]};
; #pragma unroll
;           for (int d = 0; d < 4; ++d) { const unsigned ww = rows[k][d]; o[2 * d] += a2 * cvt8lo(ww); o[2 * d + 1] += a2 * cvt8hi(ww); }
;         }
	v_cvt_pk_f32_fp8_e32 v[232:233], v144
	v_cvt_pk_f32_fp8_sdwa v[234:235], v144 src0_sel:WORD_1
	v_pk_fma_f32 v[216:217], v[66:67], v[232:233], v[216:217] op_sel:[1,0,0]
	v_pk_fma_f32 v[218:219], v[66:67], v[234:235], v[218:219] op_sel:[1,0,0]
	v_cvt_pk_f32_fp8_e32 v[236:237], v145
	v_cvt_pk_f32_fp8_sdwa v[238:239], v145 src0_sel:WORD_1
	v_pk_fma_f32 v[220:221], v[66:67], v[236:237], v[220:221] op_sel:[1,0,0]
	v_pk_fma_f32 v[222:223], v[66:67], v[238:239], v[222:223] op_sel:[1,0,0]
	v_cvt_pk_f32_fp8_e32 v[232:233], v146
	v_cvt_pk_f32_fp8_sdwa v[234:235], v146 src0_sel:WORD_1
	v_pk_fma_f32 v[224:225], v[66:67], v[232:233], v[224:225] op_sel:[1,0,0]
	v_pk_fma_f32 v[226:227], v[66:67], v[234:235], v[226:227] op_sel:[1,0,0]
	v_cvt_pk_f32_fp8_e32 v[236:237], v147
	v_cvt_pk_f32_fp8_sdwa v[238:239], v147 src0_sel:WORD_1
	v_pk_fma_f32 v[228:229], v[66:67], v[236:237], v[228:229] op_sel:[1,0,0]
	v_pk_fma_f32 v[230:231], v[66:67], v[238:239], v[230:231] op_sel:[1,0,0]
	ds_write2_b32 v5, v10, v11 offset0:4 offset1:20
	ds_write2_b32 v5, v12, v13 offset0:132 offset1:148
	s_waitcnt lgkmcnt(0)
	ds_read_b128 v[20:23], v6 offset:16
	ds_read_b128 v[24:27], v6 offset:32
	ds_read_b128 v[28:31], v6 offset:48
	ds_read_b128 v[32:35], v6 offset:64
	ds_read_b128 v[36:39], v6 offset:80
	ds_read_b128 v[40:43], v6 offset:96
	ds_read_b128 v[44:47], v6 offset:112
	ds_read_b128 v[48:51], v6 offset:128
	s_waitcnt vmcnt(15)
	v_cvt_pk_f32_fp8_e32 v[232:233], v148
	v_cvt_pk_f32_fp8_sdwa v[234:235], v148 src0_sel:WORD_1
	v_pk_fma_f32 v[216:217], v[68:69], v[232:233], v[216:217] op_sel_hi:[0,1,1]
	v_pk_fma_f32 v[218:219], v[68:69], v[234:235], v[218:219] op_sel_hi:[0,1,1]
	v_cvt_pk_f32_fp8_e32 v[236:237], v149
	v_cvt_pk_f32_fp8_sdwa v[238:239], v149 src0_sel:WORD_1
	v_pk_fma_f32 v[220:221], v[68:69], v[236:237], v[220:221] op_sel_hi:[0,1,1]
	v_pk_fma_f32 v[222:223], v[68:69], v[238:239], v[222:223] op_sel_hi:[0,1,1]
	v_cvt_pk_f32_fp8_e32 v[232:233], v150
	v_cvt_pk_f32_fp8_sdwa v[234:235], v150 src0_sel:WORD_1
	v_pk_fma_f32 v[224:225], v[68:69], v[232:233], v[224:225] op_sel_hi:[0,1,1]
	v_pk_fma_f32 v[226:227], v[68:69], v[234:235], v[226:227] op_sel_hi:[0,1,1]
	v_cvt_pk_f32_fp8_e32 v[236:237], v151
	v_cvt_pk_f32_fp8_sdwa v[238:239], v151 src0_sel:WORD_1
	v_pk_fma_f32 v[228:229], v[68:69], v[236:237], v[228:229] op_sel_hi:[0,1,1]
	v_pk_fma_f32 v[230:231], v[68:69], v[238:239], v[230:231] op_sel_hi:[0,1,1]
	s_waitcnt vmcnt(14)
	v_cvt_pk_f32_fp8_e32 v[232:233], v152
	v_cvt_pk_f32_fp8_sdwa v[234:235], v152 src0_sel:WORD_1
	v_pk_fma_f32 v[216:217], v[68:69], v[232:233], v[216:217] op_sel:[1,0,0]
	v_pk_fma_f32 v[218:219], v[68:69], v[234:235], v[218:219] op_sel:[1,0,0]
	v_cvt_pk_f32_fp8_e32 v[236:237], v153
	v_cvt_pk_f32_fp8_sdwa v[238:239], v153 src0_sel:WORD_1
	v_pk_fma_f32 v[220:221], v[68:69], v[236:237], v[220:221] op_sel:[1,0,0]
	v_pk_fma_f32 v[222:223], v[68:69], v[238:239], v[222:223] op_sel:[1,0,0]
	v_cvt_pk_f32_fp8_e32 v[232:233], v154
	v_cvt_pk_f32_fp8_sdwa v[234:235], v154 src0_sel:WORD_1
	v_pk_fma_f32 v[224:225], v[68:69], v[232:233], v[224:225] op_sel:[1,0,0]
	v_pk_fma_f32 v[226:227], v[68:69], v[234:235], v[226:227] op_sel:[1,0,0]
	v_cvt_pk_f32_fp8_e32 v[236:237], v155
	v_cvt_pk_f32_fp8_sdwa v[238:239], v155 src0_sel:WORD_1
	v_pk_fma_f32 v[228:229], v[68:69], v[236:237], v[228:229] op_sel:[1,0,0]
	v_pk_fma_f32 v[230:231], v[68:69], v[238:239], v[230:231] op_sel:[1,0,0]
	s_waitcnt vmcnt(13)
	v_cvt_pk_f32_fp8_e32 v[232:233], v156
	v_cvt_pk_f32_fp8_sdwa v[234:235], v156 src0_sel:WORD_1
	v_pk_fma_f32 v[216:217], v[70:71], v[232:233], v[216:217] op_sel_hi:[0,1,1]
	v_pk_fma_f32 v[218:219], v[70:71], v[234:235], v[218:219] op_sel_hi:[0,1,1]
	v_cvt_pk_f32_fp8_e32 v[236:237], v157
	v_cvt_pk_f32_fp8_sdwa v[238:239], v157 src0_sel:WORD_1
	v_pk_fma_f32 v[220:221], v[70:71], v[236:237], v[220:221] op_sel_hi:[0,1,1]
	v_pk_fma_f32 v[222:223], v[70:71], v[238:239], v[222:223] op_sel_hi:[0,1,1]
	v_cvt_pk_f32_fp8_e32 v[232:233], v158
	v_cvt_pk_f32_fp8_sdwa v[234:235], v158 src0_sel:WORD_1
	v_pk_fma_f32 v[224:225], v[70:71], v[232:233], v[224:225] op_sel_hi:[0,1,1]
	v_pk_fma_f32 v[226:227], v[70:71], v[234:235], v[226:227] op_sel_hi:[0,1,1]
	v_cvt_pk_f32_fp8_e32 v[236:237], v159
	v_cvt_pk_f32_fp8_sdwa v[238:239], v159 src0_sel:WORD_1
	v_pk_fma_f32 v[228:229], v[70:71], v[236:237], v[228:229] op_sel_hi:[0,1,1]
	v_pk_fma_f32 v[230:231], v[70:71], v[238:239], v[230:231] op_sel_hi:[0,1,1]
	s_waitcnt vmcnt(12)
	v_cvt_pk_f32_fp8_e32 v[232:233], v160
	v_cvt_pk_f32_fp8_sdwa v[234:235], v160 src0_sel:WORD_1
	v_pk_fma_f32 v[216:217], v[70:71], v[232:233], v[216:217] op_sel:[1,0,0]
	v_pk_fma_f32 v[218:219], v[70:71], v[234:235], v[218:219] op_sel:[1,0,0]
	v_cvt_pk_f32_fp8_e32 v[236:237], v161
	v_cvt_pk_f32_fp8_sdwa v[238:239], v161 src0_sel:WORD_1
	v_pk_fma_f32 v[220:221], v[70:71], v[236:237], v[220:221] op_sel:[1,0,0]
	v_pk_fma_f32 v[222:223], v[70:71], v[238:239], v[222:223] op_sel:[1,0,0]
	v_cvt_pk_f32_fp8_e32 v[232:233], v162
	v_cvt_pk_f32_fp8_sdwa v[234:235], v162 src0_sel:WORD_1
	v_pk_fma_f32 v[224:225], v[70:71], v[232:233], v[224:225] op_sel:[1,0,0]
	v_pk_fma_f32 v[226:227], v[70:71], v[234:235], v[226:227] op_sel:[1,0,0]
	v_cvt_pk_f32_fp8_e32 v[236:237], v163
	v_cvt_pk_f32_fp8_sdwa v[238:239], v163 src0_sel:WORD_1
	v_pk_fma_f32 v[228:229], v[70:71], v[236:237], v[228:229] op_sel:[1,0,0]
	v_pk_fma_f32 v[230:231], v[70:71], v[238:239], v[230:231] op_sel:[1,0,0]
	s_waitcnt vmcnt(11)
; DI f2_t cvt8lo(unsigned w) { return __builtin_amdgcn_cvt_pk_f32_fp8(w, false); }
; DI f2_t cvt8hi(unsigned w) { return __builtin_amdgcn_cvt_pk_f32_fp8(w, true); }
; DI void phase11(const Params& p, char* smem, int rep) {
;     ...
;         for (int k = 0; k < 16; ++k) rows[k] = *(const u32x4*)(vb + (size_t)ida[k] * 2048);
; #pragma unroll
;         for (int k = 0; k < 16; ++k) {
;           const f2_t a2 = {aa[k], aa[k]};
; #pragma unroll
;           for (int d = 0; d < 4; ++d) { const unsigned ww = rows[k][d]; o[2 * d] += a2 * cvt8lo(ww); o[2 * d + 1] += a2 * cvt8hi(ww); }
;         }
	v_cvt_pk_f32_fp8_e32 v[232:233], v164
	v_cvt_pk_f32_fp8_sdwa v[234:235], v164 src0_sel:WORD_1
	v_pk_fma_f32 v[216:217], v[72:73], v[232:233], v[216:217] op_sel_hi:[0,1,1]
	v_pk_fma_f32 v[218:219], v[72:73], v[234:235], v[218:219] op_sel_hi:[0,1,1]
	v_cvt_pk_f32_fp8_e32 v[236:237], v165
	v_cvt_pk_f32_fp8_sdwa v[238:239], v165 src0_sel:WORD_1
	v_pk_fma_f32 v[220:221], v[72:73], v[236:237], v[220:221] op_sel_hi:[0,1,1]
	v_pk_fma_f32 v[222:223], v[72:73], v[238:239], v[222:223] op_sel_hi:[0,1,1]
	v_cvt_pk_f32_fp8_e32 v[232:233], v166
	v_cvt_pk_f32_fp8_sdwa v[234:235], v166 src0_sel:WORD_1
	v_pk_fma_f32 v[224:225], v[72:73], v[232:233], v[224:225] op_sel_hi:[0,1,1]
	v_pk_fma_f32 v[226:227], v[72:73], v[234:235], v[226:227] op_sel_hi:[0,1,1]
	v_cvt_pk_f32_fp8_e32 v[236:237], v167
	v_cvt_pk_f32_fp8_sdwa v[238:239], v167 src0_sel:WORD_1
	v_pk_fma_f32 v[228:229], v[72:73], v[236:237], v[228:229] op_sel_hi:[0,1,1]
	v_pk_fma_f32 v[230:231], v[72:73], v[238:239], v[230:231] op_sel_hi:[0,1,1]
	s_waitcnt vmcnt(10)
	v_cvt_pk_f32_fp8_e32 v[232:233], v168
	v_cvt_pk_f32_fp8_sdwa v[234:235], v168 src0_sel:WORD_1
	v_pk_fma_f32 v[216:217], v[72:73], v[232:233], v[216:217] op_sel:[1,0,0]
	v_pk_fma_f32 v[218:219], v[72:73], v[234:235], v[218:219] op_sel:[1,0,0]
	v_cvt_pk_f32_fp8_e32 v[236:237], v169
	v_cvt_pk_f32_fp8_sdwa v[238:239], v169 src0_sel:WORD_1
	v_pk_fma_f32 v[220:221], v[72:73], v[236:237], v[220:221] op_sel:[1,0,0]
	v_pk_fma_f32 v[222:223], v[72:73], v[238:239], v[222:223] op_sel:[1,0,0]
	v_cvt_pk_f32_fp8_e32 v[232:233], v170
	v_cvt_pk_f32_fp8_sdwa v[234:235], v170 src0_sel:WORD_1
	v_pk_fma_f32 v[224:225], v[72:73], v[232:233], v[224:225] op_sel:[1,0,0]
	v_pk_fma_f32 v[226:227], v[72:73], v[234:235], v[226:227] op_sel:[1,0,0]
	v_cvt_pk_f32_fp8_e32 v[236:237], v171
	v_cvt_pk_f32_fp8_sdwa v[238:239], v171 src0_sel:WORD_1
	v_pk_fma_f32 v[228:229], v[72:73], v[236:237], v[228:229] op_sel:[1,0,0]
	v_pk_fma_f32 v[230:231], v[72:73], v[238:239], v[230:231] op_sel:[1,0,0]
	s_waitcnt vmcnt(9)
	v_cvt_pk_f32_fp8_e32 v[232:233], v172
	v_cvt_pk_f32_fp8_sdwa v[234:235], v172 src0_sel:WORD_1
	v_pk_fma_f32 v[216:217], v[74:75], v[232:233], v[216:217] op_sel_hi:[0,1,1]
	v_pk_fma_f32 v[218:219], v[74:75], v[234:235], v[218:219] op_sel_hi:[0,1,1]
	v_cvt_pk_f32_fp8_e32 v[236:237], v173
	v_cvt_pk_f32_fp8_sdwa v[238:239], v173 src0_sel:WORD_1
	v_pk_fma_f32 v[220:221], v[74:75], v[236:237], v[220:221] op_sel_hi:[0,1,1]
	v_pk_fma_f32 v[222:223], v[74:75], v[238:239], v[222:223] op_sel_hi:[0,1,1]
	v_cvt_pk_f32_fp8_e32 v[232:233], v174
	v_cvt_pk_f32_fp8_sdwa v[234:235], v174 src0_sel:WORD_1
	v_pk_fma_f32 v[224:225], v[74:75], v[232:233], v[224:225] op_sel_hi:[0,1,1]
	v_pk_fma_f32 v[226:227], v[74:75], v[234:235], v[226:227] op_sel_hi:[0,1,1]
	v_cvt_pk_f32_fp8_e32 v[236:237], v175
	v_cvt_pk_f32_fp8_sdwa v[238:239], v175 src0_sel:WORD_1
	v_pk_fma_f32 v[228:229], v[74:75], v[236:237], v[228:229] op_sel_hi:[0,1,1]
	v_pk_fma_f32 v[230:231], v[74:75], v[238:239], v[230:231] op_sel_hi:[0,1,1]
	s_waitcnt vmcnt(8)
	v_cvt_pk_f32_fp8_e32 v[232:233], v176
	v_cvt_pk_f32_fp8_sdwa v[234:235], v176 src0_sel:WORD_1
	v_pk_fma_f32 v[216:217], v[74:75], v[232:233], v[216:217] op_sel:[1,0,0]
	v_pk_fma_f32 v[218:219], v[74:75], v[234:235], v[218:219] op_sel:[1,0,0]
	v_cvt_pk_f32_fp8_e32 v[236:237], v177
	v_cvt_pk_f32_fp8_sdwa v[238:239], v177 src0_sel:WORD_1
	v_pk_fma_f32 v[220:221], v[74:75], v[236:237], v[220:221] op_sel:[1,0,0]
	v_pk_fma_f32 v[222:223], v[74:75], v[238:239], v[222:223] op_sel:[1,0,0]
	v_cvt_pk_f32_fp8_e32 v[232:233], v178
	v_cvt_pk_f32_fp8_sdwa v[234:235], v178 src0_sel:WORD_1
	v_pk_fma_f32 v[224:225], v[74:75], v[232:233], v[224:225] op_sel:[1,0,0]
	v_pk_fma_f32 v[226:227], v[74:75], v[234:235], v[226:227] op_sel:[1,0,0]
	v_cvt_pk_f32_fp8_e32 v[236:237], v179
	v_cvt_pk_f32_fp8_sdwa v[238:239], v179 src0_sel:WORD_1
	v_pk_fma_f32 v[228:229], v[74:75], v[236:237], v[228:229] op_sel:[1,0,0]
	v_pk_fma_f32 v[230:231], v[74:75], v[238:239], v[230:231] op_sel:[1,0,0]
	s_waitcnt vmcnt(7)
	v_cvt_pk_f32_fp8_e32 v[232:233], v180
	v_cvt_pk_f32_fp8_sdwa v[234:235], v180 src0_sel:WORD_1
	v_pk_fma_f32 v[216:217], v[76:77], v[232:233], v[216:217] op_sel_hi:[0,1,1]
	v_pk_fma_f32 v[218:219], v[76:77], v[234:235], v[218:219] op_sel_hi:[0,1,1]
	v_cvt_pk_f32_fp8_e32 v[236:237], v181
	v_cvt_pk_f32_fp8_sdwa v[238:239], v181 src0_sel:WORD_1
	v_pk_fma_f32 v[220:221], v[76:77], v[236:237], v[220:221] op_sel_hi:[0,1,1]
	v_pk_fma_f32 v[222:223], v[76:77], v[238:239], v[222:223] op_sel_hi:[0,1,1]
	v_cvt_pk_f32_fp8_e32 v[232:233], v182
	v_cvt_pk_f32_fp8_sdwa v[234:235], v182 src0_sel:WORD_1
	v_pk_fma_f32 v[224:225], v[76:77], v[232:233], v[224:225] op_sel_hi:[0,1,1]
	v_pk_fma_f32 v[226:227], v[76:77], v[234:235], v[226:227] op_sel_hi:[0,1,1]
	v_cvt_pk_f32_fp8_e32 v[236:237], v183
	v_cvt_pk_f32_fp8_sdwa v[238:239], v183 src0_sel:WORD_1
	v_pk_fma_f32 v[228:229], v[76:77], v[236:237], v[228:229] op_sel_hi:[0,1,1]
	v_pk_fma_f32 v[230:231], v[76:77], v[238:239], v[230:231] op_sel_hi:[0,1,1]
	s_waitcnt vmcnt(6)
	v_cvt_pk_f32_fp8_e32 v[232:233], v184
	v_cvt_pk_f32_fp8_sdwa v[234:235], v184 src0_sel:WORD_1
	v_pk_fma_f32 v[216:217], v[76:77], v[232:233], v[216:217] op_sel:[1,0,0]
	v_pk_fma_f32 v[218:219], v[76:77], v[234:235], v[218:219] op_sel:[1,0,0]
	v_cvt_pk_f32_fp8_e32 v[236:237], v185
	v_cvt_pk_f32_fp8_sdwa v[238:239], v185 src0_sel:WORD_1
	v_pk_fma_f32 v[220:221], v[76:77], v[236:237], v[220:221] op_sel:[1,0,0]
	v_pk_fma_f32 v[222:223], v[76:77], v[238:239], v[222:223] op_sel:[1,0,0]
	v_cvt_pk_f32_fp8_e32 v[232:233], v186
	v_cvt_pk_f32_fp8_sdwa v[234:235], v186 src0_sel:WORD_1
	v_pk_fma_f32 v[224:225], v[76:77], v[232:233], v[224:225] op_sel:[1,0,0]
	v_pk_fma_f32 v[226:227], v[76:77], v[234:235], v[226:227] op_sel:[1,0,0]
	v_cvt_pk_f32_fp8_e32 v[236:237], v187
	v_cvt_pk_f32_fp8_sdwa v[238:239], v187 src0_sel:WORD_1
	v_pk_fma_f32 v[228:229], v[76:77], v[236:237], v[228:229] op_sel:[1,0,0]
	v_pk_fma_f32 v[230:231], v[76:77], v[238:239], v[230:231] op_sel:[1,0,0]
	s_waitcnt vmcnt(5)
; DI f2_t cvt8lo(unsigned w) { return __builtin_amdgcn_cvt_pk_f32_fp8(w, false); }
; DI f2_t cvt8hi(unsigned w) { return __builtin_amdgcn_cvt_pk_f32_fp8(w, true); }
; DI void phase11(const Params& p, char* smem, int rep) {
;     ...
;         for (int k = 0; k < 16; ++k) rows[k] = *(const u32x4*)(vb + (size_t)ida[k] * 2048);
; #pragma unroll
;         for (int k = 0; k < 16; ++k) {
;           const f2_t a2 = {aa[k], aa[k]};
; #pragma unroll
;           for (int d = 0; d < 4; ++d) { const unsigned ww = rows[k][d]; o[2 * d] += a2 * cvt8lo(ww); o[2 * d + 1] += a2 * cvt8hi(ww); }
;         }
	v_cvt_pk_f32_fp8_e32 v[232:233], v190
	v_cvt_pk_f32_fp8_sdwa v[234:235], v190 src0_sel:WORD_1
	v_pk_fma_f32 v[216:217], v[78:79], v[232:233], v[216:217] op_sel_hi:[0,1,1]
	v_pk_fma_f32 v[218:219], v[78:79], v[234:235], v[218:219] op_sel_hi:[0,1,1]
	v_cvt_pk_f32_fp8_e32 v[236:237], v191
	v_cvt_pk_f32_fp8_sdwa v[238:239], v191 src0_sel:WORD_1
	v_pk_fma_f32 v[220:221], v[78:79], v[236:237], v[220:221] op_sel_hi:[0,1,1]
	v_pk_fma_f32 v[222:223], v[78:79], v[238:239], v[222:223] op_sel_hi:[0,1,1]
	v_cvt_pk_f32_fp8_e32 v[232:233], v192
	v_cvt_pk_f32_fp8_sdwa v[234:235], v192 src0_sel:WORD_1
	v_pk_fma_f32 v[224:225], v[78:79], v[232:233], v[224:225] op_sel_hi:[0,1,1]
	v_pk_fma_f32 v[226:227], v[78:79], v[234:235], v[226:227] op_sel_hi:[0,1,1]
	v_cvt_pk_f32_fp8_e32 v[236:237], v193
	v_cvt_pk_f32_fp8_sdwa v[238:239], v193 src0_sel:WORD_1
	v_pk_fma_f32 v[228:229], v[78:79], v[236:237], v[228:229] op_sel_hi:[0,1,1]
	v_pk_fma_f32 v[230:231], v[78:79], v[238:239], v[230:231] op_sel_hi:[0,1,1]
	s_waitcnt vmcnt(4)
	v_cvt_pk_f32_fp8_e32 v[232:233], v194
	v_cvt_pk_f32_fp8_sdwa v[234:235], v194 src0_sel:WORD_1
	v_pk_fma_f32 v[216:217], v[78:79], v[232:233], v[216:217] op_sel:[1,0,0]
	v_pk_fma_f32 v[218:219], v[78:79], v[234:235], v[218:219] op_sel:[1,0,0]
	v_cvt_pk_f32_fp8_e32 v[236:237], v195
	v_cvt_pk_f32_fp8_sdwa v[238:239], v195 src0_sel:WORD_1
	v_pk_fma_f32 v[220:221], v[78:79], v[236:237], v[220:221] op_sel:[1,0,0]
	v_pk_fma_f32 v[222:223], v[78:79], v[238:239], v[222:223] op_sel:[1,0,0]
	v_cvt_pk_f32_fp8_e32 v[232:233], v196
	v_cvt_pk_f32_fp8_sdwa v[234:235], v196 src0_sel:WORD_1
	v_pk_fma_f32 v[224:225], v[78:79], v[232:233], v[224:225] op_sel:[1,0,0]
	v_pk_fma_f32 v[226:227], v[78:79], v[234:235], v[226:227] op_sel:[1,0,0]
	v_cvt_pk_f32_fp8_e32 v[236:237], v197
	v_cvt_pk_f32_fp8_sdwa v[238:239], v197 src0_sel:WORD_1
	v_pk_fma_f32 v[228:229], v[78:79], v[236:237], v[228:229] op_sel:[1,0,0]
	v_pk_fma_f32 v[230:231], v[78:79], v[238:239], v[230:231] op_sel:[1,0,0]
	s_waitcnt vmcnt(3)
	v_cvt_pk_f32_fp8_e32 v[232:233], v198
	v_cvt_pk_f32_fp8_sdwa v[234:235], v198 src0_sel:WORD_1
	v_pk_fma_f32 v[216:217], v[80:81], v[232:233], v[216:217] op_sel_hi:[0,1,1]
	v_pk_fma_f32 v[218:219], v[80:81], v[234:235], v[218:219] op_sel_hi:[0,1,1]
	v_cvt_pk_f32_fp8_e32 v[236:237], v199
	v_cvt_pk_f32_fp8_sdwa v[238:239], v199 src0_sel:WORD_1
	v_pk_fma_f32 v[220:221], v[80:81], v[236:237], v[220:221] op_sel_hi:[0,1,1]
	v_pk_fma_f32 v[222:223], v[80:81], v[238:239], v[222:223] op_sel_hi:[0,1,1]
	v_cvt_pk_f32_fp8_e32 v[232:233], v200
	v_cvt_pk_f32_fp8_sdwa v[234:235], v200 src0_sel:WORD_1
	v_pk_fma_f32 v[224:225], v[80:81], v[232:233], v[224:225] op_sel_hi:[0,1,1]
	v_pk_fma_f32 v[226:227], v[80:81], v[234:235], v[226:227] op_sel_hi:[0,1,1]
	v_cvt_pk_f32_fp8_e32 v[236:237], v201
	v_cvt_pk_f32_fp8_sdwa v[238:239], v201 src0_sel:WORD_1
	v_pk_fma_f32 v[228:229], v[80:81], v[236:237], v[228:229] op_sel_hi:[0,1,1]
	v_pk_fma_f32 v[230:231], v[80:81], v[238:239], v[230:231] op_sel_hi:[0,1,1]
	s_waitcnt vmcnt(2)
	v_cvt_pk_f32_fp8_e32 v[232:233], v202
	v_cvt_pk_f32_fp8_sdwa v[234:235], v202 src0_sel:WORD_1
	v_pk_fma_f32 v[216:217], v[80:81], v[232:233], v[216:217] op_sel:[1,0,0]
	v_pk_fma_f32 v[218:219], v[80:81], v[234:235], v[218:219] op_sel:[1,0,0]
	v_cvt_pk_f32_fp8_e32 v[236:237], v203
	v_cvt_pk_f32_fp8_sdwa v[238:239], v203 src0_sel:WORD_1
	v_pk_fma_f32 v[220:221], v[80:81], v[236:237], v[220:221] op_sel:[1,0,0]
	v_pk_fma_f32 v[222:223], v[80:81], v[238:239], v[222:223] op_sel:[1,0,0]
	v_cvt_pk_f32_fp8_e32 v[232:233], v204
	v_cvt_pk_f32_fp8_sdwa v[234:235], v204 src0_sel:WORD_1
	v_pk_fma_f32 v[224:225], v[80:81], v[232:233], v[224:225] op_sel:[1,0,0]
	v_pk_fma_f32 v[226:227], v[80:81], v[234:235], v[226:227] op_sel:[1,0,0]
	v_cvt_pk_f32_fp8_e32 v[236:237], v205
	v_cvt_pk_f32_fp8_sdwa v[238:239], v205 src0_sel:WORD_1
	v_pk_fma_f32 v[228:229], v[80:81], v[236:237], v[228:229] op_sel:[1,0,0]
	v_pk_fma_f32 v[230:231], v[80:81], v[238:239], v[230:231] op_sel:[1,0,0]
	s_waitcnt vmcnt(1)
	v_cvt_pk_f32_fp8_e32 v[232:233], v206
	v_cvt_pk_f32_fp8_sdwa v[234:235], v206 src0_sel:WORD_1
	v_pk_fma_f32 v[216:217], v[82:83], v[232:233], v[216:217] op_sel_hi:[0,1,1]
	v_pk_fma_f32 v[218:219], v[82:83], v[234:235], v[218:219] op_sel_hi:[0,1,1]
	v_cvt_pk_f32_fp8_e32 v[236:237], v207
	v_cvt_pk_f32_fp8_sdwa v[238:239], v207 src0_sel:WORD_1
	v_pk_fma_f32 v[220:221], v[82:83], v[236:237], v[220:221] op_sel_hi:[0,1,1]
	v_pk_fma_f32 v[222:223], v[82:83], v[238:239], v[222:223] op_sel_hi:[0,1,1]
	v_cvt_pk_f32_fp8_e32 v[232:233], v208
	v_cvt_pk_f32_fp8_sdwa v[234:235], v208 src0_sel:WORD_1
	v_pk_fma_f32 v[224:225], v[82:83], v[232:233], v[224:225] op_sel_hi:[0,1,1]
	v_pk_fma_f32 v[226:227], v[82:83], v[234:235], v[226:227] op_sel_hi:[0,1,1]
	v_cvt_pk_f32_fp8_e32 v[236:237], v209
	v_cvt_pk_f32_fp8_sdwa v[238:239], v209 src0_sel:WORD_1
	v_pk_fma_f32 v[228:229], v[82:83], v[236:237], v[228:229] op_sel_hi:[0,1,1]
	v_pk_fma_f32 v[230:231], v[82:83], v[238:239], v[230:231] op_sel_hi:[0,1,1]
	s_waitcnt vmcnt(0)
; DI unsigned pk2(float a, float b) { f2_t v = {a, b}; bf2_t r = __builtin_convertvector(v, bf2_t); return __builtin_bit_cast(unsigned, r); }
; DI void wave_lds_sync() { asm volatile("s_waitcnt lgkmcnt(0)" ::: "memory"); __builtin_amdgcn_wave_barrier(); }
; DI void phase11(const Params& p, char* smem, int rep) {
;     ...
;       const int tok = __builtin_amdgcn_readfirstlane(c * 16 + w * 4 + t);
;       const int i0 = IDS[(size_t)tok * 128 + lane], i1 = IDS[(size_t)tok * 128 + 64 + lane];
;       const float a0 = ACT[(size_t)tok * 128 + lane], a1 = ACT[(size_t)tok * 128 + 64 + lane];
;       wave_lds_sync();
;       lw[(lane & 3) * 32 + (lane >> 2)] = i0; lw[(lane & 3) * 32 + 16 + (lane >> 2)] = i1;
;       lf[(lane & 3) * 32 + (lane >> 2)] = a0; lf[(lane & 3) * 32 + 16 + (lane >> 2)] = a1;
;       wave_lds_sync();
;     ...
;       float ov[16];
; #pragma unroll
;       for (int d = 0; d < 4; ++d) { ov[4 * d] = o[2 * d].x; ov[4 * d + 1] = o[2 * d].y; ov[4 * d + 2] = o[2 * d + 1].x; ov[4 * d + 3] = o[2 * d + 1].y; }
;       float q8[8], q4[4];
; #pragma unroll
;       for (int k = 0; k < 8; ++k) q8[k] = (b5 ? ov[8 + k] : ov[k]) + __shfl_xor(b5 ? ov[k] : ov[8 + k], 32);
; #pragma unroll
;       for (int k = 0; k < 4; ++k) q4[k] = (b4 ? q8[4 + k] : q8[k]) + __shfl_xor(b4 ? q8[k] : q8[4 + k], 16);
;       *(uint2*)(OUTP + (size_t)tok * D_ + s * 256 + l15 * 16 + 8 * b5 + 4 * b4) = make_uint2(pk2(q4[0], q4[1]), pk2(q4[2], q4[3]));
	v_cvt_pk_f32_fp8_e32 v[232:233], v210
	v_cvt_pk_f32_fp8_sdwa v[234:235], v210 src0_sel:WORD_1
	v_pk_fma_f32 v[216:217], v[82:83], v[232:233], v[216:217] op_sel:[1,0,0]
	v_pk_fma_f32 v[218:219], v[82:83], v[234:235], v[218:219] op_sel:[1,0,0]
	v_cvt_pk_f32_fp8_e32 v[236:237], v211
	v_cvt_pk_f32_fp8_sdwa v[238:239], v211 src0_sel:WORD_1
	v_pk_fma_f32 v[220:221], v[82:83], v[236:237], v[220:221] op_sel:[1,0,0]
	v_pk_fma_f32 v[222:223], v[82:83], v[238:239], v[222:223] op_sel:[1,0,0]
	v_cvt_pk_f32_fp8_e32 v[232:233], v212
	v_cvt_pk_f32_fp8_sdwa v[234:235], v212 src0_sel:WORD_1
	v_pk_fma_f32 v[224:225], v[82:83], v[232:233], v[224:225] op_sel:[1,0,0]
	v_pk_fma_f32 v[226:227], v[82:83], v[234:235], v[226:227] op_sel:[1,0,0]
	v_cvt_pk_f32_fp8_e32 v[236:237], v213
	v_cvt_pk_f32_fp8_sdwa v[238:239], v213 src0_sel:WORD_1
	v_pk_fma_f32 v[228:229], v[82:83], v[236:237], v[228:229] op_sel:[1,0,0]
	v_pk_fma_f32 v[230:231], v[82:83], v[238:239], v[230:231] op_sel:[1,0,0]
	ds_read_b128 v[52:55], v6 offset:528
	ds_read_b128 v[56:59], v6 offset:544
	ds_read_b128 v[60:63], v6 offset:560
	ds_read_b128 v[64:67], v6 offset:576
	ds_read_b128 v[68:71], v6 offset:592
	ds_read_b128 v[72:75], v6 offset:608
	ds_read_b128 v[76:79], v6 offset:624
	ds_read_b128 v[80:83], v6 offset:640
	v_add_u32_e32 v214, s46, v4
	s_nop 0
	v_permlane32_swap_b32_e32 v216, v224
	v_permlane32_swap_b32_e32 v217, v225
	v_permlane32_swap_b32_e32 v218, v226
	v_permlane32_swap_b32_e32 v219, v227
	v_permlane32_swap_b32_e32 v220, v228
	v_permlane32_swap_b32_e32 v221, v229
	v_permlane32_swap_b32_e32 v222, v230
	v_permlane32_swap_b32_e32 v223, v231
	v_add_f32_e32 v216, v216, v224
	v_add_f32_e32 v217, v217, v225
	v_add_f32_e32 v218, v218, v226
	v_add_f32_e32 v219, v219, v227
	v_add_f32_e32 v220, v220, v228
	v_add_f32_e32 v221, v221, v229
	v_add_f32_e32 v222, v222, v230
	v_add_f32_e32 v223, v223, v231
	s_nop 1
	v_permlane16_swap_b32_e32 v216, v220
	v_permlane16_swap_b32_e32 v217, v221
	v_permlane16_swap_b32_e32 v218, v222
	v_permlane16_swap_b32_e32 v219, v223
	v_add_f32_e32 v216, v216, v220
	v_add_f32_e32 v217, v217, v221
	v_add_f32_e32 v218, v218, v222
	v_add_f32_e32 v219, v219, v223
	v_cvt_pk_bf16_f32 v232, v216, v217
	v_cvt_pk_bf16_f32 v233, v218, v219
	global_store_dwordx2 v214, v[232:233], s[14:15]
	s_add_i32 s54, s34, 1
	s_lshl_b32 s46, s54, 12
	s_add_i32 s46, s46, s24
	s_add_i32 s55, s34, 2
	s_lshl_b32 s47, s55, 9
	s_add_u32 s42, s6, s47
	s_addc_u32 s43, s7, 0
	s_add_u32 s44, s8, s47
	s_addc_u32 s45, s9, 0
	global_load_dword v10, v3, s[42:43]
	global_load_dword v11, v3, s[42:43] offset:256
	global_load_dword v12, v3, s[44:45]
	global_load_dword v13, v3, s[44:45] offset:256
	s_waitcnt lgkmcnt(0)
	v_lshl_add_u32 v20, v20, 11, v2
	v_lshl_add_u32 v21, v21, 11, v2
	v_lshl_add_u32 v22, v22, 11, v2
	v_lshl_add_u32 v23, v23, 11, v2
	v_lshl_add_u32 v24, v24, 11, v2
	v_lshl_add_u32 v25, v25, 11, v2
	v_lshl_add_u32 v26, v26, 11, v2
	v_lshl_add_u32 v27, v27, 11, v2
	v_lshl_add_u32 v28, v28, 11, v2
	v_lshl_add_u32 v29, v29, 11, v2
	v_lshl_add_u32 v30, v30, 11, v2
	v_lshl_add_u32 v31, v31, 11, v2
	v_lshl_add_u32 v32, v32, 11, v2
	v_lshl_add_u32 v33, v33, 11, v2
	v_lshl_add_u32 v34, v34, 11, v2
	v_lshl_add_u32 v35, v35, 11, v2
	v_lshl_add_u32 v36, v36, 11, v2
	v_lshl_add_u32 v37, v37, 11, v2
	v_lshl_add_u32 v38, v38, 11, v2
	v_lshl_add_u32 v39, v39, 11, v2
	v_lshl_add_u32 v40, v40, 11, v2
	v_lshl_add_u32 v41, v41, 11, v2
	v_lshl_add_u32 v42, v42, 11, v2
	v_lshl_add_u32 v43, v43, 11, v2
	v_lshl_add_u32 v44, v44, 11, v2
	v_lshl_add_u32 v45, v45, 11, v2
	v_lshl_add_u32 v46, v46, 11, v2
	v_lshl_add_u32 v47, v47, 11, v2
	v_lshl_add_u32 v48, v48, 11, v2
	v_lshl_add_u32 v49, v49, 11, v2
	v_lshl_add_u32 v50, v50, 11, v2
	v_lshl_add_u32 v51, v51, 11, v2
	global_load_dwordx4 v[84:87], v20, s[20:21]
	global_load_dwordx4 v[88:91], v21, s[20:21]
	global_load_dwordx4 v[92:95], v22, s[20:21]
	global_load_dwordx4 v[96:99], v23, s[20:21]
	global_load_dwordx4 v[100:103], v24, s[20:21]
	global_load_dwordx4 v[104:107], v25, s[20:21]
	global_load_dwordx4 v[108:111], v26, s[20:21]
	global_load_dwordx4 v[112:115], v27, s[20:21]
	global_load_dwordx4 v[116:119], v28, s[20:21]
	global_load_dwordx4 v[120:123], v29, s[20:21]
	global_load_dwordx4 v[124:127], v30, s[20:21]
	global_load_dwordx4 v[128:131], v31, s[20:21]
	global_load_dwordx4 v[132:135], v32, s[20:21]
	global_load_dwordx4 v[136:139], v33, s[20:21]
	global_load_dwordx4 v[140:143], v34, s[20:21]
	global_load_dwordx4 v[144:147], v35, s[20:21]
	global_load_dwordx4 v[148:151], v36, s[20:21]
	global_load_dwordx4 v[152:155], v37, s[20:21]
	global_load_dwordx4 v[156:159], v38, s[20:21]
	global_load_dwordx4 v[160:163], v39, s[20:21]
	global_load_dwordx4 v[164:167], v40, s[20:21]
	global_load_dwordx4 v[168:171], v41, s[20:21]
	global_load_dwordx4 v[172:175], v42, s[20:21]
	global_load_dwordx4 v[176:179], v43, s[20:21]
	global_load_dwordx4 v[180:183], v44, s[20:21]
	global_load_dwordx4 v[184:187], v45, s[20:21]
	global_load_dwordx4 v[190:193], v46, s[20:21]
	global_load_dwordx4 v[194:197], v47, s[20:21]
	global_load_dwordx4 v[198:201], v48, s[20:21]
	global_load_dwordx4 v[202:205], v49, s[20:21]
	global_load_dwordx4 v[206:209], v50, s[20:21]
	global_load_dwordx4 v[210:213], v51, s[20:21]
	s_waitcnt vmcnt(31)
; DI f2_t cvt8lo(unsigned w) { return __builtin_amdgcn_cvt_pk_f32_fp8(w, false); }
; DI f2_t cvt8hi(unsigned w) { return __builtin_amdgcn_cvt_pk_f32_fp8(w, true); }
; DI void phase11(const Params& p, char* smem, int rep) {
;     ...
;         for (int k = 0; k < 16; ++k) rows[k] = *(const u32x4*)(vb + (size_t)ida[k] * 2048);
; #pragma unroll
;         for (int k = 0; k < 16; ++k) {
;           const f2_t a2 = {aa[k], aa[k]};
; #pragma unroll
;           for (int d = 0; d < 4; ++d) { const unsigned ww = rows[k][d]; o[2 * d] += a2 * cvt8lo(ww); o[2 * d + 1] += a2 * cvt8hi(ww); }
;         }
	v_cvt_pk_f32_fp8_e32 v[232:233], v84
	v_cvt_pk_f32_fp8_sdwa v[234:235], v84 src0_sel:WORD_1
	v_pk_fma_f32 v[216:217], v[52:53], v[232:233], 0 op_sel_hi:[0,1,0]
	v_pk_fma_f32 v[218:219], v[52:53], v[234:235], 0 op_sel_hi:[0,1,0]
	v_cvt_pk_f32_fp8_e32 v[236:237], v85
	v_cvt_pk_f32_fp8_sdwa v[238:239], v85 src0_sel:WORD_1
	v_pk_fma_f32 v[220:221], v[52:53], v[236:237], 0 op_sel_hi:[0,1,0]
	v_pk_fma_f32 v[222:223], v[52:53], v[238:239], 0 op_sel_hi:[0,1,0]
	v_cvt_pk_f32_fp8_e32 v[232:233], v86
	v_cvt_pk_f32_fp8_sdwa v[234:235], v86 src0_sel:WORD_1
	v_pk_fma_f32 v[224:225], v[52:53], v[232:233], 0 op_sel_hi:[0,1,0]
	v_pk_fma_f32 v[226:227], v[52:53], v[234:235], 0 op_sel_hi:[0,1,0]
	v_cvt_pk_f32_fp8_e32 v[236:237], v87
	v_cvt_pk_f32_fp8_sdwa v[238:239], v87 src0_sel:WORD_1
	v_pk_fma_f32 v[228:229], v[52:53], v[236:237], 0 op_sel_hi:[0,1,0]
	v_pk_fma_f32 v[230:231], v[52:53], v[238:239], 0 op_sel_hi:[0,1,0]
	s_waitcnt vmcnt(30)
	v_cvt_pk_f32_fp8_e32 v[232:233], v88
	v_cvt_pk_f32_fp8_sdwa v[234:235], v88 src0_sel:WORD_1
	v_pk_fma_f32 v[216:217], v[52:53], v[232:233], v[216:217] op_sel:[1,0,0]
	v_pk_fma_f32 v[218:219], v[52:53], v[234:235], v[218:219] op_sel:[1,0,0]
	v_cvt_pk_f32_fp8_e32 v[236:237], v89
	v_cvt_pk_f32_fp8_sdwa v[238:239], v89 src0_sel:WORD_1
	v_pk_fma_f32 v[220:221], v[52:53], v[236:237], v[220:221] op_sel:[1,0,0]
	v_pk_fma_f32 v[222:223], v[52:53], v[238:239], v[222:223] op_sel:[1,0,0]
	v_cvt_pk_f32_fp8_e32 v[232:233], v90
	v_cvt_pk_f32_fp8_sdwa v[234:235], v90 src0_sel:WORD_1
	v_pk_fma_f32 v[224:225], v[52:53], v[232:233], v[224:225] op_sel:[1,0,0]
	v_pk_fma_f32 v[226:227], v[52:53], v[234:235], v[226:227] op_sel:[1,0,0]
	v_cvt_pk_f32_fp8_e32 v[236:237], v91
	v_cvt_pk_f32_fp8_sdwa v[238:239], v91 src0_sel:WORD_1
	v_pk_fma_f32 v[228:229], v[52:53], v[236:237], v[228:229] op_sel:[1,0,0]
	v_pk_fma_f32 v[230:231], v[52:53], v[238:239], v[230:231] op_sel:[1,0,0]
	s_waitcnt vmcnt(29)
	v_cvt_pk_f32_fp8_e32 v[232:233], v92
	v_cvt_pk_f32_fp8_sdwa v[234:235], v92 src0_sel:WORD_1
	v_pk_fma_f32 v[216:217], v[54:55], v[232:233], v[216:217] op_sel_hi:[0,1,1]
	v_pk_fma_f32 v[218:219], v[54:55], v[234:235], v[218:219] op_sel_hi:[0,1,1]
	v_cvt_pk_f32_fp8_e32 v[236:237], v93
	v_cvt_pk_f32_fp8_sdwa v[238:239], v93 src0_sel:WORD_1
	v_pk_fma_f32 v[220:221], v[54:55], v[236:237], v[220:221] op_sel_hi:[0,1,1]
	v_pk_fma_f32 v[222:223], v[54:55], v[238:239], v[222:223] op_sel_hi:[0,1,1]
	v_cvt_pk_f32_fp8_e32 v[232:233], v94
	v_cvt_pk_f32_fp8_sdwa v[234:235], v94 src0_sel:WORD_1
	v_pk_fma_f32 v[224:225], v[54:55], v[232:233], v[224:225] op_sel_hi:[0,1,1]
	v_pk_fma_f32 v[226:227], v[54:55], v[234:235], v[226:227] op_sel_hi:[0,1,1]
	v_cvt_pk_f32_fp8_e32 v[236:237], v95
	v_cvt_pk_f32_fp8_sdwa v[238:239], v95 src0_sel:WORD_1
	v_pk_fma_f32 v[228:229], v[54:55], v[236:237], v[228:229] op_sel_hi:[0,1,1]
	v_pk_fma_f32 v[230:231], v[54:55], v[238:239], v[230:231] op_sel_hi:[0,1,1]
	s_waitcnt vmcnt(28)
	v_cvt_pk_f32_fp8_e32 v[232:233], v96
	v_cvt_pk_f32_fp8_sdwa v[234:235], v96 src0_sel:WORD_1
	v_pk_fma_f32 v[216:217], v[54:55], v[232:233], v[216:217] op_sel:[1,0,0]
	v_pk_fma_f32 v[218:219], v[54:55], v[234:235], v[218:219] op_sel:[1,0,0]
	v_cvt_pk_f32_fp8_e32 v[236:237], v97
	v_cvt_pk_f32_fp8_sdwa v[238:239], v97 src0_sel:WORD_1
	v_pk_fma_f32 v[220:221], v[54:55], v[236:237], v[220:221] op_sel:[1,0,0]
	v_pk_fma_f32 v[222:223], v[54:55], v[238:239], v[222:223] op_sel:[1,0,0]
	v_cvt_pk_f32_fp8_e32 v[232:233], v98
	v_cvt_pk_f32_fp8_sdwa v[234:235], v98 src0_sel:WORD_1
	v_pk_fma_f32 v[224:225], v[54:55], v[232:233], v[224:225] op_sel:[1,0,0]
	v_pk_fma_f32 v[226:227], v[54:55], v[234:235], v[226:227] op_sel:[1,0,0]
	v_cvt_pk_f32_fp8_e32 v[236:237], v99
	v_cvt_pk_f32_fp8_sdwa v[238:239], v99 src0_sel:WORD_1
	v_pk_fma_f32 v[228:229], v[54:55], v[236:237], v[228:229] op_sel:[1,0,0]
	v_pk_fma_f32 v[230:231], v[54:55], v[238:239], v[230:231] op_sel:[1,0,0]
	s_waitcnt vmcnt(27)
	v_cvt_pk_f32_fp8_e32 v[232:233], v100
	v_cvt_pk_f32_fp8_sdwa v[234:235], v100 src0_sel:WORD_1
	v_pk_fma_f32 v[216:217], v[56:57], v[232:233], v[216:217] op_sel_hi:[0,1,1]
	v_pk_fma_f32 v[218:219], v[56:57], v[234:235], v[218:219] op_sel_hi:[0,1,1]
	v_cvt_pk_f32_fp8_e32 v[236:237], v101
	v_cvt_pk_f32_fp8_sdwa v[238:239], v101 src0_sel:WORD_1
	v_pk_fma_f32 v[220:221], v[56:57], v[236:237], v[220:221] op_sel_hi:[0,1,1]
	v_pk_fma_f32 v[222:223], v[56:57], v[238:239], v[222:223] op_sel_hi:[0,1,1]
	v_cvt_pk_f32_fp8_e32 v[232:233], v102
	v_cvt_pk_f32_fp8_sdwa v[234:235], v102 src0_sel:WORD_1
	v_pk_fma_f32 v[224:225], v[56:57], v[232:233], v[224:225] op_sel_hi:[0,1,1]
	v_pk_fma_f32 v[226:227], v[56:57], v[234:235], v[226:227] op_sel_hi:[0,1,1]
	v_cvt_pk_f32_fp8_e32 v[236:237], v103
	v_cvt_pk_f32_fp8_sdwa v[238:239], v103 src0_sel:WORD_1
	v_pk_fma_f32 v[228:229], v[56:57], v[236:237], v[228:229] op_sel_hi:[0,1,1]
	v_pk_fma_f32 v[230:231], v[56:57], v[238:239], v[230:231] op_sel_hi:[0,1,1]
	s_waitcnt vmcnt(26)
	v_cvt_pk_f32_fp8_e32 v[232:233], v104
	v_cvt_pk_f32_fp8_sdwa v[234:235], v104 src0_sel:WORD_1
	v_pk_fma_f32 v[216:217], v[56:57], v[232:233], v[216:217] op_sel:[1,0,0]
	v_pk_fma_f32 v[218:219], v[56:57], v[234:235], v[218:219] op_sel:[1,0,0]
	v_cvt_pk_f32_fp8_e32 v[236:237], v105
	v_cvt_pk_f32_fp8_sdwa v[238:239], v105 src0_sel:WORD_1
	v_pk_fma_f32 v[220:221], v[56:57], v[236:237], v[220:221] op_sel:[1,0,0]
	v_pk_fma_f32 v[222:223], v[56:57], v[238:239], v[222:223] op_sel:[1,0,0]
	v_cvt_pk_f32_fp8_e32 v[232:233], v106
	v_cvt_pk_f32_fp8_sdwa v[234:235], v106 src0_sel:WORD_1
	v_pk_fma_f32 v[224:225], v[56:57], v[232:233], v[224:225] op_sel:[1,0,0]
	v_pk_fma_f32 v[226:227], v[56:57], v[234:235], v[226:227] op_sel:[1,0,0]
	v_cvt_pk_f32_fp8_e32 v[236:237], v107
	v_cvt_pk_f32_fp8_sdwa v[238:239], v107 src0_sel:WORD_1
	v_pk_fma_f32 v[228:229], v[56:57], v[236:237], v[228:229] op_sel:[1,0,0]
	v_pk_fma_f32 v[230:231], v[56:57], v[238:239], v[230:231] op_sel:[1,0,0]
	s_waitcnt vmcnt(25)
; DI f2_t cvt8lo(unsigned w) { return __builtin_amdgcn_cvt_pk_f32_fp8(w, false); }
; DI f2_t cvt8hi(unsigned w) { return __builtin_amdgcn_cvt_pk_f32_fp8(w, true); }
; DI void phase11(const Params& p, char* smem, int rep) {
;     ...
;         for (int k = 0; k < 16; ++k) rows[k] = *(const u32x4*)(vb + (size_t)ida[k] * 2048);
; #pragma unroll
;         for (int k = 0; k < 16; ++k) {
;           const f2_t a2 = {aa[k], aa[k]};
; #pragma unroll
;           for (int d = 0; d < 4; ++d) { const unsigned ww = rows[k][d]; o[2 * d] += a2 * cvt8lo(ww); o[2 * d + 1] += a2 * cvt8hi(ww); }
;         }
	v_cvt_pk_f32_fp8_e32 v[232:233], v108
	v_cvt_pk_f32_fp8_sdwa v[234:235], v108 src0_sel:WORD_1
	v_pk_fma_f32 v[216:217], v[58:59], v[232:233], v[216:217] op_sel_hi:[0,1,1]
	v_pk_fma_f32 v[218:219], v[58:59], v[234:235], v[218:219] op_sel_hi:[0,1,1]
	v_cvt_pk_f32_fp8_e32 v[236:237], v109
	v_cvt_pk_f32_fp8_sdwa v[238:239], v109 src0_sel:WORD_1
	v_pk_fma_f32 v[220:221], v[58:59], v[236:237], v[220:221] op_sel_hi:[0,1,1]
	v_pk_fma_f32 v[222:223], v[58:59], v[238:239], v[222:223] op_sel_hi:[0,1,1]
	v_cvt_pk_f32_fp8_e32 v[232:233], v110
	v_cvt_pk_f32_fp8_sdwa v[234:235], v110 src0_sel:WORD_1
	v_pk_fma_f32 v[224:225], v[58:59], v[232:233], v[224:225] op_sel_hi:[0,1,1]
	v_pk_fma_f32 v[226:227], v[58:59], v[234:235], v[226:227] op_sel_hi:[0,1,1]
	v_cvt_pk_f32_fp8_e32 v[236:237], v111
	v_cvt_pk_f32_fp8_sdwa v[238:239], v111 src0_sel:WORD_1
	v_pk_fma_f32 v[228:229], v[58:59], v[236:237], v[228:229] op_sel_hi:[0,1,1]
	v_pk_fma_f32 v[230:231], v[58:59], v[238:239], v[230:231] op_sel_hi:[0,1,1]
	s_waitcnt vmcnt(24)
	v_cvt_pk_f32_fp8_e32 v[232:233], v112
	v_cvt_pk_f32_fp8_sdwa v[234:235], v112 src0_sel:WORD_1
	v_pk_fma_f32 v[216:217], v[58:59], v[232:233], v[216:217] op_sel:[1,0,0]
	v_pk_fma_f32 v[218:219], v[58:59], v[234:235], v[218:219] op_sel:[1,0,0]
	v_cvt_pk_f32_fp8_e32 v[236:237], v113
	v_cvt_pk_f32_fp8_sdwa v[238:239], v113 src0_sel:WORD_1
	v_pk_fma_f32 v[220:221], v[58:59], v[236:237], v[220:221] op_sel:[1,0,0]
	v_pk_fma_f32 v[222:223], v[58:59], v[238:239], v[222:223] op_sel:[1,0,0]
	v_cvt_pk_f32_fp8_e32 v[232:233], v114
	v_cvt_pk_f32_fp8_sdwa v[234:235], v114 src0_sel:WORD_1
	v_pk_fma_f32 v[224:225], v[58:59], v[232:233], v[224:225] op_sel:[1,0,0]
	v_pk_fma_f32 v[226:227], v[58:59], v[234:235], v[226:227] op_sel:[1,0,0]
	v_cvt_pk_f32_fp8_e32 v[236:237], v115
	v_cvt_pk_f32_fp8_sdwa v[238:239], v115 src0_sel:WORD_1
	v_pk_fma_f32 v[228:229], v[58:59], v[236:237], v[228:229] op_sel:[1,0,0]
	v_pk_fma_f32 v[230:231], v[58:59], v[238:239], v[230:231] op_sel:[1,0,0]
	s_waitcnt vmcnt(23)
	v_cvt_pk_f32_fp8_e32 v[232:233], v116
	v_cvt_pk_f32_fp8_sdwa v[234:235], v116 src0_sel:WORD_1
	v_pk_fma_f32 v[216:217], v[60:61], v[232:233], v[216:217] op_sel_hi:[0,1,1]
	v_pk_fma_f32 v[218:219], v[60:61], v[234:235], v[218:219] op_sel_hi:[0,1,1]
	v_cvt_pk_f32_fp8_e32 v[236:237], v117
	v_cvt_pk_f32_fp8_sdwa v[238:239], v117 src0_sel:WORD_1
	v_pk_fma_f32 v[220:221], v[60:61], v[236:237], v[220:221] op_sel_hi:[0,1,1]
	v_pk_fma_f32 v[222:223], v[60:61], v[238:239], v[222:223] op_sel_hi:[0,1,1]
	v_cvt_pk_f32_fp8_e32 v[232:233], v118
	v_cvt_pk_f32_fp8_sdwa v[234:235], v118 src0_sel:WORD_1
	v_pk_fma_f32 v[224:225], v[60:61], v[232:233], v[224:225] op_sel_hi:[0,1,1]
	v_pk_fma_f32 v[226:227], v[60:61], v[234:235], v[226:227] op_sel_hi:[0,1,1]
	v_cvt_pk_f32_fp8_e32 v[236:237], v119
	v_cvt_pk_f32_fp8_sdwa v[238:239], v119 src0_sel:WORD_1
	v_pk_fma_f32 v[228:229], v[60:61], v[236:237], v[228:229] op_sel_hi:[0,1,1]
	v_pk_fma_f32 v[230:231], v[60:61], v[238:239], v[230:231] op_sel_hi:[0,1,1]
	s_waitcnt vmcnt(22)
	v_cvt_pk_f32_fp8_e32 v[232:233], v120
	v_cvt_pk_f32_fp8_sdwa v[234:235], v120 src0_sel:WORD_1
	v_pk_fma_f32 v[216:217], v[60:61], v[232:233], v[216:217] op_sel:[1,0,0]
	v_pk_fma_f32 v[218:219], v[60:61], v[234:235], v[218:219] op_sel:[1,0,0]
	v_cvt_pk_f32_fp8_e32 v[236:237], v121
	v_cvt_pk_f32_fp8_sdwa v[238:239], v121 src0_sel:WORD_1
	v_pk_fma_f32 v[220:221], v[60:61], v[236:237], v[220:221] op_sel:[1,0,0]
	v_pk_fma_f32 v[222:223], v[60:61], v[238:239], v[222:223] op_sel:[1,0,0]
	v_cvt_pk_f32_fp8_e32 v[232:233], v122
	v_cvt_pk_f32_fp8_sdwa v[234:235], v122 src0_sel:WORD_1
	v_pk_fma_f32 v[224:225], v[60:61], v[232:233], v[224:225] op_sel:[1,0,0]
	v_pk_fma_f32 v[226:227], v[60:61], v[234:235], v[226:227] op_sel:[1,0,0]
	v_cvt_pk_f32_fp8_e32 v[236:237], v123
	v_cvt_pk_f32_fp8_sdwa v[238:239], v123 src0_sel:WORD_1
	v_pk_fma_f32 v[228:229], v[60:61], v[236:237], v[228:229] op_sel:[1,0,0]
	v_pk_fma_f32 v[230:231], v[60:61], v[238:239], v[230:231] op_sel:[1,0,0]
	s_waitcnt vmcnt(21)
	v_cvt_pk_f32_fp8_e32 v[232:233], v124
	v_cvt_pk_f32_fp8_sdwa v[234:235], v124 src0_sel:WORD_1
	v_pk_fma_f32 v[216:217], v[62:63], v[232:233], v[216:217] op_sel_hi:[0,1,1]
	v_pk_fma_f32 v[218:219], v[62:63], v[234:235], v[218:219] op_sel_hi:[0,1,1]
	v_cvt_pk_f32_fp8_e32 v[236:237], v125
	v_cvt_pk_f32_fp8_sdwa v[238:239], v125 src0_sel:WORD_1
	v_pk_fma_f32 v[220:221], v[62:63], v[236:237], v[220:221] op_sel_hi:[0,1,1]
	v_pk_fma_f32 v[222:223], v[62:63], v[238:239], v[222:223] op_sel_hi:[0,1,1]
	v_cvt_pk_f32_fp8_e32 v[232:233], v126
	v_cvt_pk_f32_fp8_sdwa v[234:235], v126 src0_sel:WORD_1
	v_pk_fma_f32 v[224:225], v[62:63], v[232:233], v[224:225] op_sel_hi:[0,1,1]
	v_pk_fma_f32 v[226:227], v[62:63], v[234:235], v[226:227] op_sel_hi:[0,1,1]
	v_cvt_pk_f32_fp8_e32 v[236:237], v127
	v_cvt_pk_f32_fp8_sdwa v[238:239], v127 src0_sel:WORD_1
	v_pk_fma_f32 v[228:229], v[62:63], v[236:237], v[228:229] op_sel_hi:[0,1,1]
	v_pk_fma_f32 v[230:231], v[62:63], v[238:239], v[230:231] op_sel_hi:[0,1,1]
	s_waitcnt vmcnt(20)
	v_cvt_pk_f32_fp8_e32 v[232:233], v128
	v_cvt_pk_f32_fp8_sdwa v[234:235], v128 src0_sel:WORD_1
	v_pk_fma_f32 v[216:217], v[62:63], v[232:233], v[216:217] op_sel:[1,0,0]
	v_pk_fma_f32 v[218:219], v[62:63], v[234:235], v[218:219] op_sel:[1,0,0]
	v_cvt_pk_f32_fp8_e32 v[236:237], v129
	v_cvt_pk_f32_fp8_sdwa v[238:239], v129 src0_sel:WORD_1
	v_pk_fma_f32 v[220:221], v[62:63], v[236:237], v[220:221] op_sel:[1,0,0]
	v_pk_fma_f32 v[222:223], v[62:63], v[238:239], v[222:223] op_sel:[1,0,0]
	v_cvt_pk_f32_fp8_e32 v[232:233], v130
	v_cvt_pk_f32_fp8_sdwa v[234:235], v130 src0_sel:WORD_1
	v_pk_fma_f32 v[224:225], v[62:63], v[232:233], v[224:225] op_sel:[1,0,0]
	v_pk_fma_f32 v[226:227], v[62:63], v[234:235], v[226:227] op_sel:[1,0,0]
	v_cvt_pk_f32_fp8_e32 v[236:237], v131
	v_cvt_pk_f32_fp8_sdwa v[238:239], v131 src0_sel:WORD_1
	v_pk_fma_f32 v[228:229], v[62:63], v[236:237], v[228:229] op_sel:[1,0,0]
	v_pk_fma_f32 v[230:231], v[62:63], v[238:239], v[230:231] op_sel:[1,0,0]
	s_waitcnt vmcnt(19)
; DI f2_t cvt8lo(unsigned w) { return __builtin_amdgcn_cvt_pk_f32_fp8(w, false); }
; DI f2_t cvt8hi(unsigned w) { return __builtin_amdgcn_cvt_pk_f32_fp8(w, true); }
; DI void wave_lds_sync() { asm volatile("s_waitcnt lgkmcnt(0)" ::: "memory"); __builtin_amdgcn_wave_barrier(); }
; DI void phase11(const Params& p, char* smem, int rep) {
;     ...
;       wave_lds_sync();
;       lw[(lane & 3) * 32 + (lane >> 2)] = i0; lw[(lane & 3) * 32 + 16 + (lane >> 2)] = i1;
;       lf[(lane & 3) * 32 + (lane >> 2)] = a0; lf[(lane & 3) * 32 + 16 + (lane >> 2)] = a1;
;       wave_lds_sync();
;     ...
;         for (int k = 0; k < 16; ++k) rows[k] = *(const u32x4*)(vb + (size_t)ida[k] * 2048);
; #pragma unroll
;         for (int k = 0; k < 16; ++k) {
;           const f2_t a2 = {aa[k], aa[k]};
; #pragma unroll
;           for (int d = 0; d < 4; ++d) { const unsigned ww = rows[k][d]; o[2 * d] += a2 * cvt8lo(ww); o[2 * d + 1] += a2 * cvt8hi(ww); }
;         }
	v_cvt_pk_f32_fp8_e32 v[232:233], v132
	v_cvt_pk_f32_fp8_sdwa v[234:235], v132 src0_sel:WORD_1
	v_pk_fma_f32 v[216:217], v[64:65], v[232:233], v[216:217] op_sel_hi:[0,1,1]
	v_pk_fma_f32 v[218:219], v[64:65], v[234:235], v[218:219] op_sel_hi:[0,1,1]
	v_cvt_pk_f32_fp8_e32 v[236:237], v133
	v_cvt_pk_f32_fp8_sdwa v[238:239], v133 src0_sel:WORD_1
	v_pk_fma_f32 v[220:221], v[64:65], v[236:237], v[220:221] op_sel_hi:[0,1,1]
	v_pk_fma_f32 v[222:223], v[64:65], v[238:239], v[222:223] op_sel_hi:[0,1,1]
	v_cvt_pk_f32_fp8_e32 v[232:233], v134
	v_cvt_pk_f32_fp8_sdwa v[234:235], v134 src0_sel:WORD_1
	v_pk_fma_f32 v[224:225], v[64:65], v[232:233], v[224:225] op_sel_hi:[0,1,1]
	v_pk_fma_f32 v[226:227], v[64:65], v[234:235], v[226:227] op_sel_hi:[0,1,1]
	v_cvt_pk_f32_fp8_e32 v[236:237], v135
	v_cvt_pk_f32_fp8_sdwa v[238:239], v135 src0_sel:WORD_1
	v_pk_fma_f32 v[228:229], v[64:65], v[236:237], v[228:229] op_sel_hi:[0,1,1]
	v_pk_fma_f32 v[230:231], v[64:65], v[238:239], v[230:231] op_sel_hi:[0,1,1]
	s_waitcnt vmcnt(18)
	v_cvt_pk_f32_fp8_e32 v[232:233], v136
	v_cvt_pk_f32_fp8_sdwa v[234:235], v136 src0_sel:WORD_1
	v_pk_fma_f32 v[216:217], v[64:65], v[232:233], v[216:217] op_sel:[1,0,0]
	v_pk_fma_f32 v[218:219], v[64:65], v[234:235], v[218:219] op_sel:[1,0,0]
	v_cvt_pk_f32_fp8_e32 v[236:237], v137
	v_cvt_pk_f32_fp8_sdwa v[238:239], v137 src0_sel:WORD_1
	v_pk_fma_f32 v[220:221], v[64:65], v[236:237], v[220:221] op_sel:[1,0,0]
	v_pk_fma_f32 v[222:223], v[64:65], v[238:239], v[222:223] op_sel:[1,0,0]
	v_cvt_pk_f32_fp8_e32 v[232:233], v138
	v_cvt_pk_f32_fp8_sdwa v[234:235], v138 src0_sel:WORD_1
	v_pk_fma_f32 v[224:225], v[64:65], v[232:233], v[224:225] op_sel:[1,0,0]
	v_pk_fma_f32 v[226:227], v[64:65], v[234:235], v[226:227] op_sel:[1,0,0]
	v_cvt_pk_f32_fp8_e32 v[236:237], v139
	v_cvt_pk_f32_fp8_sdwa v[238:239], v139 src0_sel:WORD_1
	v_pk_fma_f32 v[228:229], v[64:65], v[236:237], v[228:229] op_sel:[1,0,0]
	v_pk_fma_f32 v[230:231], v[64:65], v[238:239], v[230:231] op_sel:[1,0,0]
	s_waitcnt vmcnt(17)
	v_cvt_pk_f32_fp8_e32 v[232:233], v140
	v_cvt_pk_f32_fp8_sdwa v[234:235], v140 src0_sel:WORD_1
	v_pk_fma_f32 v[216:217], v[66:67], v[232:233], v[216:217] op_sel_hi:[0,1,1]
	v_pk_fma_f32 v[218:219], v[66:67], v[234:235], v[218:219] op_sel_hi:[0,1,1]
	v_cvt_pk_f32_fp8_e32 v[236:237], v141
	v_cvt_pk_f32_fp8_sdwa v[238:239], v141 src0_sel:WORD_1
	v_pk_fma_f32 v[220:221], v[66:67], v[236:237], v[220:221] op_sel_hi:[0,1,1]
	v_pk_fma_f32 v[222:223], v[66:67], v[238:239], v[222:223] op_sel_hi:[0,1,1]
	v_cvt_pk_f32_fp8_e32 v[232:233], v142
	v_cvt_pk_f32_fp8_sdwa v[234:235], v142 src0_sel:WORD_1
	v_pk_fma_f32 v[224:225], v[66:67], v[232:233], v[224:225] op_sel_hi:[0,1,1]
	v_pk_fma_f32 v[226:227], v[66:67], v[234:235], v[226:227] op_sel_hi:[0,1,1]
	v_cvt_pk_f32_fp8_e32 v[236:237], v143
	v_cvt_pk_f32_fp8_sdwa v[238:239], v143 src0_sel:WORD_1
	v_pk_fma_f32 v[228:229], v[66:67], v[236:237], v[228:229] op_sel_hi:[0,1,1]
	v_pk_fma_f32 v[230:231], v[66:67], v[238:239], v[230:231] op_sel_hi:[0,1,1]
	s_waitcnt vmcnt(16)
	v_cvt_pk_f32_fp8_e32 v[232:233], v144
	v_cvt_pk_f32_fp8_sdwa v[234:235], v144 src0_sel:WORD_1
	v_pk_fma_f32 v[216:217], v[66:67], v[232:233], v[216:217] op_sel:[1,0,0]
	v_pk_fma_f32 v[218:219], v[66:67], v[234:235], v[218:219] op_sel:[1,0,0]
	v_cvt_pk_f32_fp8_e32 v[236:237], v145
	v_cvt_pk_f32_fp8_sdwa v[238:239], v145 src0_sel:WORD_1
	v_pk_fma_f32 v[220:221], v[66:67], v[236:237], v[220:221] op_sel:[1,0,0]
	v_pk_fma_f32 v[222:223], v[66:67], v[238:239], v[222:223] op_sel:[1,0,0]
	v_cvt_pk_f32_fp8_e32 v[232:233], v146
	v_cvt_pk_f32_fp8_sdwa v[234:235], v146 src0_sel:WORD_1
	v_pk_fma_f32 v[224:225], v[66:67], v[232:233], v[224:225] op_sel:[1,0,0]
	v_pk_fma_f32 v[226:227], v[66:67], v[234:235], v[226:227] op_sel:[1,0,0]
	v_cvt_pk_f32_fp8_e32 v[236:237], v147
	v_cvt_pk_f32_fp8_sdwa v[238:239], v147 src0_sel:WORD_1
	v_pk_fma_f32 v[228:229], v[66:67], v[236:237], v[228:229] op_sel:[1,0,0]
	v_pk_fma_f32 v[230:231], v[66:67], v[238:239], v[230:231] op_sel:[1,0,0]
	ds_write2_b32 v5, v10, v11 offset0:4 offset1:20
	ds_write2_b32 v5, v12, v13 offset0:132 offset1:148
	s_waitcnt lgkmcnt(0)
	ds_read_b128 v[20:23], v6 offset:16
	ds_read_b128 v[24:27], v6 offset:32
	ds_read_b128 v[28:31], v6 offset:48
	ds_read_b128 v[32:35], v6 offset:64
	ds_read_b128 v[36:39], v6 offset:80
	ds_read_b128 v[40:43], v6 offset:96
	ds_read_b128 v[44:47], v6 offset:112
	ds_read_b128 v[48:51], v6 offset:128
	s_waitcnt vmcnt(15)
	v_cvt_pk_f32_fp8_e32 v[232:233], v148
	v_cvt_pk_f32_fp8_sdwa v[234:235], v148 src0_sel:WORD_1
	v_pk_fma_f32 v[216:217], v[68:69], v[232:233], v[216:217] op_sel_hi:[0,1,1]
	v_pk_fma_f32 v[218:219], v[68:69], v[234:235], v[218:219] op_sel_hi:[0,1,1]
	v_cvt_pk_f32_fp8_e32 v[236:237], v149
	v_cvt_pk_f32_fp8_sdwa v[238:239], v149 src0_sel:WORD_1
	v_pk_fma_f32 v[220:221], v[68:69], v[236:237], v[220:221] op_sel_hi:[0,1,1]
	v_pk_fma_f32 v[222:223], v[68:69], v[238:239], v[222:223] op_sel_hi:[0,1,1]
	v_cvt_pk_f32_fp8_e32 v[232:233], v150
	v_cvt_pk_f32_fp8_sdwa v[234:235], v150 src0_sel:WORD_1
	v_pk_fma_f32 v[224:225], v[68:69], v[232:233], v[224:225] op_sel_hi:[0,1,1]
	v_pk_fma_f32 v[226:227], v[68:69], v[234:235], v[226:227] op_sel_hi:[0,1,1]
	v_cvt_pk_f32_fp8_e32 v[236:237], v151
	v_cvt_pk_f32_fp8_sdwa v[238:239], v151 src0_sel:WORD_1
	v_pk_fma_f32 v[228:229], v[68:69], v[236:237], v[228:229] op_sel_hi:[0,1,1]
	v_pk_fma_f32 v[230:231], v[68:69], v[238:239], v[230:231] op_sel_hi:[0,1,1]
	s_waitcnt vmcnt(14)
; DI f2_t cvt8lo(unsigned w) { return __builtin_amdgcn_cvt_pk_f32_fp8(w, false); }
; DI f2_t cvt8hi(unsigned w) { return __builtin_amdgcn_cvt_pk_f32_fp8(w, true); }
; DI void phase11(const Params& p, char* smem, int rep) {
;     ...
;         for (int k = 0; k < 16; ++k) rows[k] = *(const u32x4*)(vb + (size_t)ida[k] * 2048);
; #pragma unroll
;         for (int k = 0; k < 16; ++k) {
;           const f2_t a2 = {aa[k], aa[k]};
; #pragma unroll
;           for (int d = 0; d < 4; ++d) { const unsigned ww = rows[k][d]; o[2 * d] += a2 * cvt8lo(ww); o[2 * d + 1] += a2 * cvt8hi(ww); }
;         }
	v_cvt_pk_f32_fp8_e32 v[232:233], v152
	v_cvt_pk_f32_fp8_sdwa v[234:235], v152 src0_sel:WORD_1
	v_pk_fma_f32 v[216:217], v[68:69], v[232:233], v[216:217] op_sel:[1,0,0]
	v_pk_fma_f32 v[218:219], v[68:69], v[234:235], v[218:219] op_sel:[1,0,0]
	v_cvt_pk_f32_fp8_e32 v[236:237], v153
	v_cvt_pk_f32_fp8_sdwa v[238:239], v153 src0_sel:WORD_1
	v_pk_fma_f32 v[220:221], v[68:69], v[236:237], v[220:221] op_sel:[1,0,0]
	v_pk_fma_f32 v[222:223], v[68:69], v[238:239], v[222:223] op_sel:[1,0,0]
	v_cvt_pk_f32_fp8_e32 v[232:233], v154
	v_cvt_pk_f32_fp8_sdwa v[234:235], v154 src0_sel:WORD_1
	v_pk_fma_f32 v[224:225], v[68:69], v[232:233], v[224:225] op_sel:[1,0,0]
	v_pk_fma_f32 v[226:227], v[68:69], v[234:235], v[226:227] op_sel:[1,0,0]
	v_cvt_pk_f32_fp8_e32 v[236:237], v155
	v_cvt_pk_f32_fp8_sdwa v[238:239], v155 src0_sel:WORD_1
	v_pk_fma_f32 v[228:229], v[68:69], v[236:237], v[228:229] op_sel:[1,0,0]
	v_pk_fma_f32 v[230:231], v[68:69], v[238:239], v[230:231] op_sel:[1,0,0]
	s_waitcnt vmcnt(13)
	v_cvt_pk_f32_fp8_e32 v[232:233], v156
	v_cvt_pk_f32_fp8_sdwa v[234:235], v156 src0_sel:WORD_1
	v_pk_fma_f32 v[216:217], v[70:71], v[232:233], v[216:217] op_sel_hi:[0,1,1]
	v_pk_fma_f32 v[218:219], v[70:71], v[234:235], v[218:219] op_sel_hi:[0,1,1]
	v_cvt_pk_f32_fp8_e32 v[236:237], v157
	v_cvt_pk_f32_fp8_sdwa v[238:239], v157 src0_sel:WORD_1
	v_pk_fma_f32 v[220:221], v[70:71], v[236:237], v[220:221] op_sel_hi:[0,1,1]
	v_pk_fma_f32 v[222:223], v[70:71], v[238:239], v[222:223] op_sel_hi:[0,1,1]
	v_cvt_pk_f32_fp8_e32 v[232:233], v158
	v_cvt_pk_f32_fp8_sdwa v[234:235], v158 src0_sel:WORD_1
	v_pk_fma_f32 v[224:225], v[70:71], v[232:233], v[224:225] op_sel_hi:[0,1,1]
	v_pk_fma_f32 v[226:227], v[70:71], v[234:235], v[226:227] op_sel_hi:[0,1,1]
	v_cvt_pk_f32_fp8_e32 v[236:237], v159
	v_cvt_pk_f32_fp8_sdwa v[238:239], v159 src0_sel:WORD_1
	v_pk_fma_f32 v[228:229], v[70:71], v[236:237], v[228:229] op_sel_hi:[0,1,1]
	v_pk_fma_f32 v[230:231], v[70:71], v[238:239], v[230:231] op_sel_hi:[0,1,1]
	s_waitcnt vmcnt(12)
	v_cvt_pk_f32_fp8_e32 v[232:233], v160
	v_cvt_pk_f32_fp8_sdwa v[234:235], v160 src0_sel:WORD_1
	v_pk_fma_f32 v[216:217], v[70:71], v[232:233], v[216:217] op_sel:[1,0,0]
	v_pk_fma_f32 v[218:219], v[70:71], v[234:235], v[218:219] op_sel:[1,0,0]
	v_cvt_pk_f32_fp8_e32 v[236:237], v161
	v_cvt_pk_f32_fp8_sdwa v[238:239], v161 src0_sel:WORD_1
	v_pk_fma_f32 v[220:221], v[70:71], v[236:237], v[220:221] op_sel:[1,0,0]
	v_pk_fma_f32 v[222:223], v[70:71], v[238:239], v[222:223] op_sel:[1,0,0]
	v_cvt_pk_f32_fp8_e32 v[232:233], v162
	v_cvt_pk_f32_fp8_sdwa v[234:235], v162 src0_sel:WORD_1
	v_pk_fma_f32 v[224:225], v[70:71], v[232:233], v[224:225] op_sel:[1,0,0]
	v_pk_fma_f32 v[226:227], v[70:71], v[234:235], v[226:227] op_sel:[1,0,0]
	v_cvt_pk_f32_fp8_e32 v[236:237], v163
	v_cvt_pk_f32_fp8_sdwa v[238:239], v163 src0_sel:WORD_1
	v_pk_fma_f32 v[228:229], v[70:71], v[236:237], v[228:229] op_sel:[1,0,0]
	v_pk_fma_f32 v[230:231], v[70:71], v[238:239], v[230:231] op_sel:[1,0,0]
	s_waitcnt vmcnt(11)
	v_cvt_pk_f32_fp8_e32 v[232:233], v164
	v_cvt_pk_f32_fp8_sdwa v[234:235], v164 src0_sel:WORD_1
	v_pk_fma_f32 v[216:217], v[72:73], v[232:233], v[216:217] op_sel_hi:[0,1,1]
	v_pk_fma_f32 v[218:219], v[72:73], v[234:235], v[218:219] op_sel_hi:[0,1,1]
	v_cvt_pk_f32_fp8_e32 v[236:237], v165
	v_cvt_pk_f32_fp8_sdwa v[238:239], v165 src0_sel:WORD_1
	v_pk_fma_f32 v[220:221], v[72:73], v[236:237], v[220:221] op_sel_hi:[0,1,1]
	v_pk_fma_f32 v[222:223], v[72:73], v[238:239], v[222:223] op_sel_hi:[0,1,1]
	v_cvt_pk_f32_fp8_e32 v[232:233], v166
	v_cvt_pk_f32_fp8_sdwa v[234:235], v166 src0_sel:WORD_1
	v_pk_fma_f32 v[224:225], v[72:73], v[232:233], v[224:225] op_sel_hi:[0,1,1]
	v_pk_fma_f32 v[226:227], v[72:73], v[234:235], v[226:227] op_sel_hi:[0,1,1]
	v_cvt_pk_f32_fp8_e32 v[236:237], v167
	v_cvt_pk_f32_fp8_sdwa v[238:239], v167 src0_sel:WORD_1
	v_pk_fma_f32 v[228:229], v[72:73], v[236:237], v[228:229] op_sel_hi:[0,1,1]
	v_pk_fma_f32 v[230:231], v[72:73], v[238:239], v[230:231] op_sel_hi:[0,1,1]
	s_waitcnt vmcnt(10)
	v_cvt_pk_f32_fp8_e32 v[232:233], v168
	v_cvt_pk_f32_fp8_sdwa v[234:235], v168 src0_sel:WORD_1
	v_pk_fma_f32 v[216:217], v[72:73], v[232:233], v[216:217] op_sel:[1,0,0]
	v_pk_fma_f32 v[218:219], v[72:73], v[234:235], v[218:219] op_sel:[1,0,0]
	v_cvt_pk_f32_fp8_e32 v[236:237], v169
	v_cvt_pk_f32_fp8_sdwa v[238:239], v169 src0_sel:WORD_1
	v_pk_fma_f32 v[220:221], v[72:73], v[236:237], v[220:221] op_sel:[1,0,0]
	v_pk_fma_f32 v[222:223], v[72:73], v[238:239], v[222:223] op_sel:[1,0,0]
	v_cvt_pk_f32_fp8_e32 v[232:233], v170
	v_cvt_pk_f32_fp8_sdwa v[234:235], v170 src0_sel:WORD_1
	v_pk_fma_f32 v[224:225], v[72:73], v[232:233], v[224:225] op_sel:[1,0,0]
	v_pk_fma_f32 v[226:227], v[72:73], v[234:235], v[226:227] op_sel:[1,0,0]
	v_cvt_pk_f32_fp8_e32 v[236:237], v171
	v_cvt_pk_f32_fp8_sdwa v[238:239], v171 src0_sel:WORD_1
	v_pk_fma_f32 v[228:229], v[72:73], v[236:237], v[228:229] op_sel:[1,0,0]
	v_pk_fma_f32 v[230:231], v[72:73], v[238:239], v[230:231] op_sel:[1,0,0]
	s_waitcnt vmcnt(9)
	v_cvt_pk_f32_fp8_e32 v[232:233], v172
	v_cvt_pk_f32_fp8_sdwa v[234:235], v172 src0_sel:WORD_1
	v_pk_fma_f32 v[216:217], v[74:75], v[232:233], v[216:217] op_sel_hi:[0,1,1]
	v_pk_fma_f32 v[218:219], v[74:75], v[234:235], v[218:219] op_sel_hi:[0,1,1]
	v_cvt_pk_f32_fp8_e32 v[236:237], v173
	v_cvt_pk_f32_fp8_sdwa v[238:239], v173 src0_sel:WORD_1
	v_pk_fma_f32 v[220:221], v[74:75], v[236:237], v[220:221] op_sel_hi:[0,1,1]
	v_pk_fma_f32 v[222:223], v[74:75], v[238:239], v[222:223] op_sel_hi:[0,1,1]
	v_cvt_pk_f32_fp8_e32 v[232:233], v174
	v_cvt_pk_f32_fp8_sdwa v[234:235], v174 src0_sel:WORD_1
	v_pk_fma_f32 v[224:225], v[74:75], v[232:233], v[224:225] op_sel_hi:[0,1,1]
	v_pk_fma_f32 v[226:227], v[74:75], v[234:235], v[226:227] op_sel_hi:[0,1,1]
	v_cvt_pk_f32_fp8_e32 v[236:237], v175
	v_cvt_pk_f32_fp8_sdwa v[238:239], v175 src0_sel:WORD_1
	v_pk_fma_f32 v[228:229], v[74:75], v[236:237], v[228:229] op_sel_hi:[0,1,1]
	v_pk_fma_f32 v[230:231], v[74:75], v[238:239], v[230:231] op_sel_hi:[0,1,1]
	s_waitcnt vmcnt(8)
; DI f2_t cvt8lo(unsigned w) { return __builtin_amdgcn_cvt_pk_f32_fp8(w, false); }
; DI f2_t cvt8hi(unsigned w) { return __builtin_amdgcn_cvt_pk_f32_fp8(w, true); }
; DI void phase11(const Params& p, char* smem, int rep) {
;     ...
;         for (int k = 0; k < 16; ++k) rows[k] = *(const u32x4*)(vb + (size_t)ida[k] * 2048);
; #pragma unroll
;         for (int k = 0; k < 16; ++k) {
;           const f2_t a2 = {aa[k], aa[k]};
; #pragma unroll
;           for (int d = 0; d < 4; ++d) { const unsigned ww = rows[k][d]; o[2 * d] += a2 * cvt8lo(ww); o[2 * d + 1] += a2 * cvt8hi(ww); }
;         }
	v_cvt_pk_f32_fp8_e32 v[232:233], v176
	v_cvt_pk_f32_fp8_sdwa v[234:235], v176 src0_sel:WORD_1
	v_pk_fma_f32 v[216:217], v[74:75], v[232:233], v[216:217] op_sel:[1,0,0]
	v_pk_fma_f32 v[218:219], v[74:75], v[234:235], v[218:219] op_sel:[1,0,0]
	v_cvt_pk_f32_fp8_e32 v[236:237], v177
	v_cvt_pk_f32_fp8_sdwa v[238:239], v177 src0_sel:WORD_1
	v_pk_fma_f32 v[220:221], v[74:75], v[236:237], v[220:221] op_sel:[1,0,0]
	v_pk_fma_f32 v[222:223], v[74:75], v[238:239], v[222:223] op_sel:[1,0,0]
	v_cvt_pk_f32_fp8_e32 v[232:233], v178
	v_cvt_pk_f32_fp8_sdwa v[234:235], v178 src0_sel:WORD_1
	v_pk_fma_f32 v[224:225], v[74:75], v[232:233], v[224:225] op_sel:[1,0,0]
	v_pk_fma_f32 v[226:227], v[74:75], v[234:235], v[226:227] op_sel:[1,0,0]
	v_cvt_pk_f32_fp8_e32 v[236:237], v179
	v_cvt_pk_f32_fp8_sdwa v[238:239], v179 src0_sel:WORD_1
	v_pk_fma_f32 v[228:229], v[74:75], v[236:237], v[228:229] op_sel:[1,0,0]
	v_pk_fma_f32 v[230:231], v[74:75], v[238:239], v[230:231] op_sel:[1,0,0]
	s_waitcnt vmcnt(7)
	v_cvt_pk_f32_fp8_e32 v[232:233], v180
	v_cvt_pk_f32_fp8_sdwa v[234:235], v180 src0_sel:WORD_1
	v_pk_fma_f32 v[216:217], v[76:77], v[232:233], v[216:217] op_sel_hi:[0,1,1]
	v_pk_fma_f32 v[218:219], v[76:77], v[234:235], v[218:219] op_sel_hi:[0,1,1]
	v_cvt_pk_f32_fp8_e32 v[236:237], v181
	v_cvt_pk_f32_fp8_sdwa v[238:239], v181 src0_sel:WORD_1
	v_pk_fma_f32 v[220:221], v[76:77], v[236:237], v[220:221] op_sel_hi:[0,1,1]
	v_pk_fma_f32 v[222:223], v[76:77], v[238:239], v[222:223] op_sel_hi:[0,1,1]
	v_cvt_pk_f32_fp8_e32 v[232:233], v182
	v_cvt_pk_f32_fp8_sdwa v[234:235], v182 src0_sel:WORD_1
	v_pk_fma_f32 v[224:225], v[76:77], v[232:233], v[224:225] op_sel_hi:[0,1,1]
	v_pk_fma_f32 v[226:227], v[76:77], v[234:235], v[226:227] op_sel_hi:[0,1,1]
	v_cvt_pk_f32_fp8_e32 v[236:237], v183
	v_cvt_pk_f32_fp8_sdwa v[238:239], v183 src0_sel:WORD_1
	v_pk_fma_f32 v[228:229], v[76:77], v[236:237], v[228:229] op_sel_hi:[0,1,1]
	v_pk_fma_f32 v[230:231], v[76:77], v[238:239], v[230:231] op_sel_hi:[0,1,1]
	s_waitcnt vmcnt(6)
	v_cvt_pk_f32_fp8_e32 v[232:233], v184
	v_cvt_pk_f32_fp8_sdwa v[234:235], v184 src0_sel:WORD_1
	v_pk_fma_f32 v[216:217], v[76:77], v[232:233], v[216:217] op_sel:[1,0,0]
	v_pk_fma_f32 v[218:219], v[76:77], v[234:235], v[218:219] op_sel:[1,0,0]
	v_cvt_pk_f32_fp8_e32 v[236:237], v185
	v_cvt_pk_f32_fp8_sdwa v[238:239], v185 src0_sel:WORD_1
	v_pk_fma_f32 v[220:221], v[76:77], v[236:237], v[220:221] op_sel:[1,0,0]
	v_pk_fma_f32 v[222:223], v[76:77], v[238:239], v[222:223] op_sel:[1,0,0]
	v_cvt_pk_f32_fp8_e32 v[232:233], v186
	v_cvt_pk_f32_fp8_sdwa v[234:235], v186 src0_sel:WORD_1
	v_pk_fma_f32 v[224:225], v[76:77], v[232:233], v[224:225] op_sel:[1,0,0]
	v_pk_fma_f32 v[226:227], v[76:77], v[234:235], v[226:227] op_sel:[1,0,0]
	v_cvt_pk_f32_fp8_e32 v[236:237], v187
	v_cvt_pk_f32_fp8_sdwa v[238:239], v187 src0_sel:WORD_1
	v_pk_fma_f32 v[228:229], v[76:77], v[236:237], v[228:229] op_sel:[1,0,0]
	v_pk_fma_f32 v[230:231], v[76:77], v[238:239], v[230:231] op_sel:[1,0,0]
	s_waitcnt vmcnt(5)
	v_cvt_pk_f32_fp8_e32 v[232:233], v190
	v_cvt_pk_f32_fp8_sdwa v[234:235], v190 src0_sel:WORD_1
	v_pk_fma_f32 v[216:217], v[78:79], v[232:233], v[216:217] op_sel_hi:[0,1,1]
	v_pk_fma_f32 v[218:219], v[78:79], v[234:235], v[218:219] op_sel_hi:[0,1,1]
	v_cvt_pk_f32_fp8_e32 v[236:237], v191
	v_cvt_pk_f32_fp8_sdwa v[238:239], v191 src0_sel:WORD_1
	v_pk_fma_f32 v[220:221], v[78:79], v[236:237], v[220:221] op_sel_hi:[0,1,1]
	v_pk_fma_f32 v[222:223], v[78:79], v[238:239], v[222:223] op_sel_hi:[0,1,1]
	v_cvt_pk_f32_fp8_e32 v[232:233], v192
	v_cvt_pk_f32_fp8_sdwa v[234:235], v192 src0_sel:WORD_1
	v_pk_fma_f32 v[224:225], v[78:79], v[232:233], v[224:225] op_sel_hi:[0,1,1]
	v_pk_fma_f32 v[226:227], v[78:79], v[234:235], v[226:227] op_sel_hi:[0,1,1]
	v_cvt_pk_f32_fp8_e32 v[236:237], v193
	v_cvt_pk_f32_fp8_sdwa v[238:239], v193 src0_sel:WORD_1
	v_pk_fma_f32 v[228:229], v[78:79], v[236:237], v[228:229] op_sel_hi:[0,1,1]
	v_pk_fma_f32 v[230:231], v[78:79], v[238:239], v[230:231] op_sel_hi:[0,1,1]
	s_waitcnt vmcnt(4)
	v_cvt_pk_f32_fp8_e32 v[232:233], v194
	v_cvt_pk_f32_fp8_sdwa v[234:235], v194 src0_sel:WORD_1
	v_pk_fma_f32 v[216:217], v[78:79], v[232:233], v[216:217] op_sel:[1,0,0]
	v_pk_fma_f32 v[218:219], v[78:79], v[234:235], v[218:219] op_sel:[1,0,0]
	v_cvt_pk_f32_fp8_e32 v[236:237], v195
	v_cvt_pk_f32_fp8_sdwa v[238:239], v195 src0_sel:WORD_1
	v_pk_fma_f32 v[220:221], v[78:79], v[236:237], v[220:221] op_sel:[1,0,0]
	v_pk_fma_f32 v[222:223], v[78:79], v[238:239], v[222:223] op_sel:[1,0,0]
	v_cvt_pk_f32_fp8_e32 v[232:233], v196
	v_cvt_pk_f32_fp8_sdwa v[234:235], v196 src0_sel:WORD_1
	v_pk_fma_f32 v[224:225], v[78:79], v[232:233], v[224:225] op_sel:[1,0,0]
	v_pk_fma_f32 v[226:227], v[78:79], v[234:235], v[226:227] op_sel:[1,0,0]
	v_cvt_pk_f32_fp8_e32 v[236:237], v197
	v_cvt_pk_f32_fp8_sdwa v[238:239], v197 src0_sel:WORD_1
	v_pk_fma_f32 v[228:229], v[78:79], v[236:237], v[228:229] op_sel:[1,0,0]
	v_pk_fma_f32 v[230:231], v[78:79], v[238:239], v[230:231] op_sel:[1,0,0]
	s_waitcnt vmcnt(3)
	v_cvt_pk_f32_fp8_e32 v[232:233], v198
	v_cvt_pk_f32_fp8_sdwa v[234:235], v198 src0_sel:WORD_1
	v_pk_fma_f32 v[216:217], v[80:81], v[232:233], v[216:217] op_sel_hi:[0,1,1]
	v_pk_fma_f32 v[218:219], v[80:81], v[234:235], v[218:219] op_sel_hi:[0,1,1]
	v_cvt_pk_f32_fp8_e32 v[236:237], v199
	v_cvt_pk_f32_fp8_sdwa v[238:239], v199 src0_sel:WORD_1
	v_pk_fma_f32 v[220:221], v[80:81], v[236:237], v[220:221] op_sel_hi:[0,1,1]
	v_pk_fma_f32 v[222:223], v[80:81], v[238:239], v[222:223] op_sel_hi:[0,1,1]
	v_cvt_pk_f32_fp8_e32 v[232:233], v200
	v_cvt_pk_f32_fp8_sdwa v[234:235], v200 src0_sel:WORD_1
	v_pk_fma_f32 v[224:225], v[80:81], v[232:233], v[224:225] op_sel_hi:[0,1,1]
	v_pk_fma_f32 v[226:227], v[80:81], v[234:235], v[226:227] op_sel_hi:[0,1,1]
	v_cvt_pk_f32_fp8_e32 v[236:237], v201
	v_cvt_pk_f32_fp8_sdwa v[238:239], v201 src0_sel:WORD_1
	v_pk_fma_f32 v[228:229], v[80:81], v[236:237], v[228:229] op_sel_hi:[0,1,1]
	v_pk_fma_f32 v[230:231], v[80:81], v[238:239], v[230:231] op_sel_hi:[0,1,1]
	s_waitcnt vmcnt(2)
; DI unsigned pk2(float a, float b) { f2_t v = {a, b}; bf2_t r = __builtin_convertvector(v, bf2_t); return __builtin_bit_cast(unsigned, r); }
; DI f2_t cvt8lo(unsigned w) { return __builtin_amdgcn_cvt_pk_f32_fp8(w, false); }
; DI f2_t cvt8hi(unsigned w) { return __builtin_amdgcn_cvt_pk_f32_fp8(w, true); }
; DI void phase11(const Params& p, char* smem, int rep) {
;     ...
;       const int tok = __builtin_amdgcn_readfirstlane(c * 16 + w * 4 + t);
;       const int i0 = IDS[(size_t)tok * 128 + lane], i1 = IDS[(size_t)tok * 128 + 64 + lane];
;       const float a0 = ACT[(size_t)tok * 128 + lane], a1 = ACT[(size_t)tok * 128 + 64 + lane];
;     ...
;         for (int k = 0; k < 16; ++k) rows[k] = *(const u32x4*)(vb + (size_t)ida[k] * 2048);
; #pragma unroll
;         for (int k = 0; k < 16; ++k) {
;           const f2_t a2 = {aa[k], aa[k]};
; #pragma unroll
;           for (int d = 0; d < 4; ++d) { const unsigned ww = rows[k][d]; o[2 * d] += a2 * cvt8lo(ww); o[2 * d + 1] += a2 * cvt8hi(ww); }
;         }
;       }
;       float ov[16];
; #pragma unroll
;       for (int d = 0; d < 4; ++d) { ov[4 * d] = o[2 * d].x; ov[4 * d + 1] = o[2 * d].y; ov[4 * d + 2] = o[2 * d + 1].x; ov[4 * d + 3] = o[2 * d + 1].y; }
;       float q8[8], q4[4];
; #pragma unroll
;       for (int k = 0; k < 8; ++k) q8[k] = (b5 ? ov[8 + k] : ov[k]) + __shfl_xor(b5 ? ov[k] : ov[8 + k], 32);
; #pragma unroll
;       for (int k = 0; k < 4; ++k) q4[k] = (b4 ? q8[4 + k] : q8[k]) + __shfl_xor(b4 ? q8[k] : q8[4 + k], 16);
;       *(uint2*)(OUTP + (size_t)tok * D_ + s * 256 + l15 * 16 + 8 * b5 + 4 * b4) = make_uint2(pk2(q4[0], q4[1]), pk2(q4[2], q4[3]));
	v_cvt_pk_f32_fp8_e32 v[232:233], v202
	v_cvt_pk_f32_fp8_sdwa v[234:235], v202 src0_sel:WORD_1
	v_pk_fma_f32 v[216:217], v[80:81], v[232:233], v[216:217] op_sel:[1,0,0]
	v_pk_fma_f32 v[218:219], v[80:81], v[234:235], v[218:219] op_sel:[1,0,0]
	v_cvt_pk_f32_fp8_e32 v[236:237], v203
	v_cvt_pk_f32_fp8_sdwa v[238:239], v203 src0_sel:WORD_1
	v_pk_fma_f32 v[220:221], v[80:81], v[236:237], v[220:221] op_sel:[1,0,0]
	v_pk_fma_f32 v[222:223], v[80:81], v[238:239], v[222:223] op_sel:[1,0,0]
	v_cvt_pk_f32_fp8_e32 v[232:233], v204
	v_cvt_pk_f32_fp8_sdwa v[234:235], v204 src0_sel:WORD_1
	v_pk_fma_f32 v[224:225], v[80:81], v[232:233], v[224:225] op_sel:[1,0,0]
	v_pk_fma_f32 v[226:227], v[80:81], v[234:235], v[226:227] op_sel:[1,0,0]
	v_cvt_pk_f32_fp8_e32 v[236:237], v205
	v_cvt_pk_f32_fp8_sdwa v[238:239], v205 src0_sel:WORD_1
	v_pk_fma_f32 v[228:229], v[80:81], v[236:237], v[228:229] op_sel:[1,0,0]
	v_pk_fma_f32 v[230:231], v[80:81], v[238:239], v[230:231] op_sel:[1,0,0]
	s_waitcnt vmcnt(1)
	v_cvt_pk_f32_fp8_e32 v[232:233], v206
	v_cvt_pk_f32_fp8_sdwa v[234:235], v206 src0_sel:WORD_1
	v_pk_fma_f32 v[216:217], v[82:83], v[232:233], v[216:217] op_sel_hi:[0,1,1]
	v_pk_fma_f32 v[218:219], v[82:83], v[234:235], v[218:219] op_sel_hi:[0,1,1]
	v_cvt_pk_f32_fp8_e32 v[236:237], v207
	v_cvt_pk_f32_fp8_sdwa v[238:239], v207 src0_sel:WORD_1
	v_pk_fma_f32 v[220:221], v[82:83], v[236:237], v[220:221] op_sel_hi:[0,1,1]
	v_pk_fma_f32 v[222:223], v[82:83], v[238:239], v[222:223] op_sel_hi:[0,1,1]
	v_cvt_pk_f32_fp8_e32 v[232:233], v208
	v_cvt_pk_f32_fp8_sdwa v[234:235], v208 src0_sel:WORD_1
	v_pk_fma_f32 v[224:225], v[82:83], v[232:233], v[224:225] op_sel_hi:[0,1,1]
	v_pk_fma_f32 v[226:227], v[82:83], v[234:235], v[226:227] op_sel_hi:[0,1,1]
	v_cvt_pk_f32_fp8_e32 v[236:237], v209
	v_cvt_pk_f32_fp8_sdwa v[238:239], v209 src0_sel:WORD_1
	v_pk_fma_f32 v[228:229], v[82:83], v[236:237], v[228:229] op_sel_hi:[0,1,1]
	v_pk_fma_f32 v[230:231], v[82:83], v[238:239], v[230:231] op_sel_hi:[0,1,1]
	s_waitcnt vmcnt(0)
	v_cvt_pk_f32_fp8_e32 v[232:233], v210
	v_cvt_pk_f32_fp8_sdwa v[234:235], v210 src0_sel:WORD_1
	v_pk_fma_f32 v[216:217], v[82:83], v[232:233], v[216:217] op_sel:[1,0,0]
	v_pk_fma_f32 v[218:219], v[82:83], v[234:235], v[218:219] op_sel:[1,0,0]
	v_cvt_pk_f32_fp8_e32 v[236:237], v211
	v_cvt_pk_f32_fp8_sdwa v[238:239], v211 src0_sel:WORD_1
	v_pk_fma_f32 v[220:221], v[82:83], v[236:237], v[220:221] op_sel:[1,0,0]
	v_pk_fma_f32 v[222:223], v[82:83], v[238:239], v[222:223] op_sel:[1,0,0]
	v_cvt_pk_f32_fp8_e32 v[232:233], v212
	v_cvt_pk_f32_fp8_sdwa v[234:235], v212 src0_sel:WORD_1
	v_pk_fma_f32 v[224:225], v[82:83], v[232:233], v[224:225] op_sel:[1,0,0]
	v_pk_fma_f32 v[226:227], v[82:83], v[234:235], v[226:227] op_sel:[1,0,0]
	v_cvt_pk_f32_fp8_e32 v[236:237], v213
	v_cvt_pk_f32_fp8_sdwa v[238:239], v213 src0_sel:WORD_1
	v_pk_fma_f32 v[228:229], v[82:83], v[236:237], v[228:229] op_sel:[1,0,0]
	v_pk_fma_f32 v[230:231], v[82:83], v[238:239], v[230:231] op_sel:[1,0,0]
	ds_read_b128 v[52:55], v6 offset:528
	ds_read_b128 v[56:59], v6 offset:544
	ds_read_b128 v[60:63], v6 offset:560
	ds_read_b128 v[64:67], v6 offset:576
	ds_read_b128 v[68:71], v6 offset:592
	ds_read_b128 v[72:75], v6 offset:608
	ds_read_b128 v[76:79], v6 offset:624
	ds_read_b128 v[80:83], v6 offset:640
	v_add_u32_e32 v214, s46, v4
	s_nop 0
	v_permlane32_swap_b32_e32 v216, v224
	v_permlane32_swap_b32_e32 v217, v225
	v_permlane32_swap_b32_e32 v218, v226
	v_permlane32_swap_b32_e32 v219, v227
	v_permlane32_swap_b32_e32 v220, v228
	v_permlane32_swap_b32_e32 v221, v229
	v_permlane32_swap_b32_e32 v222, v230
	v_permlane32_swap_b32_e32 v223, v231
	v_add_f32_e32 v216, v216, v224
	v_add_f32_e32 v217, v217, v225
	v_add_f32_e32 v218, v218, v226
	v_add_f32_e32 v219, v219, v227
	v_add_f32_e32 v220, v220, v228
	v_add_f32_e32 v221, v221, v229
	v_add_f32_e32 v222, v222, v230
	v_add_f32_e32 v223, v223, v231
	s_nop 1
	v_permlane16_swap_b32_e32 v216, v220
	v_permlane16_swap_b32_e32 v217, v221
	v_permlane16_swap_b32_e32 v218, v222
	v_permlane16_swap_b32_e32 v219, v223
	v_add_f32_e32 v216, v216, v220
	v_add_f32_e32 v217, v217, v221
	v_add_f32_e32 v218, v218, v222
	v_add_f32_e32 v219, v219, v223
	v_cvt_pk_bf16_f32 v232, v216, v217
	v_cvt_pk_bf16_f32 v233, v218, v219
	global_store_dwordx2 v214, v[232:233], s[14:15]
	s_add_i32 s54, s34, 2
	s_lshl_b32 s46, s54, 12
	s_add_i32 s46, s46, s24
	s_add_i32 s55, s34, 3
	s_lshl_b32 s47, s55, 9
	s_add_u32 s42, s6, s47
	s_addc_u32 s43, s7, 0
	s_add_u32 s44, s8, s47
	s_addc_u32 s45, s9, 0
	global_load_dword v10, v3, s[42:43]
	global_load_dword v11, v3, s[42:43] offset:256
	global_load_dword v12, v3, s[44:45]
	global_load_dword v13, v3, s[44:45] offset:256
	s_waitcnt lgkmcnt(0)
; DI f2_t cvt8lo(unsigned w) { return __builtin_amdgcn_cvt_pk_f32_fp8(w, false); }
; DI f2_t cvt8hi(unsigned w) { return __builtin_amdgcn_cvt_pk_f32_fp8(w, true); }
; DI void phase11(const Params& p, char* smem, int rep) {
;     ...
;         u32x4 rows[16];
; #pragma unroll
;         for (int k = 0; k < 16; ++k) rows[k] = *(const u32x4*)(vb + (size_t)ida[k] * 2048);
; #pragma unroll
;         for (int k = 0; k < 16; ++k) {
;           const f2_t a2 = {aa[k], aa[k]};
; #pragma unroll
;           for (int d = 0; d < 4; ++d) { const unsigned ww = rows[k][d]; o[2 * d] += a2 * cvt8lo(ww); o[2 * d + 1] += a2 * cvt8hi(ww); }
;         }
	v_lshl_add_u32 v20, v20, 11, v2
	v_lshl_add_u32 v21, v21, 11, v2
	v_lshl_add_u32 v22, v22, 11, v2
	v_lshl_add_u32 v23, v23, 11, v2
	v_lshl_add_u32 v24, v24, 11, v2
	v_lshl_add_u32 v25, v25, 11, v2
	v_lshl_add_u32 v26, v26, 11, v2
	v_lshl_add_u32 v27, v27, 11, v2
	v_lshl_add_u32 v28, v28, 11, v2
	v_lshl_add_u32 v29, v29, 11, v2
	v_lshl_add_u32 v30, v30, 11, v2
	v_lshl_add_u32 v31, v31, 11, v2
	v_lshl_add_u32 v32, v32, 11, v2
	v_lshl_add_u32 v33, v33, 11, v2
	v_lshl_add_u32 v34, v34, 11, v2
	v_lshl_add_u32 v35, v35, 11, v2
	v_lshl_add_u32 v36, v36, 11, v2
	v_lshl_add_u32 v37, v37, 11, v2
	v_lshl_add_u32 v38, v38, 11, v2
	v_lshl_add_u32 v39, v39, 11, v2
	v_lshl_add_u32 v40, v40, 11, v2
	v_lshl_add_u32 v41, v41, 11, v2
	v_lshl_add_u32 v42, v42, 11, v2
	v_lshl_add_u32 v43, v43, 11, v2
	v_lshl_add_u32 v44, v44, 11, v2
	v_lshl_add_u32 v45, v45, 11, v2
	v_lshl_add_u32 v46, v46, 11, v2
	v_lshl_add_u32 v47, v47, 11, v2
	v_lshl_add_u32 v48, v48, 11, v2
	v_lshl_add_u32 v49, v49, 11, v2
	v_lshl_add_u32 v50, v50, 11, v2
	v_lshl_add_u32 v51, v51, 11, v2
	global_load_dwordx4 v[84:87], v20, s[20:21]
	global_load_dwordx4 v[88:91], v21, s[20:21]
	global_load_dwordx4 v[92:95], v22, s[20:21]
	global_load_dwordx4 v[96:99], v23, s[20:21]
	global_load_dwordx4 v[100:103], v24, s[20:21]
	global_load_dwordx4 v[104:107], v25, s[20:21]
	global_load_dwordx4 v[108:111], v26, s[20:21]
	global_load_dwordx4 v[112:115], v27, s[20:21]
	global_load_dwordx4 v[116:119], v28, s[20:21]
	global_load_dwordx4 v[120:123], v29, s[20:21]
	global_load_dwordx4 v[124:127], v30, s[20:21]
	global_load_dwordx4 v[128:131], v31, s[20:21]
	global_load_dwordx4 v[132:135], v32, s[20:21]
	global_load_dwordx4 v[136:139], v33, s[20:21]
	global_load_dwordx4 v[140:143], v34, s[20:21]
	global_load_dwordx4 v[144:147], v35, s[20:21]
	global_load_dwordx4 v[148:151], v36, s[20:21]
	global_load_dwordx4 v[152:155], v37, s[20:21]
	global_load_dwordx4 v[156:159], v38, s[20:21]
	global_load_dwordx4 v[160:163], v39, s[20:21]
	global_load_dwordx4 v[164:167], v40, s[20:21]
	global_load_dwordx4 v[168:171], v41, s[20:21]
	global_load_dwordx4 v[172:175], v42, s[20:21]
	global_load_dwordx4 v[176:179], v43, s[20:21]
	global_load_dwordx4 v[180:183], v44, s[20:21]
	global_load_dwordx4 v[184:187], v45, s[20:21]
	global_load_dwordx4 v[190:193], v46, s[20:21]
	global_load_dwordx4 v[194:197], v47, s[20:21]
	global_load_dwordx4 v[198:201], v48, s[20:21]
	global_load_dwordx4 v[202:205], v49, s[20:21]
	global_load_dwordx4 v[206:209], v50, s[20:21]
	global_load_dwordx4 v[210:213], v51, s[20:21]
	s_waitcnt vmcnt(31)
	v_cvt_pk_f32_fp8_e32 v[232:233], v84
	v_cvt_pk_f32_fp8_sdwa v[234:235], v84 src0_sel:WORD_1
	v_pk_fma_f32 v[216:217], v[52:53], v[232:233], 0 op_sel_hi:[0,1,0]
	v_pk_fma_f32 v[218:219], v[52:53], v[234:235], 0 op_sel_hi:[0,1,0]
	v_cvt_pk_f32_fp8_e32 v[236:237], v85
	v_cvt_pk_f32_fp8_sdwa v[238:239], v85 src0_sel:WORD_1
	v_pk_fma_f32 v[220:221], v[52:53], v[236:237], 0 op_sel_hi:[0,1,0]
	v_pk_fma_f32 v[222:223], v[52:53], v[238:239], 0 op_sel_hi:[0,1,0]
	v_cvt_pk_f32_fp8_e32 v[232:233], v86
	v_cvt_pk_f32_fp8_sdwa v[234:235], v86 src0_sel:WORD_1
	v_pk_fma_f32 v[224:225], v[52:53], v[232:233], 0 op_sel_hi:[0,1,0]
	v_pk_fma_f32 v[226:227], v[52:53], v[234:235], 0 op_sel_hi:[0,1,0]
	v_cvt_pk_f32_fp8_e32 v[236:237], v87
	v_cvt_pk_f32_fp8_sdwa v[238:239], v87 src0_sel:WORD_1
	v_pk_fma_f32 v[228:229], v[52:53], v[236:237], 0 op_sel_hi:[0,1,0]
	v_pk_fma_f32 v[230:231], v[52:53], v[238:239], 0 op_sel_hi:[0,1,0]
	s_waitcnt vmcnt(30)
	v_cvt_pk_f32_fp8_e32 v[232:233], v88
	v_cvt_pk_f32_fp8_sdwa v[234:235], v88 src0_sel:WORD_1
	v_pk_fma_f32 v[216:217], v[52:53], v[232:233], v[216:217] op_sel:[1,0,0]
	v_pk_fma_f32 v[218:219], v[52:53], v[234:235], v[218:219] op_sel:[1,0,0]
	v_cvt_pk_f32_fp8_e32 v[236:237], v89
	v_cvt_pk_f32_fp8_sdwa v[238:239], v89 src0_sel:WORD_1
	v_pk_fma_f32 v[220:221], v[52:53], v[236:237], v[220:221] op_sel:[1,0,0]
	v_pk_fma_f32 v[222:223], v[52:53], v[238:239], v[222:223] op_sel:[1,0,0]
	v_cvt_pk_f32_fp8_e32 v[232:233], v90
	v_cvt_pk_f32_fp8_sdwa v[234:235], v90 src0_sel:WORD_1
	v_pk_fma_f32 v[224:225], v[52:53], v[232:233], v[224:225] op_sel:[1,0,0]
	v_pk_fma_f32 v[226:227], v[52:53], v[234:235], v[226:227] op_sel:[1,0,0]
	v_cvt_pk_f32_fp8_e32 v[236:237], v91
	v_cvt_pk_f32_fp8_sdwa v[238:239], v91 src0_sel:WORD_1
	v_pk_fma_f32 v[228:229], v[52:53], v[236:237], v[228:229] op_sel:[1,0,0]
	v_pk_fma_f32 v[230:231], v[52:53], v[238:239], v[230:231] op_sel:[1,0,0]
	s_waitcnt vmcnt(29)
	v_cvt_pk_f32_fp8_e32 v[232:233], v92
	v_cvt_pk_f32_fp8_sdwa v[234:235], v92 src0_sel:WORD_1
	v_pk_fma_f32 v[216:217], v[54:55], v[232:233], v[216:217] op_sel_hi:[0,1,1]
	v_pk_fma_f32 v[218:219], v[54:55], v[234:235], v[218:219] op_sel_hi:[0,1,1]
	v_cvt_pk_f32_fp8_e32 v[236:237], v93
	v_cvt_pk_f32_fp8_sdwa v[238:239], v93 src0_sel:WORD_1
	v_pk_fma_f32 v[220:221], v[54:55], v[236:237], v[220:221] op_sel_hi:[0,1,1]
	v_pk_fma_f32 v[222:223], v[54:55], v[238:239], v[222:223] op_sel_hi:[0,1,1]
	v_cvt_pk_f32_fp8_e32 v[232:233], v94
	v_cvt_pk_f32_fp8_sdwa v[234:235], v94 src0_sel:WORD_1
	v_pk_fma_f32 v[224:225], v[54:55], v[232:233], v[224:225] op_sel_hi:[0,1,1]
	v_pk_fma_f32 v[226:227], v[54:55], v[234:235], v[226:227] op_sel_hi:[0,1,1]
	v_cvt_pk_f32_fp8_e32 v[236:237], v95
	v_cvt_pk_f32_fp8_sdwa v[238:239], v95 src0_sel:WORD_1
	v_pk_fma_f32 v[228:229], v[54:55], v[236:237], v[228:229] op_sel_hi:[0,1,1]
	v_pk_fma_f32 v[230:231], v[54:55], v[238:239], v[230:231] op_sel_hi:[0,1,1]
	s_waitcnt vmcnt(28)
; DI f2_t cvt8lo(unsigned w) { return __builtin_amdgcn_cvt_pk_f32_fp8(w, false); }
; DI f2_t cvt8hi(unsigned w) { return __builtin_amdgcn_cvt_pk_f32_fp8(w, true); }
; DI void phase11(const Params& p, char* smem, int rep) {
;     ...
;         for (int k = 0; k < 16; ++k) rows[k] = *(const u32x4*)(vb + (size_t)ida[k] * 2048);
; #pragma unroll
;         for (int k = 0; k < 16; ++k) {
;           const f2_t a2 = {aa[k], aa[k]};
; #pragma unroll
;           for (int d = 0; d < 4; ++d) { const unsigned ww = rows[k][d]; o[2 * d] += a2 * cvt8lo(ww); o[2 * d + 1] += a2 * cvt8hi(ww); }
;         }
	v_cvt_pk_f32_fp8_e32 v[232:233], v96
	v_cvt_pk_f32_fp8_sdwa v[234:235], v96 src0_sel:WORD_1
	v_pk_fma_f32 v[216:217], v[54:55], v[232:233], v[216:217] op_sel:[1,0,0]
	v_pk_fma_f32 v[218:219], v[54:55], v[234:235], v[218:219] op_sel:[1,0,0]
	v_cvt_pk_f32_fp8_e32 v[236:237], v97
	v_cvt_pk_f32_fp8_sdwa v[238:239], v97 src0_sel:WORD_1
	v_pk_fma_f32 v[220:221], v[54:55], v[236:237], v[220:221] op_sel:[1,0,0]
	v_pk_fma_f32 v[222:223], v[54:55], v[238:239], v[222:223] op_sel:[1,0,0]
	v_cvt_pk_f32_fp8_e32 v[232:233], v98
	v_cvt_pk_f32_fp8_sdwa v[234:235], v98 src0_sel:WORD_1
	v_pk_fma_f32 v[224:225], v[54:55], v[232:233], v[224:225] op_sel:[1,0,0]
	v_pk_fma_f32 v[226:227], v[54:55], v[234:235], v[226:227] op_sel:[1,0,0]
	v_cvt_pk_f32_fp8_e32 v[236:237], v99
	v_cvt_pk_f32_fp8_sdwa v[238:239], v99 src0_sel:WORD_1
	v_pk_fma_f32 v[228:229], v[54:55], v[236:237], v[228:229] op_sel:[1,0,0]
	v_pk_fma_f32 v[230:231], v[54:55], v[238:239], v[230:231] op_sel:[1,0,0]
	s_waitcnt vmcnt(27)
	v_cvt_pk_f32_fp8_e32 v[232:233], v100
	v_cvt_pk_f32_fp8_sdwa v[234:235], v100 src0_sel:WORD_1
	v_pk_fma_f32 v[216:217], v[56:57], v[232:233], v[216:217] op_sel_hi:[0,1,1]
	v_pk_fma_f32 v[218:219], v[56:57], v[234:235], v[218:219] op_sel_hi:[0,1,1]
	v_cvt_pk_f32_fp8_e32 v[236:237], v101
	v_cvt_pk_f32_fp8_sdwa v[238:239], v101 src0_sel:WORD_1
	v_pk_fma_f32 v[220:221], v[56:57], v[236:237], v[220:221] op_sel_hi:[0,1,1]
	v_pk_fma_f32 v[222:223], v[56:57], v[238:239], v[222:223] op_sel_hi:[0,1,1]
	v_cvt_pk_f32_fp8_e32 v[232:233], v102
	v_cvt_pk_f32_fp8_sdwa v[234:235], v102 src0_sel:WORD_1
	v_pk_fma_f32 v[224:225], v[56:57], v[232:233], v[224:225] op_sel_hi:[0,1,1]
	v_pk_fma_f32 v[226:227], v[56:57], v[234:235], v[226:227] op_sel_hi:[0,1,1]
	v_cvt_pk_f32_fp8_e32 v[236:237], v103
	v_cvt_pk_f32_fp8_sdwa v[238:239], v103 src0_sel:WORD_1
	v_pk_fma_f32 v[228:229], v[56:57], v[236:237], v[228:229] op_sel_hi:[0,1,1]
	v_pk_fma_f32 v[230:231], v[56:57], v[238:239], v[230:231] op_sel_hi:[0,1,1]
	s_waitcnt vmcnt(26)
	v_cvt_pk_f32_fp8_e32 v[232:233], v104
	v_cvt_pk_f32_fp8_sdwa v[234:235], v104 src0_sel:WORD_1
	v_pk_fma_f32 v[216:217], v[56:57], v[232:233], v[216:217] op_sel:[1,0,0]
	v_pk_fma_f32 v[218:219], v[56:57], v[234:235], v[218:219] op_sel:[1,0,0]
	v_cvt_pk_f32_fp8_e32 v[236:237], v105
	v_cvt_pk_f32_fp8_sdwa v[238:239], v105 src0_sel:WORD_1
	v_pk_fma_f32 v[220:221], v[56:57], v[236:237], v[220:221] op_sel:[1,0,0]
	v_pk_fma_f32 v[222:223], v[56:57], v[238:239], v[222:223] op_sel:[1,0,0]
	v_cvt_pk_f32_fp8_e32 v[232:233], v106
	v_cvt_pk_f32_fp8_sdwa v[234:235], v106 src0_sel:WORD_1
	v_pk_fma_f32 v[224:225], v[56:57], v[232:233], v[224:225] op_sel:[1,0,0]
	v_pk_fma_f32 v[226:227], v[56:57], v[234:235], v[226:227] op_sel:[1,0,0]
	v_cvt_pk_f32_fp8_e32 v[236:237], v107
	v_cvt_pk_f32_fp8_sdwa v[238:239], v107 src0_sel:WORD_1
	v_pk_fma_f32 v[228:229], v[56:57], v[236:237], v[228:229] op_sel:[1,0,0]
	v_pk_fma_f32 v[230:231], v[56:57], v[238:239], v[230:231] op_sel:[1,0,0]
	s_waitcnt vmcnt(25)
	v_cvt_pk_f32_fp8_e32 v[232:233], v108
	v_cvt_pk_f32_fp8_sdwa v[234:235], v108 src0_sel:WORD_1
	v_pk_fma_f32 v[216:217], v[58:59], v[232:233], v[216:217] op_sel_hi:[0,1,1]
	v_pk_fma_f32 v[218:219], v[58:59], v[234:235], v[218:219] op_sel_hi:[0,1,1]
	v_cvt_pk_f32_fp8_e32 v[236:237], v109
	v_cvt_pk_f32_fp8_sdwa v[238:239], v109 src0_sel:WORD_1
	v_pk_fma_f32 v[220:221], v[58:59], v[236:237], v[220:221] op_sel_hi:[0,1,1]
	v_pk_fma_f32 v[222:223], v[58:59], v[238:239], v[222:223] op_sel_hi:[0,1,1]
	v_cvt_pk_f32_fp8_e32 v[232:233], v110
	v_cvt_pk_f32_fp8_sdwa v[234:235], v110 src0_sel:WORD_1
	v_pk_fma_f32 v[224:225], v[58:59], v[232:233], v[224:225] op_sel_hi:[0,1,1]
	v_pk_fma_f32 v[226:227], v[58:59], v[234:235], v[226:227] op_sel_hi:[0,1,1]
	v_cvt_pk_f32_fp8_e32 v[236:237], v111
	v_cvt_pk_f32_fp8_sdwa v[238:239], v111 src0_sel:WORD_1
	v_pk_fma_f32 v[228:229], v[58:59], v[236:237], v[228:229] op_sel_hi:[0,1,1]
	v_pk_fma_f32 v[230:231], v[58:59], v[238:239], v[230:231] op_sel_hi:[0,1,1]
	s_waitcnt vmcnt(24)
	v_cvt_pk_f32_fp8_e32 v[232:233], v112
	v_cvt_pk_f32_fp8_sdwa v[234:235], v112 src0_sel:WORD_1
	v_pk_fma_f32 v[216:217], v[58:59], v[232:233], v[216:217] op_sel:[1,0,0]
	v_pk_fma_f32 v[218:219], v[58:59], v[234:235], v[218:219] op_sel:[1,0,0]
	v_cvt_pk_f32_fp8_e32 v[236:237], v113
	v_cvt_pk_f32_fp8_sdwa v[238:239], v113 src0_sel:WORD_1
	v_pk_fma_f32 v[220:221], v[58:59], v[236:237], v[220:221] op_sel:[1,0,0]
	v_pk_fma_f32 v[222:223], v[58:59], v[238:239], v[222:223] op_sel:[1,0,0]
	v_cvt_pk_f32_fp8_e32 v[232:233], v114
	v_cvt_pk_f32_fp8_sdwa v[234:235], v114 src0_sel:WORD_1
	v_pk_fma_f32 v[224:225], v[58:59], v[232:233], v[224:225] op_sel:[1,0,0]
	v_pk_fma_f32 v[226:227], v[58:59], v[234:235], v[226:227] op_sel:[1,0,0]
	v_cvt_pk_f32_fp8_e32 v[236:237], v115
	v_cvt_pk_f32_fp8_sdwa v[238:239], v115 src0_sel:WORD_1
	v_pk_fma_f32 v[228:229], v[58:59], v[236:237], v[228:229] op_sel:[1,0,0]
	v_pk_fma_f32 v[230:231], v[58:59], v[238:239], v[230:231] op_sel:[1,0,0]
	s_waitcnt vmcnt(23)
	v_cvt_pk_f32_fp8_e32 v[232:233], v116
	v_cvt_pk_f32_fp8_sdwa v[234:235], v116 src0_sel:WORD_1
	v_pk_fma_f32 v[216:217], v[60:61], v[232:233], v[216:217] op_sel_hi:[0,1,1]
	v_pk_fma_f32 v[218:219], v[60:61], v[234:235], v[218:219] op_sel_hi:[0,1,1]
	v_cvt_pk_f32_fp8_e32 v[236:237], v117
	v_cvt_pk_f32_fp8_sdwa v[238:239], v117 src0_sel:WORD_1
	v_pk_fma_f32 v[220:221], v[60:61], v[236:237], v[220:221] op_sel_hi:[0,1,1]
	v_pk_fma_f32 v[222:223], v[60:61], v[238:239], v[222:223] op_sel_hi:[0,1,1]
	v_cvt_pk_f32_fp8_e32 v[232:233], v118
	v_cvt_pk_f32_fp8_sdwa v[234:235], v118 src0_sel:WORD_1
	v_pk_fma_f32 v[224:225], v[60:61], v[232:233], v[224:225] op_sel_hi:[0,1,1]
	v_pk_fma_f32 v[226:227], v[60:61], v[234:235], v[226:227] op_sel_hi:[0,1,1]
	v_cvt_pk_f32_fp8_e32 v[236:237], v119
	v_cvt_pk_f32_fp8_sdwa v[238:239], v119 src0_sel:WORD_1
	v_pk_fma_f32 v[228:229], v[60:61], v[236:237], v[228:229] op_sel_hi:[0,1,1]
	v_pk_fma_f32 v[230:231], v[60:61], v[238:239], v[230:231] op_sel_hi:[0,1,1]
	s_waitcnt vmcnt(22)
; DI f2_t cvt8lo(unsigned w) { return __builtin_amdgcn_cvt_pk_f32_fp8(w, false); }
; DI f2_t cvt8hi(unsigned w) { return __builtin_amdgcn_cvt_pk_f32_fp8(w, true); }
; DI void phase11(const Params& p, char* smem, int rep) {
;     ...
;         for (int k = 0; k < 16; ++k) rows[k] = *(const u32x4*)(vb + (size_t)ida[k] * 2048);
; #pragma unroll
;         for (int k = 0; k < 16; ++k) {
;           const f2_t a2 = {aa[k], aa[k]};
; #pragma unroll
;           for (int d = 0; d < 4; ++d) { const unsigned ww = rows[k][d]; o[2 * d] += a2 * cvt8lo(ww); o[2 * d + 1] += a2 * cvt8hi(ww); }
;         }
	v_cvt_pk_f32_fp8_e32 v[232:233], v120
	v_cvt_pk_f32_fp8_sdwa v[234:235], v120 src0_sel:WORD_1
	v_pk_fma_f32 v[216:217], v[60:61], v[232:233], v[216:217] op_sel:[1,0,0]
	v_pk_fma_f32 v[218:219], v[60:61], v[234:235], v[218:219] op_sel:[1,0,0]
	v_cvt_pk_f32_fp8_e32 v[236:237], v121
	v_cvt_pk_f32_fp8_sdwa v[238:239], v121 src0_sel:WORD_1
	v_pk_fma_f32 v[220:221], v[60:61], v[236:237], v[220:221] op_sel:[1,0,0]
	v_pk_fma_f32 v[222:223], v[60:61], v[238:239], v[222:223] op_sel:[1,0,0]
	v_cvt_pk_f32_fp8_e32 v[232:233], v122
	v_cvt_pk_f32_fp8_sdwa v[234:235], v122 src0_sel:WORD_1
	v_pk_fma_f32 v[224:225], v[60:61], v[232:233], v[224:225] op_sel:[1,0,0]
	v_pk_fma_f32 v[226:227], v[60:61], v[234:235], v[226:227] op_sel:[1,0,0]
	v_cvt_pk_f32_fp8_e32 v[236:237], v123
	v_cvt_pk_f32_fp8_sdwa v[238:239], v123 src0_sel:WORD_1
	v_pk_fma_f32 v[228:229], v[60:61], v[236:237], v[228:229] op_sel:[1,0,0]
	v_pk_fma_f32 v[230:231], v[60:61], v[238:239], v[230:231] op_sel:[1,0,0]
	s_waitcnt vmcnt(21)
	v_cvt_pk_f32_fp8_e32 v[232:233], v124
	v_cvt_pk_f32_fp8_sdwa v[234:235], v124 src0_sel:WORD_1
	v_pk_fma_f32 v[216:217], v[62:63], v[232:233], v[216:217] op_sel_hi:[0,1,1]
	v_pk_fma_f32 v[218:219], v[62:63], v[234:235], v[218:219] op_sel_hi:[0,1,1]
	v_cvt_pk_f32_fp8_e32 v[236:237], v125
	v_cvt_pk_f32_fp8_sdwa v[238:239], v125 src0_sel:WORD_1
	v_pk_fma_f32 v[220:221], v[62:63], v[236:237], v[220:221] op_sel_hi:[0,1,1]
	v_pk_fma_f32 v[222:223], v[62:63], v[238:239], v[222:223] op_sel_hi:[0,1,1]
	v_cvt_pk_f32_fp8_e32 v[232:233], v126
	v_cvt_pk_f32_fp8_sdwa v[234:235], v126 src0_sel:WORD_1
	v_pk_fma_f32 v[224:225], v[62:63], v[232:233], v[224:225] op_sel_hi:[0,1,1]
	v_pk_fma_f32 v[226:227], v[62:63], v[234:235], v[226:227] op_sel_hi:[0,1,1]
	v_cvt_pk_f32_fp8_e32 v[236:237], v127
	v_cvt_pk_f32_fp8_sdwa v[238:239], v127 src0_sel:WORD_1
	v_pk_fma_f32 v[228:229], v[62:63], v[236:237], v[228:229] op_sel_hi:[0,1,1]
	v_pk_fma_f32 v[230:231], v[62:63], v[238:239], v[230:231] op_sel_hi:[0,1,1]
	s_waitcnt vmcnt(20)
	v_cvt_pk_f32_fp8_e32 v[232:233], v128
	v_cvt_pk_f32_fp8_sdwa v[234:235], v128 src0_sel:WORD_1
	v_pk_fma_f32 v[216:217], v[62:63], v[232:233], v[216:217] op_sel:[1,0,0]
	v_pk_fma_f32 v[218:219], v[62:63], v[234:235], v[218:219] op_sel:[1,0,0]
	v_cvt_pk_f32_fp8_e32 v[236:237], v129
	v_cvt_pk_f32_fp8_sdwa v[238:239], v129 src0_sel:WORD_1
	v_pk_fma_f32 v[220:221], v[62:63], v[236:237], v[220:221] op_sel:[1,0,0]
	v_pk_fma_f32 v[222:223], v[62:63], v[238:239], v[222:223] op_sel:[1,0,0]
	v_cvt_pk_f32_fp8_e32 v[232:233], v130
	v_cvt_pk_f32_fp8_sdwa v[234:235], v130 src0_sel:WORD_1
	v_pk_fma_f32 v[224:225], v[62:63], v[232:233], v[224:225] op_sel:[1,0,0]
	v_pk_fma_f32 v[226:227], v[62:63], v[234:235], v[226:227] op_sel:[1,0,0]
	v_cvt_pk_f32_fp8_e32 v[236:237], v131
	v_cvt_pk_f32_fp8_sdwa v[238:239], v131 src0_sel:WORD_1
	v_pk_fma_f32 v[228:229], v[62:63], v[236:237], v[228:229] op_sel:[1,0,0]
	v_pk_fma_f32 v[230:231], v[62:63], v[238:239], v[230:231] op_sel:[1,0,0]
	s_waitcnt vmcnt(19)
	v_cvt_pk_f32_fp8_e32 v[232:233], v132
	v_cvt_pk_f32_fp8_sdwa v[234:235], v132 src0_sel:WORD_1
	v_pk_fma_f32 v[216:217], v[64:65], v[232:233], v[216:217] op_sel_hi:[0,1,1]
	v_pk_fma_f32 v[218:219], v[64:65], v[234:235], v[218:219] op_sel_hi:[0,1,1]
	v_cvt_pk_f32_fp8_e32 v[236:237], v133
	v_cvt_pk_f32_fp8_sdwa v[238:239], v133 src0_sel:WORD_1
	v_pk_fma_f32 v[220:221], v[64:65], v[236:237], v[220:221] op_sel_hi:[0,1,1]
	v_pk_fma_f32 v[222:223], v[64:65], v[238:239], v[222:223] op_sel_hi:[0,1,1]
	v_cvt_pk_f32_fp8_e32 v[232:233], v134
	v_cvt_pk_f32_fp8_sdwa v[234:235], v134 src0_sel:WORD_1
	v_pk_fma_f32 v[224:225], v[64:65], v[232:233], v[224:225] op_sel_hi:[0,1,1]
	v_pk_fma_f32 v[226:227], v[64:65], v[234:235], v[226:227] op_sel_hi:[0,1,1]
	v_cvt_pk_f32_fp8_e32 v[236:237], v135
	v_cvt_pk_f32_fp8_sdwa v[238:239], v135 src0_sel:WORD_1
	v_pk_fma_f32 v[228:229], v[64:65], v[236:237], v[228:229] op_sel_hi:[0,1,1]
	v_pk_fma_f32 v[230:231], v[64:65], v[238:239], v[230:231] op_sel_hi:[0,1,1]
	s_waitcnt vmcnt(18)
	v_cvt_pk_f32_fp8_e32 v[232:233], v136
	v_cvt_pk_f32_fp8_sdwa v[234:235], v136 src0_sel:WORD_1
	v_pk_fma_f32 v[216:217], v[64:65], v[232:233], v[216:217] op_sel:[1,0,0]
	v_pk_fma_f32 v[218:219], v[64:65], v[234:235], v[218:219] op_sel:[1,0,0]
	v_cvt_pk_f32_fp8_e32 v[236:237], v137
	v_cvt_pk_f32_fp8_sdwa v[238:239], v137 src0_sel:WORD_1
	v_pk_fma_f32 v[220:221], v[64:65], v[236:237], v[220:221] op_sel:[1,0,0]
	v_pk_fma_f32 v[222:223], v[64:65], v[238:239], v[222:223] op_sel:[1,0,0]
	v_cvt_pk_f32_fp8_e32 v[232:233], v138
	v_cvt_pk_f32_fp8_sdwa v[234:235], v138 src0_sel:WORD_1
	v_pk_fma_f32 v[224:225], v[64:65], v[232:233], v[224:225] op_sel:[1,0,0]
	v_pk_fma_f32 v[226:227], v[64:65], v[234:235], v[226:227] op_sel:[1,0,0]
	v_cvt_pk_f32_fp8_e32 v[236:237], v139
	v_cvt_pk_f32_fp8_sdwa v[238:239], v139 src0_sel:WORD_1
	v_pk_fma_f32 v[228:229], v[64:65], v[236:237], v[228:229] op_sel:[1,0,0]
	v_pk_fma_f32 v[230:231], v[64:65], v[238:239], v[230:231] op_sel:[1,0,0]
	s_waitcnt vmcnt(17)
	v_cvt_pk_f32_fp8_e32 v[232:233], v140
	v_cvt_pk_f32_fp8_sdwa v[234:235], v140 src0_sel:WORD_1
	v_pk_fma_f32 v[216:217], v[66:67], v[232:233], v[216:217] op_sel_hi:[0,1,1]
	v_pk_fma_f32 v[218:219], v[66:67], v[234:235], v[218:219] op_sel_hi:[0,1,1]
	v_cvt_pk_f32_fp8_e32 v[236:237], v141
	v_cvt_pk_f32_fp8_sdwa v[238:239], v141 src0_sel:WORD_1
	v_pk_fma_f32 v[220:221], v[66:67], v[236:237], v[220:221] op_sel_hi:[0,1,1]
	v_pk_fma_f32 v[222:223], v[66:67], v[238:239], v[222:223] op_sel_hi:[0,1,1]
	v_cvt_pk_f32_fp8_e32 v[232:233], v142
	v_cvt_pk_f32_fp8_sdwa v[234:235], v142 src0_sel:WORD_1
	v_pk_fma_f32 v[224:225], v[66:67], v[232:233], v[224:225] op_sel_hi:[0,1,1]
	v_pk_fma_f32 v[226:227], v[66:67], v[234:235], v[226:227] op_sel_hi:[0,1,1]
	v_cvt_pk_f32_fp8_e32 v[236:237], v143
	v_cvt_pk_f32_fp8_sdwa v[238:239], v143 src0_sel:WORD_1
	v_pk_fma_f32 v[228:229], v[66:67], v[236:237], v[228:229] op_sel_hi:[0,1,1]
	v_pk_fma_f32 v[230:231], v[66:67], v[238:239], v[230:231] op_sel_hi:[0,1,1]
	s_waitcnt vmcnt(16)
; DI f2_t cvt8lo(unsigned w) { return __builtin_amdgcn_cvt_pk_f32_fp8(w, false); }
; DI f2_t cvt8hi(unsigned w) { return __builtin_amdgcn_cvt_pk_f32_fp8(w, true); }
; DI void wave_lds_sync() { asm volatile("s_waitcnt lgkmcnt(0)" ::: "memory"); __builtin_amdgcn_wave_barrier(); }
; DI void phase11(const Params& p, char* smem, int rep) {
;     ...
;       wave_lds_sync();
;       lw[(lane & 3) * 32 + (lane >> 2)] = i0; lw[(lane & 3) * 32 + 16 + (lane >> 2)] = i1;
;       lf[(lane & 3) * 32 + (lane >> 2)] = a0; lf[(lane & 3) * 32 + 16 + (lane >> 2)] = a1;
;       wave_lds_sync();
;     ...
;         for (int k = 0; k < 16; ++k) rows[k] = *(const u32x4*)(vb + (size_t)ida[k] * 2048);
; #pragma unroll
;         for (int k = 0; k < 16; ++k) {
;           const f2_t a2 = {aa[k], aa[k]};
; #pragma unroll
;           for (int d = 0; d < 4; ++d) { const unsigned ww = rows[k][d]; o[2 * d] += a2 * cvt8lo(ww); o[2 * d + 1] += a2 * cvt8hi(ww); }
;         }
	v_cvt_pk_f32_fp8_e32 v[232:233], v144
	v_cvt_pk_f32_fp8_sdwa v[234:235], v144 src0_sel:WORD_1
	v_pk_fma_f32 v[216:217], v[66:67], v[232:233], v[216:217] op_sel:[1,0,0]
	v_pk_fma_f32 v[218:219], v[66:67], v[234:235], v[218:219] op_sel:[1,0,0]
	v_cvt_pk_f32_fp8_e32 v[236:237], v145
	v_cvt_pk_f32_fp8_sdwa v[238:239], v145 src0_sel:WORD_1
	v_pk_fma_f32 v[220:221], v[66:67], v[236:237], v[220:221] op_sel:[1,0,0]
	v_pk_fma_f32 v[222:223], v[66:67], v[238:239], v[222:223] op_sel:[1,0,0]
	v_cvt_pk_f32_fp8_e32 v[232:233], v146
	v_cvt_pk_f32_fp8_sdwa v[234:235], v146 src0_sel:WORD_1
	v_pk_fma_f32 v[224:225], v[66:67], v[232:233], v[224:225] op_sel:[1,0,0]
	v_pk_fma_f32 v[226:227], v[66:67], v[234:235], v[226:227] op_sel:[1,0,0]
	v_cvt_pk_f32_fp8_e32 v[236:237], v147
	v_cvt_pk_f32_fp8_sdwa v[238:239], v147 src0_sel:WORD_1
	v_pk_fma_f32 v[228:229], v[66:67], v[236:237], v[228:229] op_sel:[1,0,0]
	v_pk_fma_f32 v[230:231], v[66:67], v[238:239], v[230:231] op_sel:[1,0,0]
	ds_write2_b32 v5, v10, v11 offset0:4 offset1:20
	ds_write2_b32 v5, v12, v13 offset0:132 offset1:148
	s_waitcnt lgkmcnt(0)
	ds_read_b128 v[20:23], v6 offset:16
	ds_read_b128 v[24:27], v6 offset:32
	ds_read_b128 v[28:31], v6 offset:48
	ds_read_b128 v[32:35], v6 offset:64
	ds_read_b128 v[36:39], v6 offset:80
	ds_read_b128 v[40:43], v6 offset:96
	ds_read_b128 v[44:47], v6 offset:112
	ds_read_b128 v[48:51], v6 offset:128
	s_waitcnt vmcnt(15)
	v_cvt_pk_f32_fp8_e32 v[232:233], v148
	v_cvt_pk_f32_fp8_sdwa v[234:235], v148 src0_sel:WORD_1
	v_pk_fma_f32 v[216:217], v[68:69], v[232:233], v[216:217] op_sel_hi:[0,1,1]
	v_pk_fma_f32 v[218:219], v[68:69], v[234:235], v[218:219] op_sel_hi:[0,1,1]
	v_cvt_pk_f32_fp8_e32 v[236:237], v149
	v_cvt_pk_f32_fp8_sdwa v[238:239], v149 src0_sel:WORD_1
	v_pk_fma_f32 v[220:221], v[68:69], v[236:237], v[220:221] op_sel_hi:[0,1,1]
	v_pk_fma_f32 v[222:223], v[68:69], v[238:239], v[222:223] op_sel_hi:[0,1,1]
	v_cvt_pk_f32_fp8_e32 v[232:233], v150
	v_cvt_pk_f32_fp8_sdwa v[234:235], v150 src0_sel:WORD_1
	v_pk_fma_f32 v[224:225], v[68:69], v[232:233], v[224:225] op_sel_hi:[0,1,1]
	v_pk_fma_f32 v[226:227], v[68:69], v[234:235], v[226:227] op_sel_hi:[0,1,1]
	v_cvt_pk_f32_fp8_e32 v[236:237], v151
	v_cvt_pk_f32_fp8_sdwa v[238:239], v151 src0_sel:WORD_1
	v_pk_fma_f32 v[228:229], v[68:69], v[236:237], v[228:229] op_sel_hi:[0,1,1]
	v_pk_fma_f32 v[230:231], v[68:69], v[238:239], v[230:231] op_sel_hi:[0,1,1]
	s_waitcnt vmcnt(14)
	v_cvt_pk_f32_fp8_e32 v[232:233], v152
	v_cvt_pk_f32_fp8_sdwa v[234:235], v152 src0_sel:WORD_1
	v_pk_fma_f32 v[216:217], v[68:69], v[232:233], v[216:217] op_sel:[1,0,0]
	v_pk_fma_f32 v[218:219], v[68:69], v[234:235], v[218:219] op_sel:[1,0,0]
	v_cvt_pk_f32_fp8_e32 v[236:237], v153
	v_cvt_pk_f32_fp8_sdwa v[238:239], v153 src0_sel:WORD_1
	v_pk_fma_f32 v[220:221], v[68:69], v[236:237], v[220:221] op_sel:[1,0,0]
	v_pk_fma_f32 v[222:223], v[68:69], v[238:239], v[222:223] op_sel:[1,0,0]
	v_cvt_pk_f32_fp8_e32 v[232:233], v154
	v_cvt_pk_f32_fp8_sdwa v[234:235], v154 src0_sel:WORD_1
	v_pk_fma_f32 v[224:225], v[68:69], v[232:233], v[224:225] op_sel:[1,0,0]
	v_pk_fma_f32 v[226:227], v[68:69], v[234:235], v[226:227] op_sel:[1,0,0]
	v_cvt_pk_f32_fp8_e32 v[236:237], v155
	v_cvt_pk_f32_fp8_sdwa v[238:239], v155 src0_sel:WORD_1
	v_pk_fma_f32 v[228:229], v[68:69], v[236:237], v[228:229] op_sel:[1,0,0]
	v_pk_fma_f32 v[230:231], v[68:69], v[238:239], v[230:231] op_sel:[1,0,0]
	s_waitcnt vmcnt(13)
	v_cvt_pk_f32_fp8_e32 v[232:233], v156
	v_cvt_pk_f32_fp8_sdwa v[234:235], v156 src0_sel:WORD_1
	v_pk_fma_f32 v[216:217], v[70:71], v[232:233], v[216:217] op_sel_hi:[0,1,1]
	v_pk_fma_f32 v[218:219], v[70:71], v[234:235], v[218:219] op_sel_hi:[0,1,1]
	v_cvt_pk_f32_fp8_e32 v[236:237], v157
	v_cvt_pk_f32_fp8_sdwa v[238:239], v157 src0_sel:WORD_1
	v_pk_fma_f32 v[220:221], v[70:71], v[236:237], v[220:221] op_sel_hi:[0,1,1]
	v_pk_fma_f32 v[222:223], v[70:71], v[238:239], v[222:223] op_sel_hi:[0,1,1]
	v_cvt_pk_f32_fp8_e32 v[232:233], v158
	v_cvt_pk_f32_fp8_sdwa v[234:235], v158 src0_sel:WORD_1
	v_pk_fma_f32 v[224:225], v[70:71], v[232:233], v[224:225] op_sel_hi:[0,1,1]
	v_pk_fma_f32 v[226:227], v[70:71], v[234:235], v[226:227] op_sel_hi:[0,1,1]
	v_cvt_pk_f32_fp8_e32 v[236:237], v159
	v_cvt_pk_f32_fp8_sdwa v[238:239], v159 src0_sel:WORD_1
	v_pk_fma_f32 v[228:229], v[70:71], v[236:237], v[228:229] op_sel_hi:[0,1,1]
	v_pk_fma_f32 v[230:231], v[70:71], v[238:239], v[230:231] op_sel_hi:[0,1,1]
	s_waitcnt vmcnt(12)
	v_cvt_pk_f32_fp8_e32 v[232:233], v160
	v_cvt_pk_f32_fp8_sdwa v[234:235], v160 src0_sel:WORD_1
	v_pk_fma_f32 v[216:217], v[70:71], v[232:233], v[216:217] op_sel:[1,0,0]
	v_pk_fma_f32 v[218:219], v[70:71], v[234:235], v[218:219] op_sel:[1,0,0]
	v_cvt_pk_f32_fp8_e32 v[236:237], v161
	v_cvt_pk_f32_fp8_sdwa v[238:239], v161 src0_sel:WORD_1
	v_pk_fma_f32 v[220:221], v[70:71], v[236:237], v[220:221] op_sel:[1,0,0]
	v_pk_fma_f32 v[222:223], v[70:71], v[238:239], v[222:223] op_sel:[1,0,0]
	v_cvt_pk_f32_fp8_e32 v[232:233], v162
	v_cvt_pk_f32_fp8_sdwa v[234:235], v162 src0_sel:WORD_1
	v_pk_fma_f32 v[224:225], v[70:71], v[232:233], v[224:225] op_sel:[1,0,0]
	v_pk_fma_f32 v[226:227], v[70:71], v[234:235], v[226:227] op_sel:[1,0,0]
	v_cvt_pk_f32_fp8_e32 v[236:237], v163
	v_cvt_pk_f32_fp8_sdwa v[238:239], v163 src0_sel:WORD_1
	v_pk_fma_f32 v[228:229], v[70:71], v[236:237], v[228:229] op_sel:[1,0,0]
	v_pk_fma_f32 v[230:231], v[70:71], v[238:239], v[230:231] op_sel:[1,0,0]
	s_waitcnt vmcnt(11)
; DI f2_t cvt8lo(unsigned w) { return __builtin_amdgcn_cvt_pk_f32_fp8(w, false); }
; DI f2_t cvt8hi(unsigned w) { return __builtin_amdgcn_cvt_pk_f32_fp8(w, true); }
; DI void phase11(const Params& p, char* smem, int rep) {
;     ...
;         for (int k = 0; k < 16; ++k) rows[k] = *(const u32x4*)(vb + (size_t)ida[k] * 2048);
; #pragma unroll
;         for (int k = 0; k < 16; ++k) {
;           const f2_t a2 = {aa[k], aa[k]};
; #pragma unroll
;           for (int d = 0; d < 4; ++d) { const unsigned ww = rows[k][d]; o[2 * d] += a2 * cvt8lo(ww); o[2 * d + 1] += a2 * cvt8hi(ww); }
;         }
	v_cvt_pk_f32_fp8_e32 v[232:233], v164
	v_cvt_pk_f32_fp8_sdwa v[234:235], v164 src0_sel:WORD_1
	v_pk_fma_f32 v[216:217], v[72:73], v[232:233], v[216:217] op_sel_hi:[0,1,1]
	v_pk_fma_f32 v[218:219], v[72:73], v[234:235], v[218:219] op_sel_hi:[0,1,1]
	v_cvt_pk_f32_fp8_e32 v[236:237], v165
	v_cvt_pk_f32_fp8_sdwa v[238:239], v165 src0_sel:WORD_1
	v_pk_fma_f32 v[220:221], v[72:73], v[236:237], v[220:221] op_sel_hi:[0,1,1]
	v_pk_fma_f32 v[222:223], v[72:73], v[238:239], v[222:223] op_sel_hi:[0,1,1]
	v_cvt_pk_f32_fp8_e32 v[232:233], v166
	v_cvt_pk_f32_fp8_sdwa v[234:235], v166 src0_sel:WORD_1
	v_pk_fma_f32 v[224:225], v[72:73], v[232:233], v[224:225] op_sel_hi:[0,1,1]
	v_pk_fma_f32 v[226:227], v[72:73], v[234:235], v[226:227] op_sel_hi:[0,1,1]
	v_cvt_pk_f32_fp8_e32 v[236:237], v167
	v_cvt_pk_f32_fp8_sdwa v[238:239], v167 src0_sel:WORD_1
	v_pk_fma_f32 v[228:229], v[72:73], v[236:237], v[228:229] op_sel_hi:[0,1,1]
	v_pk_fma_f32 v[230:231], v[72:73], v[238:239], v[230:231] op_sel_hi:[0,1,1]
	s_waitcnt vmcnt(10)
	v_cvt_pk_f32_fp8_e32 v[232:233], v168
	v_cvt_pk_f32_fp8_sdwa v[234:235], v168 src0_sel:WORD_1
	v_pk_fma_f32 v[216:217], v[72:73], v[232:233], v[216:217] op_sel:[1,0,0]
	v_pk_fma_f32 v[218:219], v[72:73], v[234:235], v[218:219] op_sel:[1,0,0]
	v_cvt_pk_f32_fp8_e32 v[236:237], v169
	v_cvt_pk_f32_fp8_sdwa v[238:239], v169 src0_sel:WORD_1
	v_pk_fma_f32 v[220:221], v[72:73], v[236:237], v[220:221] op_sel:[1,0,0]
	v_pk_fma_f32 v[222:223], v[72:73], v[238:239], v[222:223] op_sel:[1,0,0]
	v_cvt_pk_f32_fp8_e32 v[232:233], v170
	v_cvt_pk_f32_fp8_sdwa v[234:235], v170 src0_sel:WORD_1
	v_pk_fma_f32 v[224:225], v[72:73], v[232:233], v[224:225] op_sel:[1,0,0]
	v_pk_fma_f32 v[226:227], v[72:73], v[234:235], v[226:227] op_sel:[1,0,0]
	v_cvt_pk_f32_fp8_e32 v[236:237], v171
	v_cvt_pk_f32_fp8_sdwa v[238:239], v171 src0_sel:WORD_1
	v_pk_fma_f32 v[228:229], v[72:73], v[236:237], v[228:229] op_sel:[1,0,0]
	v_pk_fma_f32 v[230:231], v[72:73], v[238:239], v[230:231] op_sel:[1,0,0]
	s_waitcnt vmcnt(9)
	v_cvt_pk_f32_fp8_e32 v[232:233], v172
	v_cvt_pk_f32_fp8_sdwa v[234:235], v172 src0_sel:WORD_1
	v_pk_fma_f32 v[216:217], v[74:75], v[232:233], v[216:217] op_sel_hi:[0,1,1]
	v_pk_fma_f32 v[218:219], v[74:75], v[234:235], v[218:219] op_sel_hi:[0,1,1]
	v_cvt_pk_f32_fp8_e32 v[236:237], v173
	v_cvt_pk_f32_fp8_sdwa v[238:239], v173 src0_sel:WORD_1
	v_pk_fma_f32 v[220:221], v[74:75], v[236:237], v[220:221] op_sel_hi:[0,1,1]
	v_pk_fma_f32 v[222:223], v[74:75], v[238:239], v[222:223] op_sel_hi:[0,1,1]
	v_cvt_pk_f32_fp8_e32 v[232:233], v174
	v_cvt_pk_f32_fp8_sdwa v[234:235], v174 src0_sel:WORD_1
	v_pk_fma_f32 v[224:225], v[74:75], v[232:233], v[224:225] op_sel_hi:[0,1,1]
	v_pk_fma_f32 v[226:227], v[74:75], v[234:235], v[226:227] op_sel_hi:[0,1,1]
	v_cvt_pk_f32_fp8_e32 v[236:237], v175
	v_cvt_pk_f32_fp8_sdwa v[238:239], v175 src0_sel:WORD_1
	v_pk_fma_f32 v[228:229], v[74:75], v[236:237], v[228:229] op_sel_hi:[0,1,1]
	v_pk_fma_f32 v[230:231], v[74:75], v[238:239], v[230:231] op_sel_hi:[0,1,1]
	s_waitcnt vmcnt(8)
	v_cvt_pk_f32_fp8_e32 v[232:233], v176
	v_cvt_pk_f32_fp8_sdwa v[234:235], v176 src0_sel:WORD_1
	v_pk_fma_f32 v[216:217], v[74:75], v[232:233], v[216:217] op_sel:[1,0,0]
	v_pk_fma_f32 v[218:219], v[74:75], v[234:235], v[218:219] op_sel:[1,0,0]
	v_cvt_pk_f32_fp8_e32 v[236:237], v177
	v_cvt_pk_f32_fp8_sdwa v[238:239], v177 src0_sel:WORD_1
	v_pk_fma_f32 v[220:221], v[74:75], v[236:237], v[220:221] op_sel:[1,0,0]
	v_pk_fma_f32 v[222:223], v[74:75], v[238:239], v[222:223] op_sel:[1,0,0]
	v_cvt_pk_f32_fp8_e32 v[232:233], v178
	v_cvt_pk_f32_fp8_sdwa v[234:235], v178 src0_sel:WORD_1
	v_pk_fma_f32 v[224:225], v[74:75], v[232:233], v[224:225] op_sel:[1,0,0]
	v_pk_fma_f32 v[226:227], v[74:75], v[234:235], v[226:227] op_sel:[1,0,0]
	v_cvt_pk_f32_fp8_e32 v[236:237], v179
	v_cvt_pk_f32_fp8_sdwa v[238:239], v179 src0_sel:WORD_1
	v_pk_fma_f32 v[228:229], v[74:75], v[236:237], v[228:229] op_sel:[1,0,0]
	v_pk_fma_f32 v[230:231], v[74:75], v[238:239], v[230:231] op_sel:[1,0,0]
	s_waitcnt vmcnt(7)
	v_cvt_pk_f32_fp8_e32 v[232:233], v180
	v_cvt_pk_f32_fp8_sdwa v[234:235], v180 src0_sel:WORD_1
	v_pk_fma_f32 v[216:217], v[76:77], v[232:233], v[216:217] op_sel_hi:[0,1,1]
	v_pk_fma_f32 v[218:219], v[76:77], v[234:235], v[218:219] op_sel_hi:[0,1,1]
	v_cvt_pk_f32_fp8_e32 v[236:237], v181
	v_cvt_pk_f32_fp8_sdwa v[238:239], v181 src0_sel:WORD_1
	v_pk_fma_f32 v[220:221], v[76:77], v[236:237], v[220:221] op_sel_hi:[0,1,1]
	v_pk_fma_f32 v[222:223], v[76:77], v[238:239], v[222:223] op_sel_hi:[0,1,1]
	v_cvt_pk_f32_fp8_e32 v[232:233], v182
	v_cvt_pk_f32_fp8_sdwa v[234:235], v182 src0_sel:WORD_1
	v_pk_fma_f32 v[224:225], v[76:77], v[232:233], v[224:225] op_sel_hi:[0,1,1]
	v_pk_fma_f32 v[226:227], v[76:77], v[234:235], v[226:227] op_sel_hi:[0,1,1]
	v_cvt_pk_f32_fp8_e32 v[236:237], v183
	v_cvt_pk_f32_fp8_sdwa v[238:239], v183 src0_sel:WORD_1
	v_pk_fma_f32 v[228:229], v[76:77], v[236:237], v[228:229] op_sel_hi:[0,1,1]
	v_pk_fma_f32 v[230:231], v[76:77], v[238:239], v[230:231] op_sel_hi:[0,1,1]
	s_waitcnt vmcnt(6)
	v_cvt_pk_f32_fp8_e32 v[232:233], v184
	v_cvt_pk_f32_fp8_sdwa v[234:235], v184 src0_sel:WORD_1
	v_pk_fma_f32 v[216:217], v[76:77], v[232:233], v[216:217] op_sel:[1,0,0]
	v_pk_fma_f32 v[218:219], v[76:77], v[234:235], v[218:219] op_sel:[1,0,0]
	v_cvt_pk_f32_fp8_e32 v[236:237], v185
	v_cvt_pk_f32_fp8_sdwa v[238:239], v185 src0_sel:WORD_1
	v_pk_fma_f32 v[220:221], v[76:77], v[236:237], v[220:221] op_sel:[1,0,0]
	v_pk_fma_f32 v[222:223], v[76:77], v[238:239], v[222:223] op_sel:[1,0,0]
	v_cvt_pk_f32_fp8_e32 v[232:233], v186
	v_cvt_pk_f32_fp8_sdwa v[234:235], v186 src0_sel:WORD_1
	v_pk_fma_f32 v[224:225], v[76:77], v[232:233], v[224:225] op_sel:[1,0,0]
	v_pk_fma_f32 v[226:227], v[76:77], v[234:235], v[226:227] op_sel:[1,0,0]
	v_cvt_pk_f32_fp8_e32 v[236:237], v187
	v_cvt_pk_f32_fp8_sdwa v[238:239], v187 src0_sel:WORD_1
	v_pk_fma_f32 v[228:229], v[76:77], v[236:237], v[228:229] op_sel:[1,0,0]
	v_pk_fma_f32 v[230:231], v[76:77], v[238:239], v[230:231] op_sel:[1,0,0]
	s_waitcnt vmcnt(5)
; DI f2_t cvt8lo(unsigned w) { return __builtin_amdgcn_cvt_pk_f32_fp8(w, false); }
; DI f2_t cvt8hi(unsigned w) { return __builtin_amdgcn_cvt_pk_f32_fp8(w, true); }
; DI void phase11(const Params& p, char* smem, int rep) {
;     ...
;         for (int k = 0; k < 16; ++k) rows[k] = *(const u32x4*)(vb + (size_t)ida[k] * 2048);
; #pragma unroll
;         for (int k = 0; k < 16; ++k) {
;           const f2_t a2 = {aa[k], aa[k]};
; #pragma unroll
;           for (int d = 0; d < 4; ++d) { const unsigned ww = rows[k][d]; o[2 * d] += a2 * cvt8lo(ww); o[2 * d + 1] += a2 * cvt8hi(ww); }
;         }
	v_cvt_pk_f32_fp8_e32 v[232:233], v190
	v_cvt_pk_f32_fp8_sdwa v[234:235], v190 src0_sel:WORD_1
	v_pk_fma_f32 v[216:217], v[78:79], v[232:233], v[216:217] op_sel_hi:[0,1,1]
	v_pk_fma_f32 v[218:219], v[78:79], v[234:235], v[218:219] op_sel_hi:[0,1,1]
	v_cvt_pk_f32_fp8_e32 v[236:237], v191
	v_cvt_pk_f32_fp8_sdwa v[238:239], v191 src0_sel:WORD_1
	v_pk_fma_f32 v[220:221], v[78:79], v[236:237], v[220:221] op_sel_hi:[0,1,1]
	v_pk_fma_f32 v[222:223], v[78:79], v[238:239], v[222:223] op_sel_hi:[0,1,1]
	v_cvt_pk_f32_fp8_e32 v[232:233], v192
	v_cvt_pk_f32_fp8_sdwa v[234:235], v192 src0_sel:WORD_1
	v_pk_fma_f32 v[224:225], v[78:79], v[232:233], v[224:225] op_sel_hi:[0,1,1]
	v_pk_fma_f32 v[226:227], v[78:79], v[234:235], v[226:227] op_sel_hi:[0,1,1]
	v_cvt_pk_f32_fp8_e32 v[236:237], v193
	v_cvt_pk_f32_fp8_sdwa v[238:239], v193 src0_sel:WORD_1
	v_pk_fma_f32 v[228:229], v[78:79], v[236:237], v[228:229] op_sel_hi:[0,1,1]
	v_pk_fma_f32 v[230:231], v[78:79], v[238:239], v[230:231] op_sel_hi:[0,1,1]
	s_waitcnt vmcnt(4)
	v_cvt_pk_f32_fp8_e32 v[232:233], v194
	v_cvt_pk_f32_fp8_sdwa v[234:235], v194 src0_sel:WORD_1
	v_pk_fma_f32 v[216:217], v[78:79], v[232:233], v[216:217] op_sel:[1,0,0]
	v_pk_fma_f32 v[218:219], v[78:79], v[234:235], v[218:219] op_sel:[1,0,0]
	v_cvt_pk_f32_fp8_e32 v[236:237], v195
	v_cvt_pk_f32_fp8_sdwa v[238:239], v195 src0_sel:WORD_1
	v_pk_fma_f32 v[220:221], v[78:79], v[236:237], v[220:221] op_sel:[1,0,0]
	v_pk_fma_f32 v[222:223], v[78:79], v[238:239], v[222:223] op_sel:[1,0,0]
	v_cvt_pk_f32_fp8_e32 v[232:233], v196
	v_cvt_pk_f32_fp8_sdwa v[234:235], v196 src0_sel:WORD_1
	v_pk_fma_f32 v[224:225], v[78:79], v[232:233], v[224:225] op_sel:[1,0,0]
	v_pk_fma_f32 v[226:227], v[78:79], v[234:235], v[226:227] op_sel:[1,0,0]
	v_cvt_pk_f32_fp8_e32 v[236:237], v197
	v_cvt_pk_f32_fp8_sdwa v[238:239], v197 src0_sel:WORD_1
	v_pk_fma_f32 v[228:229], v[78:79], v[236:237], v[228:229] op_sel:[1,0,0]
	v_pk_fma_f32 v[230:231], v[78:79], v[238:239], v[230:231] op_sel:[1,0,0]
	s_waitcnt vmcnt(3)
	v_cvt_pk_f32_fp8_e32 v[232:233], v198
	v_cvt_pk_f32_fp8_sdwa v[234:235], v198 src0_sel:WORD_1
	v_pk_fma_f32 v[216:217], v[80:81], v[232:233], v[216:217] op_sel_hi:[0,1,1]
	v_pk_fma_f32 v[218:219], v[80:81], v[234:235], v[218:219] op_sel_hi:[0,1,1]
	v_cvt_pk_f32_fp8_e32 v[236:237], v199
	v_cvt_pk_f32_fp8_sdwa v[238:239], v199 src0_sel:WORD_1
	v_pk_fma_f32 v[220:221], v[80:81], v[236:237], v[220:221] op_sel_hi:[0,1,1]
	v_pk_fma_f32 v[222:223], v[80:81], v[238:239], v[222:223] op_sel_hi:[0,1,1]
	v_cvt_pk_f32_fp8_e32 v[232:233], v200
	v_cvt_pk_f32_fp8_sdwa v[234:235], v200 src0_sel:WORD_1
	v_pk_fma_f32 v[224:225], v[80:81], v[232:233], v[224:225] op_sel_hi:[0,1,1]
	v_pk_fma_f32 v[226:227], v[80:81], v[234:235], v[226:227] op_sel_hi:[0,1,1]
	v_cvt_pk_f32_fp8_e32 v[236:237], v201
	v_cvt_pk_f32_fp8_sdwa v[238:239], v201 src0_sel:WORD_1
	v_pk_fma_f32 v[228:229], v[80:81], v[236:237], v[228:229] op_sel_hi:[0,1,1]
	v_pk_fma_f32 v[230:231], v[80:81], v[238:239], v[230:231] op_sel_hi:[0,1,1]
	s_waitcnt vmcnt(2)
	v_cvt_pk_f32_fp8_e32 v[232:233], v202
	v_cvt_pk_f32_fp8_sdwa v[234:235], v202 src0_sel:WORD_1
	v_pk_fma_f32 v[216:217], v[80:81], v[232:233], v[216:217] op_sel:[1,0,0]
	v_pk_fma_f32 v[218:219], v[80:81], v[234:235], v[218:219] op_sel:[1,0,0]
	v_cvt_pk_f32_fp8_e32 v[236:237], v203
	v_cvt_pk_f32_fp8_sdwa v[238:239], v203 src0_sel:WORD_1
	v_pk_fma_f32 v[220:221], v[80:81], v[236:237], v[220:221] op_sel:[1,0,0]
	v_pk_fma_f32 v[222:223], v[80:81], v[238:239], v[222:223] op_sel:[1,0,0]
	v_cvt_pk_f32_fp8_e32 v[232:233], v204
	v_cvt_pk_f32_fp8_sdwa v[234:235], v204 src0_sel:WORD_1
	v_pk_fma_f32 v[224:225], v[80:81], v[232:233], v[224:225] op_sel:[1,0,0]
	v_pk_fma_f32 v[226:227], v[80:81], v[234:235], v[226:227] op_sel:[1,0,0]
	v_cvt_pk_f32_fp8_e32 v[236:237], v205
	v_cvt_pk_f32_fp8_sdwa v[238:239], v205 src0_sel:WORD_1
	v_pk_fma_f32 v[228:229], v[80:81], v[236:237], v[228:229] op_sel:[1,0,0]
	v_pk_fma_f32 v[230:231], v[80:81], v[238:239], v[230:231] op_sel:[1,0,0]
	s_waitcnt vmcnt(1)
	v_cvt_pk_f32_fp8_e32 v[232:233], v206
	v_cvt_pk_f32_fp8_sdwa v[234:235], v206 src0_sel:WORD_1
	v_pk_fma_f32 v[216:217], v[82:83], v[232:233], v[216:217] op_sel_hi:[0,1,1]
	v_pk_fma_f32 v[218:219], v[82:83], v[234:235], v[218:219] op_sel_hi:[0,1,1]
	v_cvt_pk_f32_fp8_e32 v[236:237], v207
	v_cvt_pk_f32_fp8_sdwa v[238:239], v207 src0_sel:WORD_1
	v_pk_fma_f32 v[220:221], v[82:83], v[236:237], v[220:221] op_sel_hi:[0,1,1]
	v_pk_fma_f32 v[222:223], v[82:83], v[238:239], v[222:223] op_sel_hi:[0,1,1]
	v_cvt_pk_f32_fp8_e32 v[232:233], v208
	v_cvt_pk_f32_fp8_sdwa v[234:235], v208 src0_sel:WORD_1
	v_pk_fma_f32 v[224:225], v[82:83], v[232:233], v[224:225] op_sel_hi:[0,1,1]
	v_pk_fma_f32 v[226:227], v[82:83], v[234:235], v[226:227] op_sel_hi:[0,1,1]
	v_cvt_pk_f32_fp8_e32 v[236:237], v209
	v_cvt_pk_f32_fp8_sdwa v[238:239], v209 src0_sel:WORD_1
	v_pk_fma_f32 v[228:229], v[82:83], v[236:237], v[228:229] op_sel_hi:[0,1,1]
	v_pk_fma_f32 v[230:231], v[82:83], v[238:239], v[230:231] op_sel_hi:[0,1,1]
	s_waitcnt vmcnt(0)
; DI unsigned pk2(float a, float b) { f2_t v = {a, b}; bf2_t r = __builtin_convertvector(v, bf2_t); return __builtin_bit_cast(unsigned, r); }
; DI void phase11(const Params& p, char* smem, int rep) {
;     ...
;       const int tok = __builtin_amdgcn_readfirstlane(c * 16 + w * 4 + t);
;       const int i0 = IDS[(size_t)tok * 128 + lane], i1 = IDS[(size_t)tok * 128 + 64 + lane];
;       const float a0 = ACT[(size_t)tok * 128 + lane], a1 = ACT[(size_t)tok * 128 + 64 + lane];
;     ...
;       float ov[16];
; #pragma unroll
;       for (int d = 0; d < 4; ++d) { ov[4 * d] = o[2 * d].x; ov[4 * d + 1] = o[2 * d].y; ov[4 * d + 2] = o[2 * d + 1].x; ov[4 * d + 3] = o[2 * d + 1].y; }
;       float q8[8], q4[4];
; #pragma unroll
;       for (int k = 0; k < 8; ++k) q8[k] = (b5 ? ov[8 + k] : ov[k]) + __shfl_xor(b5 ? ov[k] : ov[8 + k], 32);
; #pragma unroll
;       for (int k = 0; k < 4; ++k) q4[k] = (b4 ? q8[4 + k] : q8[k]) + __shfl_xor(b4 ? q8[k] : q8[4 + k], 16);
;       *(uint2*)(OUTP + (size_t)tok * D_ + s * 256 + l15 * 16 + 8 * b5 + 4 * b4) = make_uint2(pk2(q4[0], q4[1]), pk2(q4[2], q4[3]));
	v_cvt_pk_f32_fp8_e32 v[232:233], v210
	v_cvt_pk_f32_fp8_sdwa v[234:235], v210 src0_sel:WORD_1
	v_pk_fma_f32 v[216:217], v[82:83], v[232:233], v[216:217] op_sel:[1,0,0]
	v_pk_fma_f32 v[218:219], v[82:83], v[234:235], v[218:219] op_sel:[1,0,0]
	v_cvt_pk_f32_fp8_e32 v[236:237], v211
	v_cvt_pk_f32_fp8_sdwa v[238:239], v211 src0_sel:WORD_1
	v_pk_fma_f32 v[220:221], v[82:83], v[236:237], v[220:221] op_sel:[1,0,0]
	v_pk_fma_f32 v[222:223], v[82:83], v[238:239], v[222:223] op_sel:[1,0,0]
	v_cvt_pk_f32_fp8_e32 v[232:233], v212
	v_cvt_pk_f32_fp8_sdwa v[234:235], v212 src0_sel:WORD_1
	v_pk_fma_f32 v[224:225], v[82:83], v[232:233], v[224:225] op_sel:[1,0,0]
	v_pk_fma_f32 v[226:227], v[82:83], v[234:235], v[226:227] op_sel:[1,0,0]
	v_cvt_pk_f32_fp8_e32 v[236:237], v213
	v_cvt_pk_f32_fp8_sdwa v[238:239], v213 src0_sel:WORD_1
	v_pk_fma_f32 v[228:229], v[82:83], v[236:237], v[228:229] op_sel:[1,0,0]
	v_pk_fma_f32 v[230:231], v[82:83], v[238:239], v[230:231] op_sel:[1,0,0]
	ds_read_b128 v[52:55], v6 offset:528
	ds_read_b128 v[56:59], v6 offset:544
	ds_read_b128 v[60:63], v6 offset:560
	ds_read_b128 v[64:67], v6 offset:576
	ds_read_b128 v[68:71], v6 offset:592
	ds_read_b128 v[72:75], v6 offset:608
	ds_read_b128 v[76:79], v6 offset:624
	ds_read_b128 v[80:83], v6 offset:640
	v_add_u32_e32 v214, s46, v4
	s_nop 0
	v_permlane32_swap_b32_e32 v216, v224
	v_permlane32_swap_b32_e32 v217, v225
	v_permlane32_swap_b32_e32 v218, v226
	v_permlane32_swap_b32_e32 v219, v227
	v_permlane32_swap_b32_e32 v220, v228
	v_permlane32_swap_b32_e32 v221, v229
	v_permlane32_swap_b32_e32 v222, v230
	v_permlane32_swap_b32_e32 v223, v231
	v_add_f32_e32 v216, v216, v224
	v_add_f32_e32 v217, v217, v225
	v_add_f32_e32 v218, v218, v226
	v_add_f32_e32 v219, v219, v227
	v_add_f32_e32 v220, v220, v228
	v_add_f32_e32 v221, v221, v229
	v_add_f32_e32 v222, v222, v230
	v_add_f32_e32 v223, v223, v231
	s_nop 1
	v_permlane16_swap_b32_e32 v216, v220
	v_permlane16_swap_b32_e32 v217, v221
	v_permlane16_swap_b32_e32 v218, v222
	v_permlane16_swap_b32_e32 v219, v223
	v_add_f32_e32 v216, v216, v220
	v_add_f32_e32 v217, v217, v221
	v_add_f32_e32 v218, v218, v222
	v_add_f32_e32 v219, v219, v223
	v_cvt_pk_bf16_f32 v232, v216, v217
	v_cvt_pk_bf16_f32 v233, v218, v219
	global_store_dwordx2 v214, v[232:233], s[14:15]
	s_add_i32 s54, s34, 3
	s_lshl_b32 s46, s54, 12
	s_add_i32 s46, s46, s24
	s_add_i32 s55, s34, 4
	s_add_i32 s51, s48, 1
	s_cmp_lt_u32 s51, s49
	s_cselect_b32 s55, s55, 8192
	s_cmp_lt_u32 s55, 8192
	s_cselect_b32 s55, s55, 0
	s_lshl_b32 s47, s55, 9
	s_add_u32 s42, s6, s47
	s_addc_u32 s43, s7, 0
	s_add_u32 s44, s8, s47
	s_addc_u32 s45, s9, 0
	global_load_dword v10, v3, s[42:43]
	global_load_dword v11, v3, s[42:43] offset:256
	global_load_dword v12, v3, s[44:45]
	global_load_dword v13, v3, s[44:45] offset:256
	s_waitcnt lgkmcnt(0)
	v_lshl_add_u32 v20, v20, 11, v2
	v_lshl_add_u32 v21, v21, 11, v2
	v_lshl_add_u32 v22, v22, 11, v2
	v_lshl_add_u32 v23, v23, 11, v2
	v_lshl_add_u32 v24, v24, 11, v2
	v_lshl_add_u32 v25, v25, 11, v2
	v_lshl_add_u32 v26, v26, 11, v2
	v_lshl_add_u32 v27, v27, 11, v2
	v_lshl_add_u32 v28, v28, 11, v2
	v_lshl_add_u32 v29, v29, 11, v2
	v_lshl_add_u32 v30, v30, 11, v2
	v_lshl_add_u32 v31, v31, 11, v2
	v_lshl_add_u32 v32, v32, 11, v2
	v_lshl_add_u32 v33, v33, 11, v2
	v_lshl_add_u32 v34, v34, 11, v2
	v_lshl_add_u32 v35, v35, 11, v2
	v_lshl_add_u32 v36, v36, 11, v2
	v_lshl_add_u32 v37, v37, 11, v2
	v_lshl_add_u32 v38, v38, 11, v2
	v_lshl_add_u32 v39, v39, 11, v2
	v_lshl_add_u32 v40, v40, 11, v2
	v_lshl_add_u32 v41, v41, 11, v2
	v_lshl_add_u32 v42, v42, 11, v2
	v_lshl_add_u32 v43, v43, 11, v2
	v_lshl_add_u32 v44, v44, 11, v2
	v_lshl_add_u32 v45, v45, 11, v2
	v_lshl_add_u32 v46, v46, 11, v2
	v_lshl_add_u32 v47, v47, 11, v2
	v_lshl_add_u32 v48, v48, 11, v2
	v_lshl_add_u32 v49, v49, 11, v2
	v_lshl_add_u32 v50, v50, 11, v2
	v_lshl_add_u32 v51, v51, 11, v2
	global_load_dwordx4 v[84:87], v20, s[20:21]
	global_load_dwordx4 v[88:91], v21, s[20:21]
	global_load_dwordx4 v[92:95], v22, s[20:21]
	global_load_dwordx4 v[96:99], v23, s[20:21]
	global_load_dwordx4 v[100:103], v24, s[20:21]
	global_load_dwordx4 v[104:107], v25, s[20:21]
	global_load_dwordx4 v[108:111], v26, s[20:21]
	global_load_dwordx4 v[112:115], v27, s[20:21]
	global_load_dwordx4 v[116:119], v28, s[20:21]
	global_load_dwordx4 v[120:123], v29, s[20:21]
	global_load_dwordx4 v[124:127], v30, s[20:21]
	global_load_dwordx4 v[128:131], v31, s[20:21]
	global_load_dwordx4 v[132:135], v32, s[20:21]
	global_load_dwordx4 v[136:139], v33, s[20:21]
	global_load_dwordx4 v[140:143], v34, s[20:21]
	global_load_dwordx4 v[144:147], v35, s[20:21]
	global_load_dwordx4 v[148:151], v36, s[20:21]
	global_load_dwordx4 v[152:155], v37, s[20:21]
	global_load_dwordx4 v[156:159], v38, s[20:21]
	global_load_dwordx4 v[160:163], v39, s[20:21]
	global_load_dwordx4 v[164:167], v40, s[20:21]
	global_load_dwordx4 v[168:171], v41, s[20:21]
	global_load_dwordx4 v[172:175], v42, s[20:21]
	global_load_dwordx4 v[176:179], v43, s[20:21]
	global_load_dwordx4 v[180:183], v44, s[20:21]
	global_load_dwordx4 v[184:187], v45, s[20:21]
	global_load_dwordx4 v[190:193], v46, s[20:21]
	global_load_dwordx4 v[194:197], v47, s[20:21]
	global_load_dwordx4 v[198:201], v48, s[20:21]
	global_load_dwordx4 v[202:205], v49, s[20:21]
	global_load_dwordx4 v[206:209], v50, s[20:21]
	global_load_dwordx4 v[210:213], v51, s[20:21]
	s_waitcnt vmcnt(31)
; DI f2_t cvt8lo(unsigned w) { return __builtin_amdgcn_cvt_pk_f32_fp8(w, false); }
; DI f2_t cvt8hi(unsigned w) { return __builtin_amdgcn_cvt_pk_f32_fp8(w, true); }
; DI void phase11(const Params& p, char* smem, int rep) {
;     ...
;         for (int k = 0; k < 16; ++k) rows[k] = *(const u32x4*)(vb + (size_t)ida[k] * 2048);
; #pragma unroll
;         for (int k = 0; k < 16; ++k) {
;           const f2_t a2 = {aa[k], aa[k]};
; #pragma unroll
;           for (int d = 0; d < 4; ++d) { const unsigned ww = rows[k][d]; o[2 * d] += a2 * cvt8lo(ww); o[2 * d + 1] += a2 * cvt8hi(ww); }
;         }
	v_cvt_pk_f32_fp8_e32 v[232:233], v84
	v_cvt_pk_f32_fp8_sdwa v[234:235], v84 src0_sel:WORD_1
	v_pk_fma_f32 v[216:217], v[52:53], v[232:233], 0 op_sel_hi:[0,1,0]
	v_pk_fma_f32 v[218:219], v[52:53], v[234:235], 0 op_sel_hi:[0,1,0]
	v_cvt_pk_f32_fp8_e32 v[236:237], v85
	v_cvt_pk_f32_fp8_sdwa v[238:239], v85 src0_sel:WORD_1
	v_pk_fma_f32 v[220:221], v[52:53], v[236:237], 0 op_sel_hi:[0,1,0]
	v_pk_fma_f32 v[222:223], v[52:53], v[238:239], 0 op_sel_hi:[0,1,0]
	v_cvt_pk_f32_fp8_e32 v[232:233], v86
	v_cvt_pk_f32_fp8_sdwa v[234:235], v86 src0_sel:WORD_1
	v_pk_fma_f32 v[224:225], v[52:53], v[232:233], 0 op_sel_hi:[0,1,0]
	v_pk_fma_f32 v[226:227], v[52:53], v[234:235], 0 op_sel_hi:[0,1,0]
	v_cvt_pk_f32_fp8_e32 v[236:237], v87
	v_cvt_pk_f32_fp8_sdwa v[238:239], v87 src0_sel:WORD_1
	v_pk_fma_f32 v[228:229], v[52:53], v[236:237], 0 op_sel_hi:[0,1,0]
	v_pk_fma_f32 v[230:231], v[52:53], v[238:239], 0 op_sel_hi:[0,1,0]
	s_waitcnt vmcnt(30)
	v_cvt_pk_f32_fp8_e32 v[232:233], v88
	v_cvt_pk_f32_fp8_sdwa v[234:235], v88 src0_sel:WORD_1
	v_pk_fma_f32 v[216:217], v[52:53], v[232:233], v[216:217] op_sel:[1,0,0]
	v_pk_fma_f32 v[218:219], v[52:53], v[234:235], v[218:219] op_sel:[1,0,0]
	v_cvt_pk_f32_fp8_e32 v[236:237], v89
	v_cvt_pk_f32_fp8_sdwa v[238:239], v89 src0_sel:WORD_1
	v_pk_fma_f32 v[220:221], v[52:53], v[236:237], v[220:221] op_sel:[1,0,0]
	v_pk_fma_f32 v[222:223], v[52:53], v[238:239], v[222:223] op_sel:[1,0,0]
	v_cvt_pk_f32_fp8_e32 v[232:233], v90
	v_cvt_pk_f32_fp8_sdwa v[234:235], v90 src0_sel:WORD_1
	v_pk_fma_f32 v[224:225], v[52:53], v[232:233], v[224:225] op_sel:[1,0,0]
	v_pk_fma_f32 v[226:227], v[52:53], v[234:235], v[226:227] op_sel:[1,0,0]
	v_cvt_pk_f32_fp8_e32 v[236:237], v91
	v_cvt_pk_f32_fp8_sdwa v[238:239], v91 src0_sel:WORD_1
	v_pk_fma_f32 v[228:229], v[52:53], v[236:237], v[228:229] op_sel:[1,0,0]
	v_pk_fma_f32 v[230:231], v[52:53], v[238:239], v[230:231] op_sel:[1,0,0]
	s_waitcnt vmcnt(29)
	v_cvt_pk_f32_fp8_e32 v[232:233], v92
	v_cvt_pk_f32_fp8_sdwa v[234:235], v92 src0_sel:WORD_1
	v_pk_fma_f32 v[216:217], v[54:55], v[232:233], v[216:217] op_sel_hi:[0,1,1]
	v_pk_fma_f32 v[218:219], v[54:55], v[234:235], v[218:219] op_sel_hi:[0,1,1]
	v_cvt_pk_f32_fp8_e32 v[236:237], v93
	v_cvt_pk_f32_fp8_sdwa v[238:239], v93 src0_sel:WORD_1
	v_pk_fma_f32 v[220:221], v[54:55], v[236:237], v[220:221] op_sel_hi:[0,1,1]
	v_pk_fma_f32 v[222:223], v[54:55], v[238:239], v[222:223] op_sel_hi:[0,1,1]
	v_cvt_pk_f32_fp8_e32 v[232:233], v94
	v_cvt_pk_f32_fp8_sdwa v[234:235], v94 src0_sel:WORD_1
	v_pk_fma_f32 v[224:225], v[54:55], v[232:233], v[224:225] op_sel_hi:[0,1,1]
	v_pk_fma_f32 v[226:227], v[54:55], v[234:235], v[226:227] op_sel_hi:[0,1,1]
	v_cvt_pk_f32_fp8_e32 v[236:237], v95
	v_cvt_pk_f32_fp8_sdwa v[238:239], v95 src0_sel:WORD_1
	v_pk_fma_f32 v[228:229], v[54:55], v[236:237], v[228:229] op_sel_hi:[0,1,1]
	v_pk_fma_f32 v[230:231], v[54:55], v[238:239], v[230:231] op_sel_hi:[0,1,1]
	s_waitcnt vmcnt(28)
	v_cvt_pk_f32_fp8_e32 v[232:233], v96
	v_cvt_pk_f32_fp8_sdwa v[234:235], v96 src0_sel:WORD_1
	v_pk_fma_f32 v[216:217], v[54:55], v[232:233], v[216:217] op_sel:[1,0,0]
	v_pk_fma_f32 v[218:219], v[54:55], v[234:235], v[218:219] op_sel:[1,0,0]
	v_cvt_pk_f32_fp8_e32 v[236:237], v97
	v_cvt_pk_f32_fp8_sdwa v[238:239], v97 src0_sel:WORD_1
	v_pk_fma_f32 v[220:221], v[54:55], v[236:237], v[220:221] op_sel:[1,0,0]
	v_pk_fma_f32 v[222:223], v[54:55], v[238:239], v[222:223] op_sel:[1,0,0]
	v_cvt_pk_f32_fp8_e32 v[232:233], v98
	v_cvt_pk_f32_fp8_sdwa v[234:235], v98 src0_sel:WORD_1
	v_pk_fma_f32 v[224:225], v[54:55], v[232:233], v[224:225] op_sel:[1,0,0]
	v_pk_fma_f32 v[226:227], v[54:55], v[234:235], v[226:227] op_sel:[1,0,0]
	v_cvt_pk_f32_fp8_e32 v[236:237], v99
	v_cvt_pk_f32_fp8_sdwa v[238:239], v99 src0_sel:WORD_1
	v_pk_fma_f32 v[228:229], v[54:55], v[236:237], v[228:229] op_sel:[1,0,0]
	v_pk_fma_f32 v[230:231], v[54:55], v[238:239], v[230:231] op_sel:[1,0,0]
	s_waitcnt vmcnt(27)
	v_cvt_pk_f32_fp8_e32 v[232:233], v100
	v_cvt_pk_f32_fp8_sdwa v[234:235], v100 src0_sel:WORD_1
	v_pk_fma_f32 v[216:217], v[56:57], v[232:233], v[216:217] op_sel_hi:[0,1,1]
	v_pk_fma_f32 v[218:219], v[56:57], v[234:235], v[218:219] op_sel_hi:[0,1,1]
	v_cvt_pk_f32_fp8_e32 v[236:237], v101
	v_cvt_pk_f32_fp8_sdwa v[238:239], v101 src0_sel:WORD_1
	v_pk_fma_f32 v[220:221], v[56:57], v[236:237], v[220:221] op_sel_hi:[0,1,1]
	v_pk_fma_f32 v[222:223], v[56:57], v[238:239], v[222:223] op_sel_hi:[0,1,1]
	v_cvt_pk_f32_fp8_e32 v[232:233], v102
	v_cvt_pk_f32_fp8_sdwa v[234:235], v102 src0_sel:WORD_1
	v_pk_fma_f32 v[224:225], v[56:57], v[232:233], v[224:225] op_sel_hi:[0,1,1]
	v_pk_fma_f32 v[226:227], v[56:57], v[234:235], v[226:227] op_sel_hi:[0,1,1]
	v_cvt_pk_f32_fp8_e32 v[236:237], v103
	v_cvt_pk_f32_fp8_sdwa v[238:239], v103 src0_sel:WORD_1
	v_pk_fma_f32 v[228:229], v[56:57], v[236:237], v[228:229] op_sel_hi:[0,1,1]
	v_pk_fma_f32 v[230:231], v[56:57], v[238:239], v[230:231] op_sel_hi:[0,1,1]
	s_waitcnt vmcnt(26)
	v_cvt_pk_f32_fp8_e32 v[232:233], v104
	v_cvt_pk_f32_fp8_sdwa v[234:235], v104 src0_sel:WORD_1
	v_pk_fma_f32 v[216:217], v[56:57], v[232:233], v[216:217] op_sel:[1,0,0]
	v_pk_fma_f32 v[218:219], v[56:57], v[234:235], v[218:219] op_sel:[1,0,0]
	v_cvt_pk_f32_fp8_e32 v[236:237], v105
	v_cvt_pk_f32_fp8_sdwa v[238:239], v105 src0_sel:WORD_1
	v_pk_fma_f32 v[220:221], v[56:57], v[236:237], v[220:221] op_sel:[1,0,0]
	v_pk_fma_f32 v[222:223], v[56:57], v[238:239], v[222:223] op_sel:[1,0,0]
	v_cvt_pk_f32_fp8_e32 v[232:233], v106
	v_cvt_pk_f32_fp8_sdwa v[234:235], v106 src0_sel:WORD_1
	v_pk_fma_f32 v[224:225], v[56:57], v[232:233], v[224:225] op_sel:[1,0,0]
	v_pk_fma_f32 v[226:227], v[56:57], v[234:235], v[226:227] op_sel:[1,0,0]
	v_cvt_pk_f32_fp8_e32 v[236:237], v107
	v_cvt_pk_f32_fp8_sdwa v[238:239], v107 src0_sel:WORD_1
	v_pk_fma_f32 v[228:229], v[56:57], v[236:237], v[228:229] op_sel:[1,0,0]
	v_pk_fma_f32 v[230:231], v[56:57], v[238:239], v[230:231] op_sel:[1,0,0]
	s_waitcnt vmcnt(25)
; DI f2_t cvt8lo(unsigned w) { return __builtin_amdgcn_cvt_pk_f32_fp8(w, false); }
; DI f2_t cvt8hi(unsigned w) { return __builtin_amdgcn_cvt_pk_f32_fp8(w, true); }
; DI void phase11(const Params& p, char* smem, int rep) {
;     ...
;         for (int k = 0; k < 16; ++k) rows[k] = *(const u32x4*)(vb + (size_t)ida[k] * 2048);
; #pragma unroll
;         for (int k = 0; k < 16; ++k) {
;           const f2_t a2 = {aa[k], aa[k]};
; #pragma unroll
;           for (int d = 0; d < 4; ++d) { const unsigned ww = rows[k][d]; o[2 * d] += a2 * cvt8lo(ww); o[2 * d + 1] += a2 * cvt8hi(ww); }
;         }
	v_cvt_pk_f32_fp8_e32 v[232:233], v108
	v_cvt_pk_f32_fp8_sdwa v[234:235], v108 src0_sel:WORD_1
	v_pk_fma_f32 v[216:217], v[58:59], v[232:233], v[216:217] op_sel_hi:[0,1,1]
	v_pk_fma_f32 v[218:219], v[58:59], v[234:235], v[218:219] op_sel_hi:[0,1,1]
	v_cvt_pk_f32_fp8_e32 v[236:237], v109
	v_cvt_pk_f32_fp8_sdwa v[238:239], v109 src0_sel:WORD_1
	v_pk_fma_f32 v[220:221], v[58:59], v[236:237], v[220:221] op_sel_hi:[0,1,1]
	v_pk_fma_f32 v[222:223], v[58:59], v[238:239], v[222:223] op_sel_hi:[0,1,1]
	v_cvt_pk_f32_fp8_e32 v[232:233], v110
	v_cvt_pk_f32_fp8_sdwa v[234:235], v110 src0_sel:WORD_1
	v_pk_fma_f32 v[224:225], v[58:59], v[232:233], v[224:225] op_sel_hi:[0,1,1]
	v_pk_fma_f32 v[226:227], v[58:59], v[234:235], v[226:227] op_sel_hi:[0,1,1]
	v_cvt_pk_f32_fp8_e32 v[236:237], v111
	v_cvt_pk_f32_fp8_sdwa v[238:239], v111 src0_sel:WORD_1
	v_pk_fma_f32 v[228:229], v[58:59], v[236:237], v[228:229] op_sel_hi:[0,1,1]
	v_pk_fma_f32 v[230:231], v[58:59], v[238:239], v[230:231] op_sel_hi:[0,1,1]
	s_waitcnt vmcnt(24)
	v_cvt_pk_f32_fp8_e32 v[232:233], v112
	v_cvt_pk_f32_fp8_sdwa v[234:235], v112 src0_sel:WORD_1
	v_pk_fma_f32 v[216:217], v[58:59], v[232:233], v[216:217] op_sel:[1,0,0]
	v_pk_fma_f32 v[218:219], v[58:59], v[234:235], v[218:219] op_sel:[1,0,0]
	v_cvt_pk_f32_fp8_e32 v[236:237], v113
	v_cvt_pk_f32_fp8_sdwa v[238:239], v113 src0_sel:WORD_1
	v_pk_fma_f32 v[220:221], v[58:59], v[236:237], v[220:221] op_sel:[1,0,0]
	v_pk_fma_f32 v[222:223], v[58:59], v[238:239], v[222:223] op_sel:[1,0,0]
	v_cvt_pk_f32_fp8_e32 v[232:233], v114
	v_cvt_pk_f32_fp8_sdwa v[234:235], v114 src0_sel:WORD_1
	v_pk_fma_f32 v[224:225], v[58:59], v[232:233], v[224:225] op_sel:[1,0,0]
	v_pk_fma_f32 v[226:227], v[58:59], v[234:235], v[226:227] op_sel:[1,0,0]
	v_cvt_pk_f32_fp8_e32 v[236:237], v115
	v_cvt_pk_f32_fp8_sdwa v[238:239], v115 src0_sel:WORD_1
	v_pk_fma_f32 v[228:229], v[58:59], v[236:237], v[228:229] op_sel:[1,0,0]
	v_pk_fma_f32 v[230:231], v[58:59], v[238:239], v[230:231] op_sel:[1,0,0]
	s_waitcnt vmcnt(23)
	v_cvt_pk_f32_fp8_e32 v[232:233], v116
	v_cvt_pk_f32_fp8_sdwa v[234:235], v116 src0_sel:WORD_1
	v_pk_fma_f32 v[216:217], v[60:61], v[232:233], v[216:217] op_sel_hi:[0,1,1]
	v_pk_fma_f32 v[218:219], v[60:61], v[234:235], v[218:219] op_sel_hi:[0,1,1]
	v_cvt_pk_f32_fp8_e32 v[236:237], v117
	v_cvt_pk_f32_fp8_sdwa v[238:239], v117 src0_sel:WORD_1
	v_pk_fma_f32 v[220:221], v[60:61], v[236:237], v[220:221] op_sel_hi:[0,1,1]
	v_pk_fma_f32 v[222:223], v[60:61], v[238:239], v[222:223] op_sel_hi:[0,1,1]
	v_cvt_pk_f32_fp8_e32 v[232:233], v118
	v_cvt_pk_f32_fp8_sdwa v[234:235], v118 src0_sel:WORD_1
	v_pk_fma_f32 v[224:225], v[60:61], v[232:233], v[224:225] op_sel_hi:[0,1,1]
	v_pk_fma_f32 v[226:227], v[60:61], v[234:235], v[226:227] op_sel_hi:[0,1,1]
	v_cvt_pk_f32_fp8_e32 v[236:237], v119
	v_cvt_pk_f32_fp8_sdwa v[238:239], v119 src0_sel:WORD_1
	v_pk_fma_f32 v[228:229], v[60:61], v[236:237], v[228:229] op_sel_hi:[0,1,1]
	v_pk_fma_f32 v[230:231], v[60:61], v[238:239], v[230:231] op_sel_hi:[0,1,1]
	s_waitcnt vmcnt(22)
	v_cvt_pk_f32_fp8_e32 v[232:233], v120
	v_cvt_pk_f32_fp8_sdwa v[234:235], v120 src0_sel:WORD_1
	v_pk_fma_f32 v[216:217], v[60:61], v[232:233], v[216:217] op_sel:[1,0,0]
	v_pk_fma_f32 v[218:219], v[60:61], v[234:235], v[218:219] op_sel:[1,0,0]
	v_cvt_pk_f32_fp8_e32 v[236:237], v121
	v_cvt_pk_f32_fp8_sdwa v[238:239], v121 src0_sel:WORD_1
	v_pk_fma_f32 v[220:221], v[60:61], v[236:237], v[220:221] op_sel:[1,0,0]
	v_pk_fma_f32 v[222:223], v[60:61], v[238:239], v[222:223] op_sel:[1,0,0]
	v_cvt_pk_f32_fp8_e32 v[232:233], v122
	v_cvt_pk_f32_fp8_sdwa v[234:235], v122 src0_sel:WORD_1
	v_pk_fma_f32 v[224:225], v[60:61], v[232:233], v[224:225] op_sel:[1,0,0]
	v_pk_fma_f32 v[226:227], v[60:61], v[234:235], v[226:227] op_sel:[1,0,0]
	v_cvt_pk_f32_fp8_e32 v[236:237], v123
	v_cvt_pk_f32_fp8_sdwa v[238:239], v123 src0_sel:WORD_1
	v_pk_fma_f32 v[228:229], v[60:61], v[236:237], v[228:229] op_sel:[1,0,0]
	v_pk_fma_f32 v[230:231], v[60:61], v[238:239], v[230:231] op_sel:[1,0,0]
	s_waitcnt vmcnt(21)
	v_cvt_pk_f32_fp8_e32 v[232:233], v124
	v_cvt_pk_f32_fp8_sdwa v[234:235], v124 src0_sel:WORD_1
	v_pk_fma_f32 v[216:217], v[62:63], v[232:233], v[216:217] op_sel_hi:[0,1,1]
	v_pk_fma_f32 v[218:219], v[62:63], v[234:235], v[218:219] op_sel_hi:[0,1,1]
	v_cvt_pk_f32_fp8_e32 v[236:237], v125
	v_cvt_pk_f32_fp8_sdwa v[238:239], v125 src0_sel:WORD_1
	v_pk_fma_f32 v[220:221], v[62:63], v[236:237], v[220:221] op_sel_hi:[0,1,1]
	v_pk_fma_f32 v[222:223], v[62:63], v[238:239], v[222:223] op_sel_hi:[0,1,1]
	v_cvt_pk_f32_fp8_e32 v[232:233], v126
	v_cvt_pk_f32_fp8_sdwa v[234:235], v126 src0_sel:WORD_1
	v_pk_fma_f32 v[224:225], v[62:63], v[232:233], v[224:225] op_sel_hi:[0,1,1]
	v_pk_fma_f32 v[226:227], v[62:63], v[234:235], v[226:227] op_sel_hi:[0,1,1]
	v_cvt_pk_f32_fp8_e32 v[236:237], v127
	v_cvt_pk_f32_fp8_sdwa v[238:239], v127 src0_sel:WORD_1
	v_pk_fma_f32 v[228:229], v[62:63], v[236:237], v[228:229] op_sel_hi:[0,1,1]
	v_pk_fma_f32 v[230:231], v[62:63], v[238:239], v[230:231] op_sel_hi:[0,1,1]
	s_waitcnt vmcnt(20)
	v_cvt_pk_f32_fp8_e32 v[232:233], v128
	v_cvt_pk_f32_fp8_sdwa v[234:235], v128 src0_sel:WORD_1
	v_pk_fma_f32 v[216:217], v[62:63], v[232:233], v[216:217] op_sel:[1,0,0]
	v_pk_fma_f32 v[218:219], v[62:63], v[234:235], v[218:219] op_sel:[1,0,0]
	v_cvt_pk_f32_fp8_e32 v[236:237], v129
	v_cvt_pk_f32_fp8_sdwa v[238:239], v129 src0_sel:WORD_1
	v_pk_fma_f32 v[220:221], v[62:63], v[236:237], v[220:221] op_sel:[1,0,0]
	v_pk_fma_f32 v[222:223], v[62:63], v[238:239], v[222:223] op_sel:[1,0,0]
	v_cvt_pk_f32_fp8_e32 v[232:233], v130
	v_cvt_pk_f32_fp8_sdwa v[234:235], v130 src0_sel:WORD_1
	v_pk_fma_f32 v[224:225], v[62:63], v[232:233], v[224:225] op_sel:[1,0,0]
	v_pk_fma_f32 v[226:227], v[62:63], v[234:235], v[226:227] op_sel:[1,0,0]
	v_cvt_pk_f32_fp8_e32 v[236:237], v131
	v_cvt_pk_f32_fp8_sdwa v[238:239], v131 src0_sel:WORD_1
	v_pk_fma_f32 v[228:229], v[62:63], v[236:237], v[228:229] op_sel:[1,0,0]
	v_pk_fma_f32 v[230:231], v[62:63], v[238:239], v[230:231] op_sel:[1,0,0]
	s_waitcnt vmcnt(19)
; DI f2_t cvt8lo(unsigned w) { return __builtin_amdgcn_cvt_pk_f32_fp8(w, false); }
; DI f2_t cvt8hi(unsigned w) { return __builtin_amdgcn_cvt_pk_f32_fp8(w, true); }
; DI void wave_lds_sync() { asm volatile("s_waitcnt lgkmcnt(0)" ::: "memory"); __builtin_amdgcn_wave_barrier(); }
; DI void phase11(const Params& p, char* smem, int rep) {
;     ...
;       wave_lds_sync();
;       lw[(lane & 3) * 32 + (lane >> 2)] = i0; lw[(lane & 3) * 32 + 16 + (lane >> 2)] = i1;
;       lf[(lane & 3) * 32 + (lane >> 2)] = a0; lf[(lane & 3) * 32 + 16 + (lane >> 2)] = a1;
;       wave_lds_sync();
;     ...
;         for (int k = 0; k < 16; ++k) rows[k] = *(const u32x4*)(vb + (size_t)ida[k] * 2048);
; #pragma unroll
;         for (int k = 0; k < 16; ++k) {
;           const f2_t a2 = {aa[k], aa[k]};
; #pragma unroll
;           for (int d = 0; d < 4; ++d) { const unsigned ww = rows[k][d]; o[2 * d] += a2 * cvt8lo(ww); o[2 * d + 1] += a2 * cvt8hi(ww); }
;         }
	v_cvt_pk_f32_fp8_e32 v[232:233], v132
	v_cvt_pk_f32_fp8_sdwa v[234:235], v132 src0_sel:WORD_1
	v_pk_fma_f32 v[216:217], v[64:65], v[232:233], v[216:217] op_sel_hi:[0,1,1]
	v_pk_fma_f32 v[218:219], v[64:65], v[234:235], v[218:219] op_sel_hi:[0,1,1]
	v_cvt_pk_f32_fp8_e32 v[236:237], v133
	v_cvt_pk_f32_fp8_sdwa v[238:239], v133 src0_sel:WORD_1
	v_pk_fma_f32 v[220:221], v[64:65], v[236:237], v[220:221] op_sel_hi:[0,1,1]
	v_pk_fma_f32 v[222:223], v[64:65], v[238:239], v[222:223] op_sel_hi:[0,1,1]
	v_cvt_pk_f32_fp8_e32 v[232:233], v134
	v_cvt_pk_f32_fp8_sdwa v[234:235], v134 src0_sel:WORD_1
	v_pk_fma_f32 v[224:225], v[64:65], v[232:233], v[224:225] op_sel_hi:[0,1,1]
	v_pk_fma_f32 v[226:227], v[64:65], v[234:235], v[226:227] op_sel_hi:[0,1,1]
	v_cvt_pk_f32_fp8_e32 v[236:237], v135
	v_cvt_pk_f32_fp8_sdwa v[238:239], v135 src0_sel:WORD_1
	v_pk_fma_f32 v[228:229], v[64:65], v[236:237], v[228:229] op_sel_hi:[0,1,1]
	v_pk_fma_f32 v[230:231], v[64:65], v[238:239], v[230:231] op_sel_hi:[0,1,1]
	s_waitcnt vmcnt(18)
	v_cvt_pk_f32_fp8_e32 v[232:233], v136
	v_cvt_pk_f32_fp8_sdwa v[234:235], v136 src0_sel:WORD_1
	v_pk_fma_f32 v[216:217], v[64:65], v[232:233], v[216:217] op_sel:[1,0,0]
	v_pk_fma_f32 v[218:219], v[64:65], v[234:235], v[218:219] op_sel:[1,0,0]
	v_cvt_pk_f32_fp8_e32 v[236:237], v137
	v_cvt_pk_f32_fp8_sdwa v[238:239], v137 src0_sel:WORD_1
	v_pk_fma_f32 v[220:221], v[64:65], v[236:237], v[220:221] op_sel:[1,0,0]
	v_pk_fma_f32 v[222:223], v[64:65], v[238:239], v[222:223] op_sel:[1,0,0]
	v_cvt_pk_f32_fp8_e32 v[232:233], v138
	v_cvt_pk_f32_fp8_sdwa v[234:235], v138 src0_sel:WORD_1
	v_pk_fma_f32 v[224:225], v[64:65], v[232:233], v[224:225] op_sel:[1,0,0]
	v_pk_fma_f32 v[226:227], v[64:65], v[234:235], v[226:227] op_sel:[1,0,0]
	v_cvt_pk_f32_fp8_e32 v[236:237], v139
	v_cvt_pk_f32_fp8_sdwa v[238:239], v139 src0_sel:WORD_1
	v_pk_fma_f32 v[228:229], v[64:65], v[236:237], v[228:229] op_sel:[1,0,0]
	v_pk_fma_f32 v[230:231], v[64:65], v[238:239], v[230:231] op_sel:[1,0,0]
	s_waitcnt vmcnt(17)
	v_cvt_pk_f32_fp8_e32 v[232:233], v140
	v_cvt_pk_f32_fp8_sdwa v[234:235], v140 src0_sel:WORD_1
	v_pk_fma_f32 v[216:217], v[66:67], v[232:233], v[216:217] op_sel_hi:[0,1,1]
	v_pk_fma_f32 v[218:219], v[66:67], v[234:235], v[218:219] op_sel_hi:[0,1,1]
	v_cvt_pk_f32_fp8_e32 v[236:237], v141
	v_cvt_pk_f32_fp8_sdwa v[238:239], v141 src0_sel:WORD_1
	v_pk_fma_f32 v[220:221], v[66:67], v[236:237], v[220:221] op_sel_hi:[0,1,1]
	v_pk_fma_f32 v[222:223], v[66:67], v[238:239], v[222:223] op_sel_hi:[0,1,1]
	v_cvt_pk_f32_fp8_e32 v[232:233], v142
	v_cvt_pk_f32_fp8_sdwa v[234:235], v142 src0_sel:WORD_1
	v_pk_fma_f32 v[224:225], v[66:67], v[232:233], v[224:225] op_sel_hi:[0,1,1]
	v_pk_fma_f32 v[226:227], v[66:67], v[234:235], v[226:227] op_sel_hi:[0,1,1]
	v_cvt_pk_f32_fp8_e32 v[236:237], v143
	v_cvt_pk_f32_fp8_sdwa v[238:239], v143 src0_sel:WORD_1
	v_pk_fma_f32 v[228:229], v[66:67], v[236:237], v[228:229] op_sel_hi:[0,1,1]
	v_pk_fma_f32 v[230:231], v[66:67], v[238:239], v[230:231] op_sel_hi:[0,1,1]
	s_waitcnt vmcnt(16)
	v_cvt_pk_f32_fp8_e32 v[232:233], v144
	v_cvt_pk_f32_fp8_sdwa v[234:235], v144 src0_sel:WORD_1
	v_pk_fma_f32 v[216:217], v[66:67], v[232:233], v[216:217] op_sel:[1,0,0]
	v_pk_fma_f32 v[218:219], v[66:67], v[234:235], v[218:219] op_sel:[1,0,0]
	v_cvt_pk_f32_fp8_e32 v[236:237], v145
	v_cvt_pk_f32_fp8_sdwa v[238:239], v145 src0_sel:WORD_1
	v_pk_fma_f32 v[220:221], v[66:67], v[236:237], v[220:221] op_sel:[1,0,0]
	v_pk_fma_f32 v[222:223], v[66:67], v[238:239], v[222:223] op_sel:[1,0,0]
	v_cvt_pk_f32_fp8_e32 v[232:233], v146
	v_cvt_pk_f32_fp8_sdwa v[234:235], v146 src0_sel:WORD_1
	v_pk_fma_f32 v[224:225], v[66:67], v[232:233], v[224:225] op_sel:[1,0,0]
	v_pk_fma_f32 v[226:227], v[66:67], v[234:235], v[226:227] op_sel:[1,0,0]
	v_cvt_pk_f32_fp8_e32 v[236:237], v147
	v_cvt_pk_f32_fp8_sdwa v[238:239], v147 src0_sel:WORD_1
	v_pk_fma_f32 v[228:229], v[66:67], v[236:237], v[228:229] op_sel:[1,0,0]
	v_pk_fma_f32 v[230:231], v[66:67], v[238:239], v[230:231] op_sel:[1,0,0]
	ds_write2_b32 v5, v10, v11 offset0:4 offset1:20
	ds_write2_b32 v5, v12, v13 offset0:132 offset1:148
	s_waitcnt lgkmcnt(0)
	ds_read_b128 v[20:23], v6 offset:16
	ds_read_b128 v[24:27], v6 offset:32
	ds_read_b128 v[28:31], v6 offset:48
	ds_read_b128 v[32:35], v6 offset:64
	ds_read_b128 v[36:39], v6 offset:80
	ds_read_b128 v[40:43], v6 offset:96
	ds_read_b128 v[44:47], v6 offset:112
	ds_read_b128 v[48:51], v6 offset:128
	s_waitcnt vmcnt(15)
	v_cvt_pk_f32_fp8_e32 v[232:233], v148
	v_cvt_pk_f32_fp8_sdwa v[234:235], v148 src0_sel:WORD_1
	v_pk_fma_f32 v[216:217], v[68:69], v[232:233], v[216:217] op_sel_hi:[0,1,1]
	v_pk_fma_f32 v[218:219], v[68:69], v[234:235], v[218:219] op_sel_hi:[0,1,1]
	v_cvt_pk_f32_fp8_e32 v[236:237], v149
	v_cvt_pk_f32_fp8_sdwa v[238:239], v149 src0_sel:WORD_1
	v_pk_fma_f32 v[220:221], v[68:69], v[236:237], v[220:221] op_sel_hi:[0,1,1]
	v_pk_fma_f32 v[222:223], v[68:69], v[238:239], v[222:223] op_sel_hi:[0,1,1]
	v_cvt_pk_f32_fp8_e32 v[232:233], v150
	v_cvt_pk_f32_fp8_sdwa v[234:235], v150 src0_sel:WORD_1
	v_pk_fma_f32 v[224:225], v[68:69], v[232:233], v[224:225] op_sel_hi:[0,1,1]
	v_pk_fma_f32 v[226:227], v[68:69], v[234:235], v[226:227] op_sel_hi:[0,1,1]
	v_cvt_pk_f32_fp8_e32 v[236:237], v151
	v_cvt_pk_f32_fp8_sdwa v[238:239], v151 src0_sel:WORD_1
	v_pk_fma_f32 v[228:229], v[68:69], v[236:237], v[228:229] op_sel_hi:[0,1,1]
	v_pk_fma_f32 v[230:231], v[68:69], v[238:239], v[230:231] op_sel_hi:[0,1,1]
	s_waitcnt vmcnt(14)
; DI f2_t cvt8lo(unsigned w) { return __builtin_amdgcn_cvt_pk_f32_fp8(w, false); }
; DI f2_t cvt8hi(unsigned w) { return __builtin_amdgcn_cvt_pk_f32_fp8(w, true); }
; DI void phase11(const Params& p, char* smem, int rep) {
;     ...
;         for (int k = 0; k < 16; ++k) rows[k] = *(const u32x4*)(vb + (size_t)ida[k] * 2048);
; #pragma unroll
;         for (int k = 0; k < 16; ++k) {
;           const f2_t a2 = {aa[k], aa[k]};
; #pragma unroll
;           for (int d = 0; d < 4; ++d) { const unsigned ww = rows[k][d]; o[2 * d] += a2 * cvt8lo(ww); o[2 * d + 1] += a2 * cvt8hi(ww); }
;         }
	v_cvt_pk_f32_fp8_e32 v[232:233], v152
	v_cvt_pk_f32_fp8_sdwa v[234:235], v152 src0_sel:WORD_1
	v_pk_fma_f32 v[216:217], v[68:69], v[232:233], v[216:217] op_sel:[1,0,0]
	v_pk_fma_f32 v[218:219], v[68:69], v[234:235], v[218:219] op_sel:[1,0,0]
	v_cvt_pk_f32_fp8_e32 v[236:237], v153
	v_cvt_pk_f32_fp8_sdwa v[238:239], v153 src0_sel:WORD_1
	v_pk_fma_f32 v[220:221], v[68:69], v[236:237], v[220:221] op_sel:[1,0,0]
	v_pk_fma_f32 v[222:223], v[68:69], v[238:239], v[222:223] op_sel:[1,0,0]
	v_cvt_pk_f32_fp8_e32 v[232:233], v154
	v_cvt_pk_f32_fp8_sdwa v[234:235], v154 src0_sel:WORD_1
	v_pk_fma_f32 v[224:225], v[68:69], v[232:233], v[224:225] op_sel:[1,0,0]
	v_pk_fma_f32 v[226:227], v[68:69], v[234:235], v[226:227] op_sel:[1,0,0]
	v_cvt_pk_f32_fp8_e32 v[236:237], v155
	v_cvt_pk_f32_fp8_sdwa v[238:239], v155 src0_sel:WORD_1
	v_pk_fma_f32 v[228:229], v[68:69], v[236:237], v[228:229] op_sel:[1,0,0]
	v_pk_fma_f32 v[230:231], v[68:69], v[238:239], v[230:231] op_sel:[1,0,0]
	s_waitcnt vmcnt(13)
	v_cvt_pk_f32_fp8_e32 v[232:233], v156
	v_cvt_pk_f32_fp8_sdwa v[234:235], v156 src0_sel:WORD_1
	v_pk_fma_f32 v[216:217], v[70:71], v[232:233], v[216:217] op_sel_hi:[0,1,1]
	v_pk_fma_f32 v[218:219], v[70:71], v[234:235], v[218:219] op_sel_hi:[0,1,1]
	v_cvt_pk_f32_fp8_e32 v[236:237], v157
	v_cvt_pk_f32_fp8_sdwa v[238:239], v157 src0_sel:WORD_1
	v_pk_fma_f32 v[220:221], v[70:71], v[236:237], v[220:221] op_sel_hi:[0,1,1]
	v_pk_fma_f32 v[222:223], v[70:71], v[238:239], v[222:223] op_sel_hi:[0,1,1]
	v_cvt_pk_f32_fp8_e32 v[232:233], v158
	v_cvt_pk_f32_fp8_sdwa v[234:235], v158 src0_sel:WORD_1
	v_pk_fma_f32 v[224:225], v[70:71], v[232:233], v[224:225] op_sel_hi:[0,1,1]
	v_pk_fma_f32 v[226:227], v[70:71], v[234:235], v[226:227] op_sel_hi:[0,1,1]
	v_cvt_pk_f32_fp8_e32 v[236:237], v159
	v_cvt_pk_f32_fp8_sdwa v[238:239], v159 src0_sel:WORD_1
	v_pk_fma_f32 v[228:229], v[70:71], v[236:237], v[228:229] op_sel_hi:[0,1,1]
	v_pk_fma_f32 v[230:231], v[70:71], v[238:239], v[230:231] op_sel_hi:[0,1,1]
	s_waitcnt vmcnt(12)
	v_cvt_pk_f32_fp8_e32 v[232:233], v160
	v_cvt_pk_f32_fp8_sdwa v[234:235], v160 src0_sel:WORD_1
	v_pk_fma_f32 v[216:217], v[70:71], v[232:233], v[216:217] op_sel:[1,0,0]
	v_pk_fma_f32 v[218:219], v[70:71], v[234:235], v[218:219] op_sel:[1,0,0]
	v_cvt_pk_f32_fp8_e32 v[236:237], v161
	v_cvt_pk_f32_fp8_sdwa v[238:239], v161 src0_sel:WORD_1
	v_pk_fma_f32 v[220:221], v[70:71], v[236:237], v[220:221] op_sel:[1,0,0]
	v_pk_fma_f32 v[222:223], v[70:71], v[238:239], v[222:223] op_sel:[1,0,0]
	v_cvt_pk_f32_fp8_e32 v[232:233], v162
	v_cvt_pk_f32_fp8_sdwa v[234:235], v162 src0_sel:WORD_1
	v_pk_fma_f32 v[224:225], v[70:71], v[232:233], v[224:225] op_sel:[1,0,0]
	v_pk_fma_f32 v[226:227], v[70:71], v[234:235], v[226:227] op_sel:[1,0,0]
	v_cvt_pk_f32_fp8_e32 v[236:237], v163
	v_cvt_pk_f32_fp8_sdwa v[238:239], v163 src0_sel:WORD_1
	v_pk_fma_f32 v[228:229], v[70:71], v[236:237], v[228:229] op_sel:[1,0,0]
	v_pk_fma_f32 v[230:231], v[70:71], v[238:239], v[230:231] op_sel:[1,0,0]
	s_waitcnt vmcnt(11)
	v_cvt_pk_f32_fp8_e32 v[232:233], v164
	v_cvt_pk_f32_fp8_sdwa v[234:235], v164 src0_sel:WORD_1
	v_pk_fma_f32 v[216:217], v[72:73], v[232:233], v[216:217] op_sel_hi:[0,1,1]
	v_pk_fma_f32 v[218:219], v[72:73], v[234:235], v[218:219] op_sel_hi:[0,1,1]
	v_cvt_pk_f32_fp8_e32 v[236:237], v165
	v_cvt_pk_f32_fp8_sdwa v[238:239], v165 src0_sel:WORD_1
	v_pk_fma_f32 v[220:221], v[72:73], v[236:237], v[220:221] op_sel_hi:[0,1,1]
	v_pk_fma_f32 v[222:223], v[72:73], v[238:239], v[222:223] op_sel_hi:[0,1,1]
	v_cvt_pk_f32_fp8_e32 v[232:233], v166
	v_cvt_pk_f32_fp8_sdwa v[234:235], v166 src0_sel:WORD_1
	v_pk_fma_f32 v[224:225], v[72:73], v[232:233], v[224:225] op_sel_hi:[0,1,1]
	v_pk_fma_f32 v[226:227], v[72:73], v[234:235], v[226:227] op_sel_hi:[0,1,1]
	v_cvt_pk_f32_fp8_e32 v[236:237], v167
	v_cvt_pk_f32_fp8_sdwa v[238:239], v167 src0_sel:WORD_1
	v_pk_fma_f32 v[228:229], v[72:73], v[236:237], v[228:229] op_sel_hi:[0,1,1]
	v_pk_fma_f32 v[230:231], v[72:73], v[238:239], v[230:231] op_sel_hi:[0,1,1]
	s_waitcnt vmcnt(10)
	v_cvt_pk_f32_fp8_e32 v[232:233], v168
	v_cvt_pk_f32_fp8_sdwa v[234:235], v168 src0_sel:WORD_1
	v_pk_fma_f32 v[216:217], v[72:73], v[232:233], v[216:217] op_sel:[1,0,0]
	v_pk_fma_f32 v[218:219], v[72:73], v[234:235], v[218:219] op_sel:[1,0,0]
	v_cvt_pk_f32_fp8_e32 v[236:237], v169
	v_cvt_pk_f32_fp8_sdwa v[238:239], v169 src0_sel:WORD_1
	v_pk_fma_f32 v[220:221], v[72:73], v[236:237], v[220:221] op_sel:[1,0,0]
	v_pk_fma_f32 v[222:223], v[72:73], v[238:239], v[222:223] op_sel:[1,0,0]
	v_cvt_pk_f32_fp8_e32 v[232:233], v170
	v_cvt_pk_f32_fp8_sdwa v[234:235], v170 src0_sel:WORD_1
	v_pk_fma_f32 v[224:225], v[72:73], v[232:233], v[224:225] op_sel:[1,0,0]
	v_pk_fma_f32 v[226:227], v[72:73], v[234:235], v[226:227] op_sel:[1,0,0]
	v_cvt_pk_f32_fp8_e32 v[236:237], v171
	v_cvt_pk_f32_fp8_sdwa v[238:239], v171 src0_sel:WORD_1
	v_pk_fma_f32 v[228:229], v[72:73], v[236:237], v[228:229] op_sel:[1,0,0]
	v_pk_fma_f32 v[230:231], v[72:73], v[238:239], v[230:231] op_sel:[1,0,0]
	s_waitcnt vmcnt(9)
	v_cvt_pk_f32_fp8_e32 v[232:233], v172
	v_cvt_pk_f32_fp8_sdwa v[234:235], v172 src0_sel:WORD_1
	v_pk_fma_f32 v[216:217], v[74:75], v[232:233], v[216:217] op_sel_hi:[0,1,1]
	v_pk_fma_f32 v[218:219], v[74:75], v[234:235], v[218:219] op_sel_hi:[0,1,1]
	v_cvt_pk_f32_fp8_e32 v[236:237], v173
	v_cvt_pk_f32_fp8_sdwa v[238:239], v173 src0_sel:WORD_1
	v_pk_fma_f32 v[220:221], v[74:75], v[236:237], v[220:221] op_sel_hi:[0,1,1]
	v_pk_fma_f32 v[222:223], v[74:75], v[238:239], v[222:223] op_sel_hi:[0,1,1]
	v_cvt_pk_f32_fp8_e32 v[232:233], v174
	v_cvt_pk_f32_fp8_sdwa v[234:235], v174 src0_sel:WORD_1
	v_pk_fma_f32 v[224:225], v[74:75], v[232:233], v[224:225] op_sel_hi:[0,1,1]
	v_pk_fma_f32 v[226:227], v[74:75], v[234:235], v[226:227] op_sel_hi:[0,1,1]
	v_cvt_pk_f32_fp8_e32 v[236:237], v175
	v_cvt_pk_f32_fp8_sdwa v[238:239], v175 src0_sel:WORD_1
	v_pk_fma_f32 v[228:229], v[74:75], v[236:237], v[228:229] op_sel_hi:[0,1,1]
	v_pk_fma_f32 v[230:231], v[74:75], v[238:239], v[230:231] op_sel_hi:[0,1,1]
	s_waitcnt vmcnt(8)
; DI f2_t cvt8lo(unsigned w) { return __builtin_amdgcn_cvt_pk_f32_fp8(w, false); }
; DI f2_t cvt8hi(unsigned w) { return __builtin_amdgcn_cvt_pk_f32_fp8(w, true); }
; DI void phase11(const Params& p, char* smem, int rep) {
;     ...
;         for (int k = 0; k < 16; ++k) rows[k] = *(const u32x4*)(vb + (size_t)ida[k] * 2048);
; #pragma unroll
;         for (int k = 0; k < 16; ++k) {
;           const f2_t a2 = {aa[k], aa[k]};
; #pragma unroll
;           for (int d = 0; d < 4; ++d) { const unsigned ww = rows[k][d]; o[2 * d] += a2 * cvt8lo(ww); o[2 * d + 1] += a2 * cvt8hi(ww); }
;         }
	v_cvt_pk_f32_fp8_e32 v[232:233], v176
	v_cvt_pk_f32_fp8_sdwa v[234:235], v176 src0_sel:WORD_1
	v_pk_fma_f32 v[216:217], v[74:75], v[232:233], v[216:217] op_sel:[1,0,0]
	v_pk_fma_f32 v[218:219], v[74:75], v[234:235], v[218:219] op_sel:[1,0,0]
	v_cvt_pk_f32_fp8_e32 v[236:237], v177
	v_cvt_pk_f32_fp8_sdwa v[238:239], v177 src0_sel:WORD_1
	v_pk_fma_f32 v[220:221], v[74:75], v[236:237], v[220:221] op_sel:[1,0,0]
	v_pk_fma_f32 v[222:223], v[74:75], v[238:239], v[222:223] op_sel:[1,0,0]
	v_cvt_pk_f32_fp8_e32 v[232:233], v178
	v_cvt_pk_f32_fp8_sdwa v[234:235], v178 src0_sel:WORD_1
	v_pk_fma_f32 v[224:225], v[74:75], v[232:233], v[224:225] op_sel:[1,0,0]
	v_pk_fma_f32 v[226:227], v[74:75], v[234:235], v[226:227] op_sel:[1,0,0]
	v_cvt_pk_f32_fp8_e32 v[236:237], v179
	v_cvt_pk_f32_fp8_sdwa v[238:239], v179 src0_sel:WORD_1
	v_pk_fma_f32 v[228:229], v[74:75], v[236:237], v[228:229] op_sel:[1,0,0]
	v_pk_fma_f32 v[230:231], v[74:75], v[238:239], v[230:231] op_sel:[1,0,0]
	s_waitcnt vmcnt(7)
	v_cvt_pk_f32_fp8_e32 v[232:233], v180
	v_cvt_pk_f32_fp8_sdwa v[234:235], v180 src0_sel:WORD_1
	v_pk_fma_f32 v[216:217], v[76:77], v[232:233], v[216:217] op_sel_hi:[0,1,1]
	v_pk_fma_f32 v[218:219], v[76:77], v[234:235], v[218:219] op_sel_hi:[0,1,1]
	v_cvt_pk_f32_fp8_e32 v[236:237], v181
	v_cvt_pk_f32_fp8_sdwa v[238:239], v181 src0_sel:WORD_1
	v_pk_fma_f32 v[220:221], v[76:77], v[236:237], v[220:221] op_sel_hi:[0,1,1]
	v_pk_fma_f32 v[222:223], v[76:77], v[238:239], v[222:223] op_sel_hi:[0,1,1]
	v_cvt_pk_f32_fp8_e32 v[232:233], v182
	v_cvt_pk_f32_fp8_sdwa v[234:235], v182 src0_sel:WORD_1
	v_pk_fma_f32 v[224:225], v[76:77], v[232:233], v[224:225] op_sel_hi:[0,1,1]
	v_pk_fma_f32 v[226:227], v[76:77], v[234:235], v[226:227] op_sel_hi:[0,1,1]
	v_cvt_pk_f32_fp8_e32 v[236:237], v183
	v_cvt_pk_f32_fp8_sdwa v[238:239], v183 src0_sel:WORD_1
	v_pk_fma_f32 v[228:229], v[76:77], v[236:237], v[228:229] op_sel_hi:[0,1,1]
	v_pk_fma_f32 v[230:231], v[76:77], v[238:239], v[230:231] op_sel_hi:[0,1,1]
	s_waitcnt vmcnt(6)
	v_cvt_pk_f32_fp8_e32 v[232:233], v184
	v_cvt_pk_f32_fp8_sdwa v[234:235], v184 src0_sel:WORD_1
	v_pk_fma_f32 v[216:217], v[76:77], v[232:233], v[216:217] op_sel:[1,0,0]
	v_pk_fma_f32 v[218:219], v[76:77], v[234:235], v[218:219] op_sel:[1,0,0]
	v_cvt_pk_f32_fp8_e32 v[236:237], v185
	v_cvt_pk_f32_fp8_sdwa v[238:239], v185 src0_sel:WORD_1
	v_pk_fma_f32 v[220:221], v[76:77], v[236:237], v[220:221] op_sel:[1,0,0]
	v_pk_fma_f32 v[222:223], v[76:77], v[238:239], v[222:223] op_sel:[1,0,0]
	v_cvt_pk_f32_fp8_e32 v[232:233], v186
	v_cvt_pk_f32_fp8_sdwa v[234:235], v186 src0_sel:WORD_1
	v_pk_fma_f32 v[224:225], v[76:77], v[232:233], v[224:225] op_sel:[1,0,0]
	v_pk_fma_f32 v[226:227], v[76:77], v[234:235], v[226:227] op_sel:[1,0,0]
	v_cvt_pk_f32_fp8_e32 v[236:237], v187
	v_cvt_pk_f32_fp8_sdwa v[238:239], v187 src0_sel:WORD_1
	v_pk_fma_f32 v[228:229], v[76:77], v[236:237], v[228:229] op_sel:[1,0,0]
	v_pk_fma_f32 v[230:231], v[76:77], v[238:239], v[230:231] op_sel:[1,0,0]
	s_waitcnt vmcnt(5)
	v_cvt_pk_f32_fp8_e32 v[232:233], v190
	v_cvt_pk_f32_fp8_sdwa v[234:235], v190 src0_sel:WORD_1
	v_pk_fma_f32 v[216:217], v[78:79], v[232:233], v[216:217] op_sel_hi:[0,1,1]
	v_pk_fma_f32 v[218:219], v[78:79], v[234:235], v[218:219] op_sel_hi:[0,1,1]
	v_cvt_pk_f32_fp8_e32 v[236:237], v191
	v_cvt_pk_f32_fp8_sdwa v[238:239], v191 src0_sel:WORD_1
	v_pk_fma_f32 v[220:221], v[78:79], v[236:237], v[220:221] op_sel_hi:[0,1,1]
	v_pk_fma_f32 v[222:223], v[78:79], v[238:239], v[222:223] op_sel_hi:[0,1,1]
	v_cvt_pk_f32_fp8_e32 v[232:233], v192
	v_cvt_pk_f32_fp8_sdwa v[234:235], v192 src0_sel:WORD_1
	v_pk_fma_f32 v[224:225], v[78:79], v[232:233], v[224:225] op_sel_hi:[0,1,1]
	v_pk_fma_f32 v[226:227], v[78:79], v[234:235], v[226:227] op_sel_hi:[0,1,1]
	v_cvt_pk_f32_fp8_e32 v[236:237], v193
	v_cvt_pk_f32_fp8_sdwa v[238:239], v193 src0_sel:WORD_1
	v_pk_fma_f32 v[228:229], v[78:79], v[236:237], v[228:229] op_sel_hi:[0,1,1]
	v_pk_fma_f32 v[230:231], v[78:79], v[238:239], v[230:231] op_sel_hi:[0,1,1]
	s_waitcnt vmcnt(4)
	v_cvt_pk_f32_fp8_e32 v[232:233], v194
	v_cvt_pk_f32_fp8_sdwa v[234:235], v194 src0_sel:WORD_1
	v_pk_fma_f32 v[216:217], v[78:79], v[232:233], v[216:217] op_sel:[1,0,0]
	v_pk_fma_f32 v[218:219], v[78:79], v[234:235], v[218:219] op_sel:[1,0,0]
	v_cvt_pk_f32_fp8_e32 v[236:237], v195
	v_cvt_pk_f32_fp8_sdwa v[238:239], v195 src0_sel:WORD_1
	v_pk_fma_f32 v[220:221], v[78:79], v[236:237], v[220:221] op_sel:[1,0,0]
	v_pk_fma_f32 v[222:223], v[78:79], v[238:239], v[222:223] op_sel:[1,0,0]
	v_cvt_pk_f32_fp8_e32 v[232:233], v196
	v_cvt_pk_f32_fp8_sdwa v[234:235], v196 src0_sel:WORD_1
	v_pk_fma_f32 v[224:225], v[78:79], v[232:233], v[224:225] op_sel:[1,0,0]
	v_pk_fma_f32 v[226:227], v[78:79], v[234:235], v[226:227] op_sel:[1,0,0]
	v_cvt_pk_f32_fp8_e32 v[236:237], v197
	v_cvt_pk_f32_fp8_sdwa v[238:239], v197 src0_sel:WORD_1
	v_pk_fma_f32 v[228:229], v[78:79], v[236:237], v[228:229] op_sel:[1,0,0]
	v_pk_fma_f32 v[230:231], v[78:79], v[238:239], v[230:231] op_sel:[1,0,0]
	s_waitcnt vmcnt(3)
; DI unsigned pk2(float a, float b) { f2_t v = {a, b}; bf2_t r = __builtin_convertvector(v, bf2_t); return __builtin_bit_cast(unsigned, r); }
; DI f2_t cvt8lo(unsigned w) { return __builtin_amdgcn_cvt_pk_f32_fp8(w, false); }
; DI f2_t cvt8hi(unsigned w) { return __builtin_amdgcn_cvt_pk_f32_fp8(w, true); }
; DI void phase11(const Params& p, char* smem, int rep) {
;     ...
;     for (int t = 0; t < 4; ++t) {
;     ...
;         for (int k = 0; k < 16; ++k) rows[k] = *(const u32x4*)(vb + (size_t)ida[k] * 2048);
; #pragma unroll
;         for (int k = 0; k < 16; ++k) {
;           const f2_t a2 = {aa[k], aa[k]};
; #pragma unroll
;           for (int d = 0; d < 4; ++d) { const unsigned ww = rows[k][d]; o[2 * d] += a2 * cvt8lo(ww); o[2 * d + 1] += a2 * cvt8hi(ww); }
;         }
;       }
;       float ov[16];
; #pragma unroll
;       for (int d = 0; d < 4; ++d) { ov[4 * d] = o[2 * d].x; ov[4 * d + 1] = o[2 * d].y; ov[4 * d + 2] = o[2 * d + 1].x; ov[4 * d + 3] = o[2 * d + 1].y; }
;       float q8[8], q4[4];
; #pragma unroll
;       for (int k = 0; k < 8; ++k) q8[k] = (b5 ? ov[8 + k] : ov[k]) + __shfl_xor(b5 ? ov[k] : ov[8 + k], 32);
; #pragma unroll
;       for (int k = 0; k < 4; ++k) q4[k] = (b4 ? q8[4 + k] : q8[k]) + __shfl_xor(b4 ? q8[k] : q8[4 + k], 16);
;       *(uint2*)(OUTP + (size_t)tok * D_ + s * 256 + l15 * 16 + 8 * b5 + 4 * b4) = make_uint2(pk2(q4[0], q4[1]), pk2(q4[2], q4[3]));
;     }
	v_cvt_pk_f32_fp8_e32 v[232:233], v198
	v_cvt_pk_f32_fp8_sdwa v[234:235], v198 src0_sel:WORD_1
	v_pk_fma_f32 v[216:217], v[80:81], v[232:233], v[216:217] op_sel_hi:[0,1,1]
	v_pk_fma_f32 v[218:219], v[80:81], v[234:235], v[218:219] op_sel_hi:[0,1,1]
	v_cvt_pk_f32_fp8_e32 v[236:237], v199
	v_cvt_pk_f32_fp8_sdwa v[238:239], v199 src0_sel:WORD_1
	v_pk_fma_f32 v[220:221], v[80:81], v[236:237], v[220:221] op_sel_hi:[0,1,1]
	v_pk_fma_f32 v[222:223], v[80:81], v[238:239], v[222:223] op_sel_hi:[0,1,1]
	v_cvt_pk_f32_fp8_e32 v[232:233], v200
	v_cvt_pk_f32_fp8_sdwa v[234:235], v200 src0_sel:WORD_1
	v_pk_fma_f32 v[224:225], v[80:81], v[232:233], v[224:225] op_sel_hi:[0,1,1]
	v_pk_fma_f32 v[226:227], v[80:81], v[234:235], v[226:227] op_sel_hi:[0,1,1]
	v_cvt_pk_f32_fp8_e32 v[236:237], v201
	v_cvt_pk_f32_fp8_sdwa v[238:239], v201 src0_sel:WORD_1
	v_pk_fma_f32 v[228:229], v[80:81], v[236:237], v[228:229] op_sel_hi:[0,1,1]
	v_pk_fma_f32 v[230:231], v[80:81], v[238:239], v[230:231] op_sel_hi:[0,1,1]
	s_waitcnt vmcnt(2)
	v_cvt_pk_f32_fp8_e32 v[232:233], v202
	v_cvt_pk_f32_fp8_sdwa v[234:235], v202 src0_sel:WORD_1
	v_pk_fma_f32 v[216:217], v[80:81], v[232:233], v[216:217] op_sel:[1,0,0]
	v_pk_fma_f32 v[218:219], v[80:81], v[234:235], v[218:219] op_sel:[1,0,0]
	v_cvt_pk_f32_fp8_e32 v[236:237], v203
	v_cvt_pk_f32_fp8_sdwa v[238:239], v203 src0_sel:WORD_1
	v_pk_fma_f32 v[220:221], v[80:81], v[236:237], v[220:221] op_sel:[1,0,0]
	v_pk_fma_f32 v[222:223], v[80:81], v[238:239], v[222:223] op_sel:[1,0,0]
	v_cvt_pk_f32_fp8_e32 v[232:233], v204
	v_cvt_pk_f32_fp8_sdwa v[234:235], v204 src0_sel:WORD_1
	v_pk_fma_f32 v[224:225], v[80:81], v[232:233], v[224:225] op_sel:[1,0,0]
	v_pk_fma_f32 v[226:227], v[80:81], v[234:235], v[226:227] op_sel:[1,0,0]
	v_cvt_pk_f32_fp8_e32 v[236:237], v205
	v_cvt_pk_f32_fp8_sdwa v[238:239], v205 src0_sel:WORD_1
	v_pk_fma_f32 v[228:229], v[80:81], v[236:237], v[228:229] op_sel:[1,0,0]
	v_pk_fma_f32 v[230:231], v[80:81], v[238:239], v[230:231] op_sel:[1,0,0]
	s_waitcnt vmcnt(1)
	v_cvt_pk_f32_fp8_e32 v[232:233], v206
	v_cvt_pk_f32_fp8_sdwa v[234:235], v206 src0_sel:WORD_1
	v_pk_fma_f32 v[216:217], v[82:83], v[232:233], v[216:217] op_sel_hi:[0,1,1]
	v_pk_fma_f32 v[218:219], v[82:83], v[234:235], v[218:219] op_sel_hi:[0,1,1]
	v_cvt_pk_f32_fp8_e32 v[236:237], v207
	v_cvt_pk_f32_fp8_sdwa v[238:239], v207 src0_sel:WORD_1
	v_pk_fma_f32 v[220:221], v[82:83], v[236:237], v[220:221] op_sel_hi:[0,1,1]
	v_pk_fma_f32 v[222:223], v[82:83], v[238:239], v[222:223] op_sel_hi:[0,1,1]
	v_cvt_pk_f32_fp8_e32 v[232:233], v208
	v_cvt_pk_f32_fp8_sdwa v[234:235], v208 src0_sel:WORD_1
	v_pk_fma_f32 v[224:225], v[82:83], v[232:233], v[224:225] op_sel_hi:[0,1,1]
	v_pk_fma_f32 v[226:227], v[82:83], v[234:235], v[226:227] op_sel_hi:[0,1,1]
	v_cvt_pk_f32_fp8_e32 v[236:237], v209
	v_cvt_pk_f32_fp8_sdwa v[238:239], v209 src0_sel:WORD_1
	v_pk_fma_f32 v[228:229], v[82:83], v[236:237], v[228:229] op_sel_hi:[0,1,1]
	v_pk_fma_f32 v[230:231], v[82:83], v[238:239], v[230:231] op_sel_hi:[0,1,1]
	s_waitcnt vmcnt(0)
	v_cvt_pk_f32_fp8_e32 v[232:233], v210
	v_cvt_pk_f32_fp8_sdwa v[234:235], v210 src0_sel:WORD_1
	v_pk_fma_f32 v[216:217], v[82:83], v[232:233], v[216:217] op_sel:[1,0,0]
	v_pk_fma_f32 v[218:219], v[82:83], v[234:235], v[218:219] op_sel:[1,0,0]
	v_cvt_pk_f32_fp8_e32 v[236:237], v211
	v_cvt_pk_f32_fp8_sdwa v[238:239], v211 src0_sel:WORD_1
	v_pk_fma_f32 v[220:221], v[82:83], v[236:237], v[220:221] op_sel:[1,0,0]
	v_pk_fma_f32 v[222:223], v[82:83], v[238:239], v[222:223] op_sel:[1,0,0]
	v_cvt_pk_f32_fp8_e32 v[232:233], v212
	v_cvt_pk_f32_fp8_sdwa v[234:235], v212 src0_sel:WORD_1
	v_pk_fma_f32 v[224:225], v[82:83], v[232:233], v[224:225] op_sel:[1,0,0]
	v_pk_fma_f32 v[226:227], v[82:83], v[234:235], v[226:227] op_sel:[1,0,0]
	v_cvt_pk_f32_fp8_e32 v[236:237], v213
	v_cvt_pk_f32_fp8_sdwa v[238:239], v213 src0_sel:WORD_1
	v_pk_fma_f32 v[228:229], v[82:83], v[236:237], v[228:229] op_sel:[1,0,0]
	v_pk_fma_f32 v[230:231], v[82:83], v[238:239], v[230:231] op_sel:[1,0,0]
	ds_read_b128 v[52:55], v6 offset:528
	ds_read_b128 v[56:59], v6 offset:544
	ds_read_b128 v[60:63], v6 offset:560
	ds_read_b128 v[64:67], v6 offset:576
	ds_read_b128 v[68:71], v6 offset:592
	ds_read_b128 v[72:75], v6 offset:608
	ds_read_b128 v[76:79], v6 offset:624
	ds_read_b128 v[80:83], v6 offset:640
	v_add_u32_e32 v214, s46, v4
	s_nop 0
	v_permlane32_swap_b32_e32 v216, v224
	v_permlane32_swap_b32_e32 v217, v225
	v_permlane32_swap_b32_e32 v218, v226
	v_permlane32_swap_b32_e32 v219, v227
	v_permlane32_swap_b32_e32 v220, v228
	v_permlane32_swap_b32_e32 v221, v229
	v_permlane32_swap_b32_e32 v222, v230
	v_permlane32_swap_b32_e32 v223, v231
	v_add_f32_e32 v216, v216, v224
	v_add_f32_e32 v217, v217, v225
	v_add_f32_e32 v218, v218, v226
	v_add_f32_e32 v219, v219, v227
	v_add_f32_e32 v220, v220, v228
	v_add_f32_e32 v221, v221, v229
	v_add_f32_e32 v222, v222, v230
	v_add_f32_e32 v223, v223, v231
	s_nop 1
	v_permlane16_swap_b32_e32 v216, v220
	v_permlane16_swap_b32_e32 v217, v221
	v_permlane16_swap_b32_e32 v218, v222
	v_permlane16_swap_b32_e32 v219, v223
	v_add_f32_e32 v216, v216, v220
	v_add_f32_e32 v217, v217, v221
	v_add_f32_e32 v218, v218, v222
	v_add_f32_e32 v219, v219, v223
	v_cvt_pk_bf16_f32 v232, v216, v217
	v_cvt_pk_bf16_f32 v233, v218, v219
	global_store_dwordx2 v214, v[232:233], s[14:15]
	s_add_i32 s48, s48, 1
	s_add_i32 s34, s34, 4
	s_cmp_lt_u32 s48, s49
	s_cbranch_scc0 .Lp11_chunk_done
	s_cmp_lt_u32 s34, 8192
	s_cbranch_scc1 .Lp11_body
	s_branch .Lp11_slice_next
